# rec scan: MFMA order within each fragment group changed so adjacent MFMAs share an operand (aa0 aa1 ai1 ai0 au0 au1)
# speedup vs baseline: 1.0011x; 1.0011x over previous
.Lrec2_loopA_d0:
	ds_read_b128 v[198:201], v130 offset:0
	ds_read_b128 v[214:217], v130 offset:576
	ds_read_b128 v[202:205], v131 offset:0
	ds_read_b128 v[218:221], v131 offset:576
	ds_read_b128 v[206:209], v130 offset:144
	ds_read_b128 v[222:225], v130 offset:720
	ds_read_b128 v[210:213], v131 offset:144
	s_waitcnt lgkmcnt(14)
	ds_read_b128 v[226:229], v131 offset:720
	s_waitcnt lgkmcnt(6)
	v_mfma_f32_16x16x32_bf16 v[100:103], v[198:201], v[20:23], v[12:15]
	v_mfma_f32_16x16x32_bf16 v[112:115], v[214:217], v[20:23], v[12:15]
	v_mfma_f32_16x16x32_bf16 v[138:141], v[214:217], v[52:55], v[16:19]
	v_mfma_f32_16x16x32_bf16 v[104:107], v[198:201], v[52:55], v[16:19]
	v_mfma_f32_16x16x32_bf16 v[108:111], v[198:201], v[84:87], v[242:245]
	v_mfma_f32_16x16x32_bf16 v[142:145], v[214:217], v[84:87], v[242:245]
	s_waitcnt lgkmcnt(4)
	v_mfma_f32_16x16x32_bf16 v[100:103], v[202:205], v[24:27], v[100:103]
	v_mfma_f32_16x16x32_bf16 v[112:115], v[218:221], v[24:27], v[112:115]
	v_mfma_f32_16x16x32_bf16 v[138:141], v[218:221], v[56:59], v[138:141]
	v_mfma_f32_16x16x32_bf16 v[104:107], v[202:205], v[56:59], v[104:107]
	ds_read_b128 v[198:201], v130 offset:288
	ds_read_b128 v[214:217], v130 offset:864
	ds_read_b128 v[202:205], v131 offset:288
	ds_read_b128 v[218:221], v131 offset:864
	s_waitcnt lgkmcnt(6)
	v_mfma_f32_16x16x32_bf16 v[100:103], v[206:209], v[28:31], v[100:103]
	v_mfma_f32_16x16x32_bf16 v[112:115], v[222:225], v[28:31], v[112:115]
	v_mfma_f32_16x16x32_bf16 v[138:141], v[222:225], v[60:63], v[138:141]
	v_mfma_f32_16x16x32_bf16 v[104:107], v[206:209], v[60:63], v[104:107]
	v_mfma_f32_16x16x32_bf16 v[108:111], v[206:209], v[88:91], v[108:111]
	v_mfma_f32_16x16x32_bf16 v[142:145], v[222:225], v[88:91], v[142:145]
	s_waitcnt lgkmcnt(4)
	v_mfma_f32_16x16x32_bf16 v[100:103], v[210:213], v[32:35], v[100:103]
	v_mfma_f32_16x16x32_bf16 v[112:115], v[226:229], v[32:35], v[112:115]
	v_mfma_f32_16x16x32_bf16 v[138:141], v[226:229], v[64:67], v[138:141]
	v_mfma_f32_16x16x32_bf16 v[104:107], v[210:213], v[64:67], v[104:107]
	ds_read_b128 v[206:209], v130 offset:432
	ds_read_b128 v[222:225], v130 offset:1008
	ds_read_b128 v[210:213], v131 offset:432
	ds_read_b128 v[226:229], v131 offset:1008
	s_waitcnt lgkmcnt(6)
	v_mfma_f32_16x16x32_bf16 v[100:103], v[198:201], v[36:39], v[100:103]
	v_mfma_f32_16x16x32_bf16 v[112:115], v[214:217], v[36:39], v[112:115]
	v_mfma_f32_16x16x32_bf16 v[138:141], v[214:217], v[68:71], v[138:141]
	v_mfma_f32_16x16x32_bf16 v[104:107], v[198:201], v[68:71], v[104:107]
	v_mfma_f32_16x16x32_bf16 v[108:111], v[198:201], v[92:95], v[108:111]
	v_mfma_f32_16x16x32_bf16 v[142:145], v[214:217], v[92:95], v[142:145]
	s_waitcnt lgkmcnt(4)
	v_mfma_f32_16x16x32_bf16 v[100:103], v[202:205], v[40:43], v[100:103]
	v_mfma_f32_16x16x32_bf16 v[112:115], v[218:221], v[40:43], v[112:115]
	v_mfma_f32_16x16x32_bf16 v[138:141], v[218:221], v[72:75], v[138:141]
	v_mfma_f32_16x16x32_bf16 v[104:107], v[202:205], v[72:75], v[104:107]
	s_waitcnt lgkmcnt(2)
	v_mfma_f32_16x16x32_bf16 v[100:103], v[206:209], v[44:47], v[100:103]
	v_mfma_f32_16x16x32_bf16 v[112:115], v[222:225], v[44:47], v[112:115]
	v_mfma_f32_16x16x32_bf16 v[138:141], v[222:225], v[76:79], v[138:141]
	v_mfma_f32_16x16x32_bf16 v[104:107], v[206:209], v[76:79], v[104:107]
	v_mfma_f32_16x16x32_bf16 v[108:111], v[206:209], v[96:99], v[108:111]
	v_mfma_f32_16x16x32_bf16 v[142:145], v[222:225], v[96:99], v[142:145]
	s_waitcnt lgkmcnt(0)
	v_mfma_f32_16x16x32_bf16 v[100:103], v[210:213], v[48:51], v[100:103]
	v_mfma_f32_16x16x32_bf16 v[112:115], v[226:229], v[48:51], v[112:115]
	v_mfma_f32_16x16x32_bf16 v[138:141], v[226:229], v[80:83], v[138:141]
	v_mfma_f32_16x16x32_bf16 v[104:107], v[210:213], v[80:83], v[104:107]
	s_waitcnt lgkmcnt(0)
	s_barrier
	s_waitcnt vmcnt(3)
	ds_write_b128 v134, v[146:149]
	ds_write_b128 v134, v[150:153] offset:4608
	ds_write_b128 v135, v[160:163]
	s_add_i32 s52, s4, 3
	s_min_u32 s52, s52, 31
	s_lshl_b32 s52, s52, 13
	s_add_u32 s26, s50, s52
	s_addc_u32 s27, s51, 0
	global_load_dwordx4 v[146:149], v154, s[26:27]
	global_load_dwordx4 v[150:153], v155, s[26:27]
	global_load_dwordx4 v[160:163], v159, s[26:27]
	v_exp_f32_e32 v198, v100
	v_exp_f32_e32 v199, v101
	v_exp_f32_e32 v200, v102
	v_exp_f32_e32 v201, v103
	v_exp_f32_e32 v202, v112
	v_exp_f32_e32 v203, v113
	v_exp_f32_e32 v204, v114
	v_exp_f32_e32 v205, v115
	v_exp_f32_e32 v214, v104
	v_add_f32_e32 v198, 1.0, v198
	v_exp_f32_e32 v215, v105
	v_add_f32_e32 v199, 1.0, v199
	v_exp_f32_e32 v216, v106
	v_add_f32_e32 v200, 1.0, v200
	v_exp_f32_e32 v217, v107
	v_add_f32_e32 v201, 1.0, v201
	v_exp_f32_e32 v218, v138
	v_add_f32_e32 v202, 1.0, v202
	v_exp_f32_e32 v219, v139
	v_add_f32_e32 v203, 1.0, v203
	v_exp_f32_e32 v220, v140
	v_add_f32_e32 v204, 1.0, v204
	v_exp_f32_e32 v221, v141
	v_add_f32_e32 v205, 1.0, v205
	v_rcp_f32_e32 v198, v198
	v_add_f32_e32 v214, 1.0, v214
	v_rcp_f32_e32 v199, v199
	v_add_f32_e32 v215, 1.0, v215
	v_rcp_f32_e32 v200, v200
	v_add_f32_e32 v216, 1.0, v216
	v_rcp_f32_e32 v201, v201
	v_add_f32_e32 v217, 1.0, v217
	v_rcp_f32_e32 v202, v202
	v_add_f32_e32 v218, 1.0, v218
	v_rcp_f32_e32 v203, v203
	v_add_f32_e32 v219, 1.0, v219
	v_rcp_f32_e32 v204, v204
	v_add_f32_e32 v220, 1.0, v220
	v_rcp_f32_e32 v205, v205
	v_add_f32_e32 v221, 1.0, v221
	v_mul_f32_e32 v198, v179, v198
	v_mul_f32_e32 v199, v179, v199
	v_mul_f32_e32 v200, v179, v200
	v_mul_f32_e32 v201, v179, v201
	v_mul_f32_e32 v202, v179, v202
	v_mul_f32_e32 v203, v179, v203
	v_mul_f32_e32 v204, v179, v204
	v_mul_f32_e32 v205, v179, v205
	v_exp_f32_e32 v120, v198
	v_exp_f32_e32 v121, v199
	v_exp_f32_e32 v122, v200
	v_exp_f32_e32 v123, v201
	v_exp_f32_e32 v124, v202
	v_exp_f32_e32 v125, v203
	v_exp_f32_e32 v126, v204
	v_exp_f32_e32 v127, v205
	v_fma_f32 v206, -v120, v120, 1.0
	v_fma_f32 v207, -v121, v121, 1.0
	v_fma_f32 v208, -v122, v122, 1.0
	v_fma_f32 v209, -v123, v123, 1.0
	v_fma_f32 v210, -v124, v124, 1.0
	v_fma_f32 v211, -v125, v125, 1.0
	v_fma_f32 v212, -v126, v126, 1.0
	v_fma_f32 v213, -v127, v127, 1.0
	v_max_f32_e32 v206, 0xda24260, v206
	v_max_f32_e32 v207, 0xda24260, v207
	v_max_f32_e32 v208, 0xda24260, v208
	v_max_f32_e32 v209, 0xda24260, v209
	v_max_f32_e32 v210, 0xda24260, v210
	v_max_f32_e32 v211, 0xda24260, v211
	v_max_f32_e32 v212, 0xda24260, v212
	v_max_f32_e32 v213, 0xda24260, v213
	v_mul_f32_e32 v198, v214, v206
	v_mul_f32_e32 v199, v215, v207
	v_mul_f32_e32 v200, v216, v208
	v_mul_f32_e32 v201, v217, v209
	v_mul_f32_e32 v202, v218, v210
	v_mul_f32_e32 v203, v219, v211
	v_mul_f32_e32 v204, v220, v212
	v_mul_f32_e32 v205, v221, v213
	v_mul_f32_e32 v214, v214, v198
	v_mul_f32_e32 v215, v215, v199
	v_mul_f32_e32 v216, v216, v200
	v_mul_f32_e32 v217, v217, v201
	v_mul_f32_e32 v218, v218, v202
	v_mul_f32_e32 v219, v219, v203
	v_mul_f32_e32 v220, v220, v204
	v_mul_f32_e32 v221, v221, v205
	v_rsq_f32_e32 v214, v214
	v_mul_f32_e32 v222, v108, v206
	v_rsq_f32_e32 v215, v215
	v_mul_f32_e32 v223, v109, v207
	v_rsq_f32_e32 v216, v216
	v_mul_f32_e32 v224, v110, v208
	v_rsq_f32_e32 v217, v217
	v_mul_f32_e32 v225, v111, v209
	v_rsq_f32_e32 v218, v218
	v_mul_f32_e32 v226, v142, v210
	v_rsq_f32_e32 v219, v219
	v_mul_f32_e32 v227, v143, v211
	v_rsq_f32_e32 v220, v220
	v_mul_f32_e32 v228, v144, v212
	v_rsq_f32_e32 v221, v221
	v_mul_f32_e32 v229, v145, v213
	v_mul_f32_e32 v170, v222, v214
	v_mul_f32_e32 v171, v223, v215
	v_mul_f32_e32 v172, v224, v216
	v_mul_f32_e32 v173, v225, v217
	v_mul_f32_e32 v174, v226, v218
	v_mul_f32_e32 v175, v227, v219
	v_mul_f32_e32 v176, v228, v220
	v_mul_f32_e32 v177, v229, v221
	v_mov_b32_e32 v198, v170
	v_mov_b32_e32 v199, v120
	v_fma_f32 v198, v121, v198, v171
	v_mul_f32_e32 v199, v199, v121
	v_fma_f32 v198, v122, v198, v172
	v_mul_f32_e32 v199, v199, v122
	v_fma_f32 v198, v123, v198, v173
	v_mul_f32_e32 v199, v199, v123
	v_fma_f32 v198, v124, v198, v174
	v_mul_f32_e32 v199, v199, v124
	v_fma_f32 v198, v125, v198, v175
	v_mul_f32_e32 v199, v199, v125
	v_fma_f32 v198, v126, v198, v176
	v_mul_f32_e32 v199, v199, v126
	v_fma_f32 v198, v127, v198, v177
	v_mul_f32_e32 v199, v199, v127
	ds_bpermute_b32 v164, v185, v199 offset:0
	ds_bpermute_b32 v246, v185, v198 offset:0
	ds_bpermute_b32 v165, v185, v199 offset:64
	ds_bpermute_b32 v247, v185, v198 offset:64
	ds_bpermute_b32 v166, v185, v199 offset:128
	ds_bpermute_b32 v248, v185, v198 offset:128
	ds_bpermute_b32 v167, v185, v199 offset:192
	ds_bpermute_b32 v249, v185, v198 offset:192
	s_waitcnt lgkmcnt(0)
	v_mov_b32_e32 v251, v246
	v_mov_b32_e32 v250, v164
	v_fma_f32 v251, v251, v165, v247
	v_mul_f32_e32 v250, v250, v165
	v_fma_f32 v251, v251, v166, v248
	v_mul_f32_e32 v250, v250, v166
	v_fma_f32 v251, v251, v167, v249
	v_mul_f32_e32 v250, v250, v167
	s_mov_b64 exec, s[10:11]
	ds_write_b64 v182, v[250:251] offset:0
	s_mov_b64 exec, -1
	s_waitcnt lgkmcnt(0)
	s_barrier
	ds_read2_b64 v[4:7], v183 offset0:0 offset1:16
	s_add_i32 s52, s4, 0
	s_lshl_b32 s52, s52, 12
	v_add_u32_e32 v197, s52, v184
	s_waitcnt lgkmcnt(0)
	v_fma_f32 v198, v180, v4, v5
	v_cndmask_b32_e64 v199, v180, v198, s[24:25]
	v_fma_f32 v180, v198, v6, v7
	v_fma_f32 v200, v199, v164, v246
	v_cndmask_b32_e64 v199, v199, v200, s[16:17]
	v_fma_f32 v200, v199, v165, v247
	v_cndmask_b32_e64 v199, v199, v200, s[20:21]
	v_fma_f32 v200, v199, v166, v248
	v_cndmask_b32_e64 v199, v199, v200, s[22:23]
	v_fma_f32 v214, v120, v199, v170
	v_fma_f32 v215, v121, v214, v171
	v_fma_f32 v216, v122, v215, v172
	v_fma_f32 v217, v123, v216, v173
	v_fma_f32 v218, v124, v217, v174
	v_fma_f32 v219, v125, v218, v175
	v_fma_f32 v220, v126, v219, v176
	v_fma_f32 v221, v127, v220, v177
	v_cvt_pk_bf16_f32 v206, v214, v215
	v_cvt_pk_bf16_f32 v208, v216, v217
	v_cvt_pk_bf16_f32 v210, v218, v219
	v_cvt_pk_bf16_f32 v212, v220, v221
	ds_write_b16 v197, v206 offset:0
	ds_write_b16_d16_hi v197, v206 offset:64
	ds_write_b16 v197, v208 offset:128
	ds_write_b16_d16_hi v197, v208 offset:192
	ds_write_b16 v197, v210 offset:256
	ds_write_b16_d16_hi v197, v210 offset:320
	ds_write_b16 v197, v212 offset:384
	ds_write_b16_d16_hi v197, v212 offset:448
	ds_read_b128 v[198:201], v130 offset:0
	ds_read_b128 v[214:217], v130 offset:576
	ds_read_b128 v[202:205], v131 offset:0
	ds_read_b128 v[218:221], v131 offset:576
	ds_read_b128 v[206:209], v130 offset:144
	ds_read_b128 v[222:225], v130 offset:720
	ds_read_b128 v[210:213], v131 offset:144
	s_waitcnt lgkmcnt(14)
	ds_read_b128 v[226:229], v131 offset:720
	s_waitcnt lgkmcnt(6)
	v_mfma_f32_16x16x32_bf16 v[100:103], v[198:201], v[20:23], v[12:15]
	v_mfma_f32_16x16x32_bf16 v[112:115], v[214:217], v[20:23], v[12:15]
	v_mfma_f32_16x16x32_bf16 v[138:141], v[214:217], v[52:55], v[16:19]
	v_mfma_f32_16x16x32_bf16 v[104:107], v[198:201], v[52:55], v[16:19]
	v_mfma_f32_16x16x32_bf16 v[108:111], v[198:201], v[84:87], v[242:245]
	v_mfma_f32_16x16x32_bf16 v[142:145], v[214:217], v[84:87], v[242:245]
	s_waitcnt lgkmcnt(4)
	v_mfma_f32_16x16x32_bf16 v[100:103], v[202:205], v[24:27], v[100:103]
	v_mfma_f32_16x16x32_bf16 v[112:115], v[218:221], v[24:27], v[112:115]
	v_mfma_f32_16x16x32_bf16 v[138:141], v[218:221], v[56:59], v[138:141]
	v_mfma_f32_16x16x32_bf16 v[104:107], v[202:205], v[56:59], v[104:107]
	ds_read_b128 v[198:201], v130 offset:288
	ds_read_b128 v[214:217], v130 offset:864
	ds_read_b128 v[202:205], v131 offset:288
	ds_read_b128 v[218:221], v131 offset:864
	s_waitcnt lgkmcnt(6)
	v_mfma_f32_16x16x32_bf16 v[100:103], v[206:209], v[28:31], v[100:103]
	v_mfma_f32_16x16x32_bf16 v[112:115], v[222:225], v[28:31], v[112:115]
	v_mfma_f32_16x16x32_bf16 v[138:141], v[222:225], v[60:63], v[138:141]
	v_mfma_f32_16x16x32_bf16 v[104:107], v[206:209], v[60:63], v[104:107]
	v_mfma_f32_16x16x32_bf16 v[108:111], v[206:209], v[88:91], v[108:111]
	v_mfma_f32_16x16x32_bf16 v[142:145], v[222:225], v[88:91], v[142:145]
	s_waitcnt lgkmcnt(4)
	v_mfma_f32_16x16x32_bf16 v[100:103], v[210:213], v[32:35], v[100:103]
	v_mfma_f32_16x16x32_bf16 v[112:115], v[226:229], v[32:35], v[112:115]
	v_mfma_f32_16x16x32_bf16 v[138:141], v[226:229], v[64:67], v[138:141]
	v_mfma_f32_16x16x32_bf16 v[104:107], v[210:213], v[64:67], v[104:107]
	ds_read_b128 v[206:209], v130 offset:432
	ds_read_b128 v[222:225], v130 offset:1008
	ds_read_b128 v[210:213], v131 offset:432
	ds_read_b128 v[226:229], v131 offset:1008
	s_waitcnt lgkmcnt(6)
	v_mfma_f32_16x16x32_bf16 v[100:103], v[198:201], v[36:39], v[100:103]
	v_mfma_f32_16x16x32_bf16 v[112:115], v[214:217], v[36:39], v[112:115]
	v_mfma_f32_16x16x32_bf16 v[138:141], v[214:217], v[68:71], v[138:141]
	v_mfma_f32_16x16x32_bf16 v[104:107], v[198:201], v[68:71], v[104:107]
	v_mfma_f32_16x16x32_bf16 v[108:111], v[198:201], v[92:95], v[108:111]
	v_mfma_f32_16x16x32_bf16 v[142:145], v[214:217], v[92:95], v[142:145]
	s_waitcnt lgkmcnt(4)
	v_mfma_f32_16x16x32_bf16 v[100:103], v[202:205], v[40:43], v[100:103]
	v_mfma_f32_16x16x32_bf16 v[112:115], v[218:221], v[40:43], v[112:115]
	v_mfma_f32_16x16x32_bf16 v[138:141], v[218:221], v[72:75], v[138:141]
	v_mfma_f32_16x16x32_bf16 v[104:107], v[202:205], v[72:75], v[104:107]
	s_waitcnt lgkmcnt(2)
	v_mfma_f32_16x16x32_bf16 v[100:103], v[206:209], v[44:47], v[100:103]
	v_mfma_f32_16x16x32_bf16 v[112:115], v[222:225], v[44:47], v[112:115]
	v_mfma_f32_16x16x32_bf16 v[138:141], v[222:225], v[76:79], v[138:141]
	v_mfma_f32_16x16x32_bf16 v[104:107], v[206:209], v[76:79], v[104:107]
	v_mfma_f32_16x16x32_bf16 v[108:111], v[206:209], v[96:99], v[108:111]
	v_mfma_f32_16x16x32_bf16 v[142:145], v[222:225], v[96:99], v[142:145]
	s_waitcnt lgkmcnt(0)
	v_mfma_f32_16x16x32_bf16 v[100:103], v[210:213], v[48:51], v[100:103]
	v_mfma_f32_16x16x32_bf16 v[112:115], v[226:229], v[48:51], v[112:115]
	v_mfma_f32_16x16x32_bf16 v[138:141], v[226:229], v[80:83], v[138:141]
	v_mfma_f32_16x16x32_bf16 v[104:107], v[210:213], v[80:83], v[104:107]
	s_waitcnt lgkmcnt(0)
	s_barrier
	s_waitcnt vmcnt(3)
	ds_write_b128 v134, v[230:233]
	ds_write_b128 v134, v[234:237] offset:4608
	ds_write_b128 v135, v[238:241]
	s_add_i32 s52, s4, 4
	s_min_u32 s52, s52, 31
	s_lshl_b32 s52, s52, 13
	s_add_u32 s26, s50, s52
	s_addc_u32 s27, s51, 0
	global_load_dwordx4 v[230:233], v154, s[26:27]
	global_load_dwordx4 v[234:237], v155, s[26:27]
	global_load_dwordx4 v[238:241], v159, s[26:27]
	v_exp_f32_e32 v198, v100
	v_exp_f32_e32 v199, v101
	v_exp_f32_e32 v200, v102
	v_exp_f32_e32 v201, v103
	v_exp_f32_e32 v202, v112
	v_exp_f32_e32 v203, v113
	v_exp_f32_e32 v204, v114
	v_exp_f32_e32 v205, v115
	v_exp_f32_e32 v214, v104
	v_add_f32_e32 v198, 1.0, v198
	v_exp_f32_e32 v215, v105
	v_add_f32_e32 v199, 1.0, v199
	v_exp_f32_e32 v216, v106
	v_add_f32_e32 v200, 1.0, v200
	v_exp_f32_e32 v217, v107
	v_add_f32_e32 v201, 1.0, v201
	v_exp_f32_e32 v218, v138
	v_add_f32_e32 v202, 1.0, v202
	v_exp_f32_e32 v219, v139
	v_add_f32_e32 v203, 1.0, v203
	v_exp_f32_e32 v220, v140
	v_add_f32_e32 v204, 1.0, v204
	v_exp_f32_e32 v221, v141
	v_add_f32_e32 v205, 1.0, v205
	v_rcp_f32_e32 v198, v198
	v_add_f32_e32 v214, 1.0, v214
	v_rcp_f32_e32 v199, v199
	v_add_f32_e32 v215, 1.0, v215
	v_rcp_f32_e32 v200, v200
	v_add_f32_e32 v216, 1.0, v216
	v_rcp_f32_e32 v201, v201
	v_add_f32_e32 v217, 1.0, v217
	v_rcp_f32_e32 v202, v202
	v_add_f32_e32 v218, 1.0, v218
	v_rcp_f32_e32 v203, v203
	v_add_f32_e32 v219, 1.0, v219
	v_rcp_f32_e32 v204, v204
	v_add_f32_e32 v220, 1.0, v220
	v_rcp_f32_e32 v205, v205
	v_add_f32_e32 v221, 1.0, v221
	v_mul_f32_e32 v198, v179, v198
	v_mul_f32_e32 v199, v179, v199
	v_mul_f32_e32 v200, v179, v200
	v_mul_f32_e32 v201, v179, v201
	v_mul_f32_e32 v202, v179, v202
	v_mul_f32_e32 v203, v179, v203
	v_mul_f32_e32 v204, v179, v204
	v_mul_f32_e32 v205, v179, v205
	v_exp_f32_e32 v120, v198
	v_exp_f32_e32 v121, v199
	v_exp_f32_e32 v122, v200
	v_exp_f32_e32 v123, v201
	v_exp_f32_e32 v124, v202
	v_exp_f32_e32 v125, v203
	v_exp_f32_e32 v126, v204
	v_exp_f32_e32 v127, v205
	v_fma_f32 v206, -v120, v120, 1.0
	v_fma_f32 v207, -v121, v121, 1.0
	v_fma_f32 v208, -v122, v122, 1.0
	v_fma_f32 v209, -v123, v123, 1.0
	v_fma_f32 v210, -v124, v124, 1.0
	v_fma_f32 v211, -v125, v125, 1.0
	v_fma_f32 v212, -v126, v126, 1.0
	v_fma_f32 v213, -v127, v127, 1.0
	v_max_f32_e32 v206, 0xda24260, v206
	v_max_f32_e32 v207, 0xda24260, v207
	v_max_f32_e32 v208, 0xda24260, v208
	v_max_f32_e32 v209, 0xda24260, v209
	v_max_f32_e32 v210, 0xda24260, v210
	v_max_f32_e32 v211, 0xda24260, v211
	v_max_f32_e32 v212, 0xda24260, v212
	v_max_f32_e32 v213, 0xda24260, v213
	v_mul_f32_e32 v198, v214, v206
	v_mul_f32_e32 v199, v215, v207
	v_mul_f32_e32 v200, v216, v208
	v_mul_f32_e32 v201, v217, v209
	v_mul_f32_e32 v202, v218, v210
	v_mul_f32_e32 v203, v219, v211
	v_mul_f32_e32 v204, v220, v212
	v_mul_f32_e32 v205, v221, v213
	v_mul_f32_e32 v214, v214, v198
	v_mul_f32_e32 v215, v215, v199
	v_mul_f32_e32 v216, v216, v200
	v_mul_f32_e32 v217, v217, v201
	v_mul_f32_e32 v218, v218, v202
	v_mul_f32_e32 v219, v219, v203
	v_mul_f32_e32 v220, v220, v204
	v_mul_f32_e32 v221, v221, v205
	v_rsq_f32_e32 v214, v214
	v_mul_f32_e32 v222, v108, v206
	v_rsq_f32_e32 v215, v215
	v_mul_f32_e32 v223, v109, v207
	v_rsq_f32_e32 v216, v216
	v_mul_f32_e32 v224, v110, v208
	v_rsq_f32_e32 v217, v217
	v_mul_f32_e32 v225, v111, v209
	v_rsq_f32_e32 v218, v218
	v_mul_f32_e32 v226, v142, v210
	v_rsq_f32_e32 v219, v219
	v_mul_f32_e32 v227, v143, v211
	v_rsq_f32_e32 v220, v220
	v_mul_f32_e32 v228, v144, v212
	v_rsq_f32_e32 v221, v221
	v_mul_f32_e32 v229, v145, v213
	v_mul_f32_e32 v170, v222, v214
	v_mul_f32_e32 v171, v223, v215
	v_mul_f32_e32 v172, v224, v216
	v_mul_f32_e32 v173, v225, v217
	v_mul_f32_e32 v174, v226, v218
	v_mul_f32_e32 v175, v227, v219
	v_mul_f32_e32 v176, v228, v220
	v_mul_f32_e32 v177, v229, v221
	v_mov_b32_e32 v198, v170
	v_mov_b32_e32 v199, v120
	v_fma_f32 v198, v121, v198, v171
	v_mul_f32_e32 v199, v199, v121
	v_fma_f32 v198, v122, v198, v172
	v_mul_f32_e32 v199, v199, v122
	v_fma_f32 v198, v123, v198, v173
	v_mul_f32_e32 v199, v199, v123
	v_fma_f32 v198, v124, v198, v174
	v_mul_f32_e32 v199, v199, v124
	v_fma_f32 v198, v125, v198, v175
	v_mul_f32_e32 v199, v199, v125
	v_fma_f32 v198, v126, v198, v176
	v_mul_f32_e32 v199, v199, v126
	v_fma_f32 v198, v127, v198, v177
	v_mul_f32_e32 v199, v199, v127
	ds_bpermute_b32 v164, v185, v199 offset:0
	ds_bpermute_b32 v246, v185, v198 offset:0
	ds_bpermute_b32 v165, v185, v199 offset:64
	ds_bpermute_b32 v247, v185, v198 offset:64
	ds_bpermute_b32 v166, v185, v199 offset:128
	ds_bpermute_b32 v248, v185, v198 offset:128
	ds_bpermute_b32 v167, v185, v199 offset:192
	ds_bpermute_b32 v249, v185, v198 offset:192
	s_waitcnt lgkmcnt(0)
	v_mov_b32_e32 v251, v246
	v_mov_b32_e32 v250, v164
	v_fma_f32 v251, v251, v165, v247
	v_mul_f32_e32 v250, v250, v165
	v_fma_f32 v251, v251, v166, v248
	v_mul_f32_e32 v250, v250, v166
	v_fma_f32 v251, v251, v167, v249
	v_mul_f32_e32 v250, v250, v167
	s_mov_b64 exec, s[10:11]
	ds_write_b64 v182, v[250:251] offset:1024
	s_mov_b64 exec, -1
	s_waitcnt lgkmcnt(0)
	s_barrier
	ds_read2_b64 v[4:7], v183 offset0:128 offset1:144
	s_add_i32 s52, s4, 1
	s_lshl_b32 s52, s52, 12
	v_add_u32_e32 v197, s52, v184
	s_waitcnt lgkmcnt(0)
	v_fma_f32 v198, v180, v4, v5
	v_cndmask_b32_e64 v199, v180, v198, s[24:25]
	v_fma_f32 v180, v198, v6, v7
	v_fma_f32 v200, v199, v164, v246
	v_cndmask_b32_e64 v199, v199, v200, s[16:17]
	v_fma_f32 v200, v199, v165, v247
	v_cndmask_b32_e64 v199, v199, v200, s[20:21]
	v_fma_f32 v200, v199, v166, v248
	v_cndmask_b32_e64 v199, v199, v200, s[22:23]
	v_fma_f32 v214, v120, v199, v170
	v_fma_f32 v215, v121, v214, v171
	v_fma_f32 v216, v122, v215, v172
	v_fma_f32 v217, v123, v216, v173
	v_fma_f32 v218, v124, v217, v174
	v_fma_f32 v219, v125, v218, v175
	v_fma_f32 v220, v126, v219, v176
	v_fma_f32 v221, v127, v220, v177
	v_cvt_pk_bf16_f32 v206, v214, v215
	v_cvt_pk_bf16_f32 v208, v216, v217
	v_cvt_pk_bf16_f32 v210, v218, v219
	v_cvt_pk_bf16_f32 v212, v220, v221
	ds_write_b16 v197, v206 offset:0
	ds_write_b16_d16_hi v197, v206 offset:64
	ds_write_b16 v197, v208 offset:128
	ds_write_b16_d16_hi v197, v208 offset:192
	ds_write_b16 v197, v210 offset:256
	ds_write_b16_d16_hi v197, v210 offset:320
	ds_write_b16 v197, v212 offset:384
	ds_write_b16_d16_hi v197, v212 offset:448
	s_add_i32 s4, s4, 2
	s_cmp_lt_u32 s4, 16
	s_cbranch_scc1 .Lrec2_loopA_d0
	ds_read_b128 v[198:201], v130 offset:0
	ds_read_b128 v[214:217], v130 offset:576
	ds_read_b128 v[202:205], v131 offset:0
	ds_read_b128 v[218:221], v131 offset:576
	ds_read_b128 v[206:209], v130 offset:144
	ds_read_b128 v[222:225], v130 offset:720
	ds_read_b128 v[210:213], v131 offset:144
	s_waitcnt lgkmcnt(14)
	ds_read_b128 v[226:229], v131 offset:720
	s_waitcnt lgkmcnt(6)
	v_mfma_f32_16x16x32_bf16 v[100:103], v[198:201], v[20:23], v[12:15]
	v_mfma_f32_16x16x32_bf16 v[112:115], v[214:217], v[20:23], v[12:15]
	v_mfma_f32_16x16x32_bf16 v[138:141], v[214:217], v[52:55], v[16:19]
	v_mfma_f32_16x16x32_bf16 v[104:107], v[198:201], v[52:55], v[16:19]
	v_mfma_f32_16x16x32_bf16 v[108:111], v[198:201], v[84:87], v[242:245]
	v_mfma_f32_16x16x32_bf16 v[142:145], v[214:217], v[84:87], v[242:245]
	s_waitcnt lgkmcnt(4)
	v_mfma_f32_16x16x32_bf16 v[100:103], v[202:205], v[24:27], v[100:103]
	v_mfma_f32_16x16x32_bf16 v[112:115], v[218:221], v[24:27], v[112:115]
	v_mfma_f32_16x16x32_bf16 v[138:141], v[218:221], v[56:59], v[138:141]
	v_mfma_f32_16x16x32_bf16 v[104:107], v[202:205], v[56:59], v[104:107]
	ds_read_b128 v[198:201], v130 offset:288
	ds_read_b128 v[214:217], v130 offset:864
	ds_read_b128 v[202:205], v131 offset:288
	ds_read_b128 v[218:221], v131 offset:864
	s_waitcnt lgkmcnt(6)
	v_mfma_f32_16x16x32_bf16 v[100:103], v[206:209], v[28:31], v[100:103]
	v_mfma_f32_16x16x32_bf16 v[112:115], v[222:225], v[28:31], v[112:115]
	v_mfma_f32_16x16x32_bf16 v[138:141], v[222:225], v[60:63], v[138:141]
	v_mfma_f32_16x16x32_bf16 v[104:107], v[206:209], v[60:63], v[104:107]
	v_mfma_f32_16x16x32_bf16 v[108:111], v[206:209], v[88:91], v[108:111]
	v_mfma_f32_16x16x32_bf16 v[142:145], v[222:225], v[88:91], v[142:145]
	s_waitcnt lgkmcnt(4)
	v_mfma_f32_16x16x32_bf16 v[100:103], v[210:213], v[32:35], v[100:103]
	v_mfma_f32_16x16x32_bf16 v[112:115], v[226:229], v[32:35], v[112:115]
	v_mfma_f32_16x16x32_bf16 v[138:141], v[226:229], v[64:67], v[138:141]
	v_mfma_f32_16x16x32_bf16 v[104:107], v[210:213], v[64:67], v[104:107]
	ds_read_b128 v[206:209], v130 offset:432
	ds_read_b128 v[222:225], v130 offset:1008
	ds_read_b128 v[210:213], v131 offset:432
	ds_read_b128 v[226:229], v131 offset:1008
	s_waitcnt lgkmcnt(6)
	v_mfma_f32_16x16x32_bf16 v[100:103], v[198:201], v[36:39], v[100:103]
	v_mfma_f32_16x16x32_bf16 v[112:115], v[214:217], v[36:39], v[112:115]
	v_mfma_f32_16x16x32_bf16 v[138:141], v[214:217], v[68:71], v[138:141]
	v_mfma_f32_16x16x32_bf16 v[104:107], v[198:201], v[68:71], v[104:107]
	v_mfma_f32_16x16x32_bf16 v[108:111], v[198:201], v[92:95], v[108:111]
	v_mfma_f32_16x16x32_bf16 v[142:145], v[214:217], v[92:95], v[142:145]
	s_waitcnt lgkmcnt(4)
	v_mfma_f32_16x16x32_bf16 v[100:103], v[202:205], v[40:43], v[100:103]
	v_mfma_f32_16x16x32_bf16 v[112:115], v[218:221], v[40:43], v[112:115]
	v_mfma_f32_16x16x32_bf16 v[138:141], v[218:221], v[72:75], v[138:141]
	v_mfma_f32_16x16x32_bf16 v[104:107], v[202:205], v[72:75], v[104:107]
	s_waitcnt lgkmcnt(2)
	v_mfma_f32_16x16x32_bf16 v[100:103], v[206:209], v[44:47], v[100:103]
	v_mfma_f32_16x16x32_bf16 v[112:115], v[222:225], v[44:47], v[112:115]
	v_mfma_f32_16x16x32_bf16 v[138:141], v[222:225], v[76:79], v[138:141]
	v_mfma_f32_16x16x32_bf16 v[104:107], v[206:209], v[76:79], v[104:107]
	v_mfma_f32_16x16x32_bf16 v[108:111], v[206:209], v[96:99], v[108:111]
	v_mfma_f32_16x16x32_bf16 v[142:145], v[222:225], v[96:99], v[142:145]
	s_waitcnt lgkmcnt(0)
	v_mfma_f32_16x16x32_bf16 v[100:103], v[210:213], v[48:51], v[100:103]
	v_mfma_f32_16x16x32_bf16 v[112:115], v[226:229], v[48:51], v[112:115]
	v_mfma_f32_16x16x32_bf16 v[138:141], v[226:229], v[80:83], v[138:141]
	v_mfma_f32_16x16x32_bf16 v[104:107], v[210:213], v[80:83], v[104:107]
	s_waitcnt lgkmcnt(0)
	s_barrier
	s_waitcnt vmcnt(3)
	ds_write_b128 v134, v[146:149]
	ds_write_b128 v134, v[150:153] offset:4608
	ds_write_b128 v135, v[160:163]
	s_add_i32 s64, s4, 0
	s_mul_i32 s71, s64, 0x30000
	s_add_u32 s38, s60, s71
	s_addc_u32 s39, s61, 0
	s_lshl_b32 s64, s64, 12
	global_load_dwordx4 v[8:11], v255, s[38:39]
	s_add_i32 s52, s4, 3
	s_min_u32 s52, s52, 31
	s_lshl_b32 s52, s52, 13
	s_add_u32 s26, s50, s52
	s_addc_u32 s27, s51, 0
	global_load_dwordx4 v[146:149], v154, s[26:27]
	global_load_dwordx4 v[150:153], v155, s[26:27]
	global_load_dwordx4 v[160:163], v159, s[26:27]
	v_exp_f32_e32 v198, v100
	v_exp_f32_e32 v199, v101
	v_exp_f32_e32 v200, v102
	v_exp_f32_e32 v201, v103
	v_exp_f32_e32 v202, v112
	v_exp_f32_e32 v203, v113
	v_exp_f32_e32 v204, v114
	v_exp_f32_e32 v205, v115
	v_exp_f32_e32 v214, v104
	v_add_f32_e32 v198, 1.0, v198
	v_exp_f32_e32 v215, v105
	v_add_f32_e32 v199, 1.0, v199
	v_exp_f32_e32 v216, v106
	v_add_f32_e32 v200, 1.0, v200
	v_exp_f32_e32 v217, v107
	v_add_f32_e32 v201, 1.0, v201
	v_exp_f32_e32 v218, v138
	v_add_f32_e32 v202, 1.0, v202
	v_exp_f32_e32 v219, v139
	v_add_f32_e32 v203, 1.0, v203
	v_exp_f32_e32 v220, v140
	v_add_f32_e32 v204, 1.0, v204
	v_exp_f32_e32 v221, v141
	v_add_f32_e32 v205, 1.0, v205
	v_rcp_f32_e32 v198, v198
	v_add_f32_e32 v214, 1.0, v214
	v_rcp_f32_e32 v199, v199
	v_add_f32_e32 v215, 1.0, v215
	v_rcp_f32_e32 v200, v200
	v_add_f32_e32 v216, 1.0, v216
	v_rcp_f32_e32 v201, v201
	v_add_f32_e32 v217, 1.0, v217
	v_rcp_f32_e32 v202, v202
	v_add_f32_e32 v218, 1.0, v218
	v_rcp_f32_e32 v203, v203
	v_add_f32_e32 v219, 1.0, v219
	v_rcp_f32_e32 v204, v204
	v_add_f32_e32 v220, 1.0, v220
	v_rcp_f32_e32 v205, v205
	v_add_f32_e32 v221, 1.0, v221
	v_mul_f32_e32 v198, v179, v198
	v_mul_f32_e32 v199, v179, v199
	v_mul_f32_e32 v200, v179, v200
	v_mul_f32_e32 v201, v179, v201
	v_mul_f32_e32 v202, v179, v202
	v_mul_f32_e32 v203, v179, v203
	v_mul_f32_e32 v204, v179, v204
	v_mul_f32_e32 v205, v179, v205
	v_exp_f32_e32 v120, v198
	v_exp_f32_e32 v121, v199
	v_exp_f32_e32 v122, v200
	v_exp_f32_e32 v123, v201
	v_exp_f32_e32 v124, v202
	v_exp_f32_e32 v125, v203
	v_exp_f32_e32 v126, v204
	v_exp_f32_e32 v127, v205
	v_fma_f32 v206, -v120, v120, 1.0
	v_fma_f32 v207, -v121, v121, 1.0
	v_fma_f32 v208, -v122, v122, 1.0
	v_fma_f32 v209, -v123, v123, 1.0
	v_fma_f32 v210, -v124, v124, 1.0
	v_fma_f32 v211, -v125, v125, 1.0
	v_fma_f32 v212, -v126, v126, 1.0
	v_fma_f32 v213, -v127, v127, 1.0
	v_max_f32_e32 v206, 0xda24260, v206
	v_max_f32_e32 v207, 0xda24260, v207
	v_max_f32_e32 v208, 0xda24260, v208
	v_max_f32_e32 v209, 0xda24260, v209
	v_max_f32_e32 v210, 0xda24260, v210
	v_max_f32_e32 v211, 0xda24260, v211
	v_max_f32_e32 v212, 0xda24260, v212
	v_max_f32_e32 v213, 0xda24260, v213
	v_mul_f32_e32 v198, v214, v206
	v_mul_f32_e32 v199, v215, v207
	v_mul_f32_e32 v200, v216, v208
	v_mul_f32_e32 v201, v217, v209
	v_mul_f32_e32 v202, v218, v210
	v_mul_f32_e32 v203, v219, v211
	v_mul_f32_e32 v204, v220, v212
	v_mul_f32_e32 v205, v221, v213
	v_mul_f32_e32 v214, v214, v198
	v_mul_f32_e32 v215, v215, v199
	v_mul_f32_e32 v216, v216, v200
	v_mul_f32_e32 v217, v217, v201
	v_mul_f32_e32 v218, v218, v202
	v_mul_f32_e32 v219, v219, v203
	v_mul_f32_e32 v220, v220, v204
	v_mul_f32_e32 v221, v221, v205
	v_rsq_f32_e32 v214, v214
	v_mul_f32_e32 v222, v108, v206
	v_rsq_f32_e32 v215, v215
	v_mul_f32_e32 v223, v109, v207
	v_rsq_f32_e32 v216, v216
	v_mul_f32_e32 v224, v110, v208
	v_rsq_f32_e32 v217, v217
	v_mul_f32_e32 v225, v111, v209
	v_rsq_f32_e32 v218, v218
	v_mul_f32_e32 v226, v142, v210
	v_rsq_f32_e32 v219, v219
	v_mul_f32_e32 v227, v143, v211
	v_rsq_f32_e32 v220, v220
	v_mul_f32_e32 v228, v144, v212
	v_rsq_f32_e32 v221, v221
	v_mul_f32_e32 v229, v145, v213
	v_mul_f32_e32 v170, v222, v214
	v_mul_f32_e32 v171, v223, v215
	v_mul_f32_e32 v172, v224, v216
	v_mul_f32_e32 v173, v225, v217
	v_mul_f32_e32 v174, v226, v218
	v_mul_f32_e32 v175, v227, v219
	v_mul_f32_e32 v176, v228, v220
	v_mul_f32_e32 v177, v229, v221
	v_mov_b32_e32 v198, v170
	v_mov_b32_e32 v199, v120
	v_fma_f32 v198, v121, v198, v171
	v_mul_f32_e32 v199, v199, v121
	v_fma_f32 v198, v122, v198, v172
	v_mul_f32_e32 v199, v199, v122
	v_fma_f32 v198, v123, v198, v173
	v_mul_f32_e32 v199, v199, v123
	v_fma_f32 v198, v124, v198, v174
	v_mul_f32_e32 v199, v199, v124
	v_fma_f32 v198, v125, v198, v175
	v_mul_f32_e32 v199, v199, v125
	v_fma_f32 v198, v126, v198, v176
	v_mul_f32_e32 v199, v199, v126
	v_fma_f32 v198, v127, v198, v177
	v_mul_f32_e32 v199, v199, v127
	ds_bpermute_b32 v164, v185, v199 offset:0
	ds_bpermute_b32 v246, v185, v198 offset:0
	ds_bpermute_b32 v165, v185, v199 offset:64
	ds_bpermute_b32 v247, v185, v198 offset:64
	ds_bpermute_b32 v166, v185, v199 offset:128
	ds_bpermute_b32 v248, v185, v198 offset:128
	ds_bpermute_b32 v167, v185, v199 offset:192
	ds_bpermute_b32 v249, v185, v198 offset:192
	s_waitcnt lgkmcnt(0)
	v_mov_b32_e32 v251, v246
	v_mov_b32_e32 v250, v164
	v_fma_f32 v251, v251, v165, v247
	v_mul_f32_e32 v250, v250, v165
	v_fma_f32 v251, v251, v166, v248
	v_mul_f32_e32 v250, v250, v166
	v_fma_f32 v251, v251, v167, v249
	v_mul_f32_e32 v250, v250, v167
	s_mov_b64 exec, s[10:11]
	ds_write_b64 v182, v[250:251] offset:0
	s_mov_b64 exec, -1
	s_waitcnt lgkmcnt(0)
	s_barrier
	ds_read2_b64 v[4:7], v183 offset0:0 offset1:16
	s_add_i32 s52, s4, 0
	s_lshl_b32 s52, s52, 12
	v_add_u32_e32 v197, s52, v184
	s_waitcnt lgkmcnt(0)
	v_fma_f32 v198, v180, v4, v5
	v_cndmask_b32_e64 v199, v180, v198, s[24:25]
	v_fma_f32 v180, v198, v6, v7
	v_fma_f32 v200, v199, v164, v246
	v_cndmask_b32_e64 v199, v199, v200, s[16:17]
	v_fma_f32 v200, v199, v165, v247
	v_cndmask_b32_e64 v199, v199, v200, s[20:21]
	v_fma_f32 v200, v199, v166, v248
	v_cndmask_b32_e64 v199, v199, v200, s[22:23]
	v_fma_f32 v214, v120, v199, v170
	v_fma_f32 v215, v121, v214, v171
	v_fma_f32 v216, v122, v215, v172
	v_fma_f32 v217, v123, v216, v173
	v_fma_f32 v218, v124, v217, v174
	v_fma_f32 v219, v125, v218, v175
	v_fma_f32 v220, v126, v219, v176
	v_fma_f32 v221, v127, v220, v177
	ds_read_u16 v206, v197 offset:0
	ds_read_u16 v207, v197 offset:64
	ds_read_u16 v208, v197 offset:128
	ds_read_u16 v209, v197 offset:192
	ds_read_u16 v210, v197 offset:256
	ds_read_u16 v211, v197 offset:320
	ds_read_u16 v212, v197 offset:384
	ds_read_u16 v213, v197 offset:448
	s_waitcnt lgkmcnt(0)
	v_lshlrev_b32_e32 v206, 16, v206
	v_lshlrev_b32_e32 v207, 16, v207
	v_lshlrev_b32_e32 v208, 16, v208
	v_lshlrev_b32_e32 v209, 16, v209
	v_lshlrev_b32_e32 v210, 16, v210
	v_lshlrev_b32_e32 v211, 16, v211
	v_lshlrev_b32_e32 v212, 16, v212
	v_lshlrev_b32_e32 v213, 16, v213
	v_add_f32_e32 v214, v214, v206
	v_add_f32_e32 v215, v215, v207
	v_add_f32_e32 v216, v216, v208
	v_add_f32_e32 v217, v217, v209
	v_add_f32_e32 v218, v218, v210
	v_add_f32_e32 v219, v219, v211
	v_add_f32_e32 v220, v220, v212
	v_add_f32_e32 v221, v221, v213
	v_cvt_pk_bf16_f32 v206, v214, v215
	v_cvt_pk_bf16_f32 v208, v216, v217
	v_cvt_pk_bf16_f32 v210, v218, v219
	v_cvt_pk_bf16_f32 v212, v220, v221
	ds_write_b16 v197, v206 offset:0
	ds_write_b16_d16_hi v197, v206 offset:64
	ds_write_b16 v197, v208 offset:128
	ds_write_b16_d16_hi v197, v208 offset:192
	ds_write_b16 v197, v210 offset:256
	ds_write_b16_d16_hi v197, v210 offset:320
	ds_write_b16 v197, v212 offset:384
	ds_write_b16_d16_hi v197, v212 offset:448
	ds_read_b128 v[198:201], v130 offset:0
	ds_read_b128 v[214:217], v130 offset:576
	ds_read_b128 v[202:205], v131 offset:0
	ds_read_b128 v[218:221], v131 offset:576
	ds_read_b128 v[206:209], v130 offset:144
	ds_read_b128 v[222:225], v130 offset:720
	ds_read_b128 v[210:213], v131 offset:144
	s_waitcnt lgkmcnt(14)
	ds_read_b128 v[226:229], v131 offset:720
	s_waitcnt lgkmcnt(6)
	v_mfma_f32_16x16x32_bf16 v[100:103], v[198:201], v[20:23], v[12:15]
	v_mfma_f32_16x16x32_bf16 v[112:115], v[214:217], v[20:23], v[12:15]
	v_mfma_f32_16x16x32_bf16 v[138:141], v[214:217], v[52:55], v[16:19]
	v_mfma_f32_16x16x32_bf16 v[104:107], v[198:201], v[52:55], v[16:19]
	v_mfma_f32_16x16x32_bf16 v[108:111], v[198:201], v[84:87], v[242:245]
	v_mfma_f32_16x16x32_bf16 v[142:145], v[214:217], v[84:87], v[242:245]
	s_waitcnt lgkmcnt(4)
	v_mfma_f32_16x16x32_bf16 v[100:103], v[202:205], v[24:27], v[100:103]
	v_mfma_f32_16x16x32_bf16 v[112:115], v[218:221], v[24:27], v[112:115]
	v_mfma_f32_16x16x32_bf16 v[138:141], v[218:221], v[56:59], v[138:141]
	v_mfma_f32_16x16x32_bf16 v[104:107], v[202:205], v[56:59], v[104:107]
	ds_read_b128 v[198:201], v130 offset:288
	ds_read_b128 v[214:217], v130 offset:864
	ds_read_b128 v[202:205], v131 offset:288
	ds_read_b128 v[218:221], v131 offset:864
	s_waitcnt lgkmcnt(6)
	v_mfma_f32_16x16x32_bf16 v[100:103], v[206:209], v[28:31], v[100:103]
	v_mfma_f32_16x16x32_bf16 v[112:115], v[222:225], v[28:31], v[112:115]
	v_mfma_f32_16x16x32_bf16 v[138:141], v[222:225], v[60:63], v[138:141]
	v_mfma_f32_16x16x32_bf16 v[104:107], v[206:209], v[60:63], v[104:107]
	v_mfma_f32_16x16x32_bf16 v[108:111], v[206:209], v[88:91], v[108:111]
	v_mfma_f32_16x16x32_bf16 v[142:145], v[222:225], v[88:91], v[142:145]
	s_waitcnt lgkmcnt(4)
	v_mfma_f32_16x16x32_bf16 v[100:103], v[210:213], v[32:35], v[100:103]
	v_mfma_f32_16x16x32_bf16 v[112:115], v[226:229], v[32:35], v[112:115]
	v_mfma_f32_16x16x32_bf16 v[138:141], v[226:229], v[64:67], v[138:141]
	v_mfma_f32_16x16x32_bf16 v[104:107], v[210:213], v[64:67], v[104:107]
	ds_read_b128 v[206:209], v130 offset:432
	ds_read_b128 v[222:225], v130 offset:1008
	ds_read_b128 v[210:213], v131 offset:432
	ds_read_b128 v[226:229], v131 offset:1008
	s_waitcnt lgkmcnt(6)
	v_mfma_f32_16x16x32_bf16 v[100:103], v[198:201], v[36:39], v[100:103]
	v_mfma_f32_16x16x32_bf16 v[112:115], v[214:217], v[36:39], v[112:115]
	v_mfma_f32_16x16x32_bf16 v[138:141], v[214:217], v[68:71], v[138:141]
	v_mfma_f32_16x16x32_bf16 v[104:107], v[198:201], v[68:71], v[104:107]
	v_mfma_f32_16x16x32_bf16 v[108:111], v[198:201], v[92:95], v[108:111]
	v_mfma_f32_16x16x32_bf16 v[142:145], v[214:217], v[92:95], v[142:145]
	s_waitcnt lgkmcnt(4)
	v_mfma_f32_16x16x32_bf16 v[100:103], v[202:205], v[40:43], v[100:103]
	v_mfma_f32_16x16x32_bf16 v[112:115], v[218:221], v[40:43], v[112:115]
	v_mfma_f32_16x16x32_bf16 v[138:141], v[218:221], v[72:75], v[138:141]
	v_mfma_f32_16x16x32_bf16 v[104:107], v[202:205], v[72:75], v[104:107]
	s_waitcnt lgkmcnt(2)
	v_mfma_f32_16x16x32_bf16 v[100:103], v[206:209], v[44:47], v[100:103]
	v_mfma_f32_16x16x32_bf16 v[112:115], v[222:225], v[44:47], v[112:115]
	v_mfma_f32_16x16x32_bf16 v[138:141], v[222:225], v[76:79], v[138:141]
	v_mfma_f32_16x16x32_bf16 v[104:107], v[206:209], v[76:79], v[104:107]
	v_mfma_f32_16x16x32_bf16 v[108:111], v[206:209], v[96:99], v[108:111]
	v_mfma_f32_16x16x32_bf16 v[142:145], v[222:225], v[96:99], v[142:145]
	s_waitcnt lgkmcnt(0)
	v_mfma_f32_16x16x32_bf16 v[100:103], v[210:213], v[48:51], v[100:103]
	v_mfma_f32_16x16x32_bf16 v[112:115], v[226:229], v[48:51], v[112:115]
	v_mfma_f32_16x16x32_bf16 v[138:141], v[226:229], v[80:83], v[138:141]
	v_mfma_f32_16x16x32_bf16 v[104:107], v[210:213], v[80:83], v[104:107]
	s_waitcnt lgkmcnt(0)
	s_barrier
	s_waitcnt vmcnt(4)
	ds_write_b128 v134, v[230:233]
	ds_write_b128 v134, v[234:237] offset:4608
	ds_write_b128 v135, v[238:241]
	s_add_i32 s64, s4, 0
	s_mul_i32 s71, s64, 0x30000
	s_add_u32 s38, s60, s71
	s_addc_u32 s39, s61, 0
	s_lshl_b32 s64, s64, 12
	v_add_u32_e32 v136, s64, v195
	ds_read_b128 v[116:119], v136
	s_waitcnt vmcnt(3)
	s_waitcnt lgkmcnt(0)
	v_lshlrev_b32_e32 v136, 16, v116
	v_lshlrev_b32_e32 v137, 16, v8
	v_and_b32_e32 v168, 0xffff0000, v116
	v_and_b32_e32 v169, 0xffff0000, v8
	v_mul_f32_e32 v136, v136, v137
	v_mul_f32_e32 v168, v168, v169
	v_cvt_pk_bf16_f32 v116, v136, v168
	v_lshlrev_b32_e32 v136, 16, v117
	v_lshlrev_b32_e32 v137, 16, v9
	v_and_b32_e32 v168, 0xffff0000, v117
	v_and_b32_e32 v169, 0xffff0000, v9
	v_mul_f32_e32 v136, v136, v137
	v_mul_f32_e32 v168, v168, v169
	v_cvt_pk_bf16_f32 v117, v136, v168
	v_lshlrev_b32_e32 v136, 16, v118
	v_lshlrev_b32_e32 v137, 16, v10
	v_and_b32_e32 v168, 0xffff0000, v118
	v_and_b32_e32 v169, 0xffff0000, v10
	v_mul_f32_e32 v136, v136, v137
	v_mul_f32_e32 v168, v168, v169
	v_cvt_pk_bf16_f32 v118, v136, v168
	v_lshlrev_b32_e32 v136, 16, v119
	v_lshlrev_b32_e32 v137, 16, v11
	v_and_b32_e32 v168, 0xffff0000, v119
	v_and_b32_e32 v169, 0xffff0000, v11
	v_mul_f32_e32 v136, v136, v137
	v_mul_f32_e32 v168, v168, v169
	v_cvt_pk_bf16_f32 v119, v136, v168
	global_store_dwordx4 v255, v[116:119], s[38:39]
	s_add_i32 s64, s4, 1
	s_mul_i32 s71, s64, 0x30000
	s_add_u32 s38, s60, s71
	s_addc_u32 s39, s61, 0
	s_lshl_b32 s64, s64, 12
	global_load_dwordx4 v[8:11], v255, s[38:39]
	s_add_i32 s52, s4, 4
	s_min_u32 s52, s52, 31
	s_lshl_b32 s52, s52, 13
	s_add_u32 s26, s50, s52
	s_addc_u32 s27, s51, 0
	global_load_dwordx4 v[230:233], v154, s[26:27]
	global_load_dwordx4 v[234:237], v155, s[26:27]
	global_load_dwordx4 v[238:241], v159, s[26:27]
	v_exp_f32_e32 v198, v100
	v_exp_f32_e32 v199, v101
	v_exp_f32_e32 v200, v102
	v_exp_f32_e32 v201, v103
	v_exp_f32_e32 v202, v112
	v_exp_f32_e32 v203, v113
	v_exp_f32_e32 v204, v114
	v_exp_f32_e32 v205, v115
	v_exp_f32_e32 v214, v104
	v_add_f32_e32 v198, 1.0, v198
	v_exp_f32_e32 v215, v105
	v_add_f32_e32 v199, 1.0, v199
	v_exp_f32_e32 v216, v106
	v_add_f32_e32 v200, 1.0, v200
	v_exp_f32_e32 v217, v107
	v_add_f32_e32 v201, 1.0, v201
	v_exp_f32_e32 v218, v138
	v_add_f32_e32 v202, 1.0, v202
	v_exp_f32_e32 v219, v139
	v_add_f32_e32 v203, 1.0, v203
	v_exp_f32_e32 v220, v140
	v_add_f32_e32 v204, 1.0, v204
	v_exp_f32_e32 v221, v141
	v_add_f32_e32 v205, 1.0, v205
	v_rcp_f32_e32 v198, v198
	v_add_f32_e32 v214, 1.0, v214
	v_rcp_f32_e32 v199, v199
	v_add_f32_e32 v215, 1.0, v215
	v_rcp_f32_e32 v200, v200
	v_add_f32_e32 v216, 1.0, v216
	v_rcp_f32_e32 v201, v201
	v_add_f32_e32 v217, 1.0, v217
	v_rcp_f32_e32 v202, v202
	v_add_f32_e32 v218, 1.0, v218
	v_rcp_f32_e32 v203, v203
	v_add_f32_e32 v219, 1.0, v219
	v_rcp_f32_e32 v204, v204
	v_add_f32_e32 v220, 1.0, v220
	v_rcp_f32_e32 v205, v205
	v_add_f32_e32 v221, 1.0, v221
	v_mul_f32_e32 v198, v179, v198
	v_mul_f32_e32 v199, v179, v199
	v_mul_f32_e32 v200, v179, v200
	v_mul_f32_e32 v201, v179, v201
	v_mul_f32_e32 v202, v179, v202
	v_mul_f32_e32 v203, v179, v203
	v_mul_f32_e32 v204, v179, v204
	v_mul_f32_e32 v205, v179, v205
	v_exp_f32_e32 v120, v198
	v_exp_f32_e32 v121, v199
	v_exp_f32_e32 v122, v200
	v_exp_f32_e32 v123, v201
	v_exp_f32_e32 v124, v202
	v_exp_f32_e32 v125, v203
	v_exp_f32_e32 v126, v204
	v_exp_f32_e32 v127, v205
	v_fma_f32 v206, -v120, v120, 1.0
	v_fma_f32 v207, -v121, v121, 1.0
	v_fma_f32 v208, -v122, v122, 1.0
	v_fma_f32 v209, -v123, v123, 1.0
	v_fma_f32 v210, -v124, v124, 1.0
	v_fma_f32 v211, -v125, v125, 1.0
	v_fma_f32 v212, -v126, v126, 1.0
	v_fma_f32 v213, -v127, v127, 1.0
	v_max_f32_e32 v206, 0xda24260, v206
	v_max_f32_e32 v207, 0xda24260, v207
	v_max_f32_e32 v208, 0xda24260, v208
	v_max_f32_e32 v209, 0xda24260, v209
	v_max_f32_e32 v210, 0xda24260, v210
	v_max_f32_e32 v211, 0xda24260, v211
	v_max_f32_e32 v212, 0xda24260, v212
	v_max_f32_e32 v213, 0xda24260, v213
	v_mul_f32_e32 v198, v214, v206
	v_mul_f32_e32 v199, v215, v207
	v_mul_f32_e32 v200, v216, v208
	v_mul_f32_e32 v201, v217, v209
	v_mul_f32_e32 v202, v218, v210
	v_mul_f32_e32 v203, v219, v211
	v_mul_f32_e32 v204, v220, v212
	v_mul_f32_e32 v205, v221, v213
	v_mul_f32_e32 v214, v214, v198
	v_mul_f32_e32 v215, v215, v199
	v_mul_f32_e32 v216, v216, v200
	v_mul_f32_e32 v217, v217, v201
	v_mul_f32_e32 v218, v218, v202
	v_mul_f32_e32 v219, v219, v203
	v_mul_f32_e32 v220, v220, v204
	v_mul_f32_e32 v221, v221, v205
	v_rsq_f32_e32 v214, v214
	v_mul_f32_e32 v222, v108, v206
	v_rsq_f32_e32 v215, v215
	v_mul_f32_e32 v223, v109, v207
	v_rsq_f32_e32 v216, v216
	v_mul_f32_e32 v224, v110, v208
	v_rsq_f32_e32 v217, v217
	v_mul_f32_e32 v225, v111, v209
	v_rsq_f32_e32 v218, v218
	v_mul_f32_e32 v226, v142, v210
	v_rsq_f32_e32 v219, v219
	v_mul_f32_e32 v227, v143, v211
	v_rsq_f32_e32 v220, v220
	v_mul_f32_e32 v228, v144, v212
	v_rsq_f32_e32 v221, v221
	v_mul_f32_e32 v229, v145, v213
	v_mul_f32_e32 v170, v222, v214
	v_mul_f32_e32 v171, v223, v215
	v_mul_f32_e32 v172, v224, v216
	v_mul_f32_e32 v173, v225, v217
	v_mul_f32_e32 v174, v226, v218
	v_mul_f32_e32 v175, v227, v219
	v_mul_f32_e32 v176, v228, v220
	v_mul_f32_e32 v177, v229, v221
	v_mov_b32_e32 v198, v170
	v_mov_b32_e32 v199, v120
	v_fma_f32 v198, v121, v198, v171
	v_mul_f32_e32 v199, v199, v121
	v_fma_f32 v198, v122, v198, v172
	v_mul_f32_e32 v199, v199, v122
	v_fma_f32 v198, v123, v198, v173
	v_mul_f32_e32 v199, v199, v123
	v_fma_f32 v198, v124, v198, v174
	v_mul_f32_e32 v199, v199, v124
	v_fma_f32 v198, v125, v198, v175
	v_mul_f32_e32 v199, v199, v125
	v_fma_f32 v198, v126, v198, v176
	v_mul_f32_e32 v199, v199, v126
	v_fma_f32 v198, v127, v198, v177
	v_mul_f32_e32 v199, v199, v127
	ds_bpermute_b32 v164, v185, v199 offset:0
	ds_bpermute_b32 v246, v185, v198 offset:0
	ds_bpermute_b32 v165, v185, v199 offset:64
	ds_bpermute_b32 v247, v185, v198 offset:64
	ds_bpermute_b32 v166, v185, v199 offset:128
	ds_bpermute_b32 v248, v185, v198 offset:128
	ds_bpermute_b32 v167, v185, v199 offset:192
	ds_bpermute_b32 v249, v185, v198 offset:192
	s_waitcnt lgkmcnt(0)
	v_mov_b32_e32 v251, v246
	v_mov_b32_e32 v250, v164
	v_fma_f32 v251, v251, v165, v247
	v_mul_f32_e32 v250, v250, v165
	v_fma_f32 v251, v251, v166, v248
	v_mul_f32_e32 v250, v250, v166
	v_fma_f32 v251, v251, v167, v249
	v_mul_f32_e32 v250, v250, v167
	s_mov_b64 exec, s[10:11]
	ds_write_b64 v182, v[250:251] offset:1024
	s_mov_b64 exec, -1
	s_waitcnt lgkmcnt(0)
	s_barrier
	ds_read2_b64 v[4:7], v183 offset0:128 offset1:144
	s_add_i32 s52, s4, 1
	s_lshl_b32 s52, s52, 12
	v_add_u32_e32 v197, s52, v184
	s_waitcnt lgkmcnt(0)
	v_fma_f32 v198, v180, v4, v5
	v_cndmask_b32_e64 v199, v180, v198, s[24:25]
	v_fma_f32 v180, v198, v6, v7
	v_fma_f32 v200, v199, v164, v246
	v_cndmask_b32_e64 v199, v199, v200, s[16:17]
	v_fma_f32 v200, v199, v165, v247
	v_cndmask_b32_e64 v199, v199, v200, s[20:21]
	v_fma_f32 v200, v199, v166, v248
	v_cndmask_b32_e64 v199, v199, v200, s[22:23]
	v_fma_f32 v214, v120, v199, v170
	v_fma_f32 v215, v121, v214, v171
	v_fma_f32 v216, v122, v215, v172
	v_fma_f32 v217, v123, v216, v173
	v_fma_f32 v218, v124, v217, v174
	v_fma_f32 v219, v125, v218, v175
	v_fma_f32 v220, v126, v219, v176
	v_fma_f32 v221, v127, v220, v177
	ds_read_u16 v206, v197 offset:0
	ds_read_u16 v207, v197 offset:64
	ds_read_u16 v208, v197 offset:128
	ds_read_u16 v209, v197 offset:192
	ds_read_u16 v210, v197 offset:256
	ds_read_u16 v211, v197 offset:320
	ds_read_u16 v212, v197 offset:384
	ds_read_u16 v213, v197 offset:448
	s_waitcnt lgkmcnt(0)
	v_lshlrev_b32_e32 v206, 16, v206
	v_lshlrev_b32_e32 v207, 16, v207
	v_lshlrev_b32_e32 v208, 16, v208
	v_lshlrev_b32_e32 v209, 16, v209
	v_lshlrev_b32_e32 v210, 16, v210
	v_lshlrev_b32_e32 v211, 16, v211
	v_lshlrev_b32_e32 v212, 16, v212
	v_lshlrev_b32_e32 v213, 16, v213
	v_add_f32_e32 v214, v214, v206
	v_add_f32_e32 v215, v215, v207
	v_add_f32_e32 v216, v216, v208
	v_add_f32_e32 v217, v217, v209
	v_add_f32_e32 v218, v218, v210
	v_add_f32_e32 v219, v219, v211
	v_add_f32_e32 v220, v220, v212
	v_add_f32_e32 v221, v221, v213
	v_cvt_pk_bf16_f32 v206, v214, v215
	v_cvt_pk_bf16_f32 v208, v216, v217
	v_cvt_pk_bf16_f32 v210, v218, v219
	v_cvt_pk_bf16_f32 v212, v220, v221
	ds_write_b16 v197, v206 offset:0
	ds_write_b16_d16_hi v197, v206 offset:64
	ds_write_b16 v197, v208 offset:128
	ds_write_b16_d16_hi v197, v208 offset:192
	ds_write_b16 v197, v210 offset:256
	ds_write_b16_d16_hi v197, v210 offset:320
	ds_write_b16 v197, v212 offset:384
	ds_write_b16_d16_hi v197, v212 offset:448
	s_add_i32 s4, s4, 2
.Lrec2_loopB_d0:
	ds_read_b128 v[198:201], v130 offset:0
	ds_read_b128 v[214:217], v130 offset:576
	ds_read_b128 v[202:205], v131 offset:0
	ds_read_b128 v[218:221], v131 offset:576
	ds_read_b128 v[206:209], v130 offset:144
	ds_read_b128 v[222:225], v130 offset:720
	ds_read_b128 v[210:213], v131 offset:144
	s_waitcnt lgkmcnt(14)
	ds_read_b128 v[226:229], v131 offset:720
	s_waitcnt lgkmcnt(6)
	v_mfma_f32_16x16x32_bf16 v[100:103], v[198:201], v[20:23], v[12:15]
	v_mfma_f32_16x16x32_bf16 v[112:115], v[214:217], v[20:23], v[12:15]
	v_mfma_f32_16x16x32_bf16 v[138:141], v[214:217], v[52:55], v[16:19]
	v_mfma_f32_16x16x32_bf16 v[104:107], v[198:201], v[52:55], v[16:19]
	v_mfma_f32_16x16x32_bf16 v[108:111], v[198:201], v[84:87], v[242:245]
	v_mfma_f32_16x16x32_bf16 v[142:145], v[214:217], v[84:87], v[242:245]
	s_waitcnt lgkmcnt(4)
	v_mfma_f32_16x16x32_bf16 v[100:103], v[202:205], v[24:27], v[100:103]
	v_mfma_f32_16x16x32_bf16 v[112:115], v[218:221], v[24:27], v[112:115]
	v_mfma_f32_16x16x32_bf16 v[138:141], v[218:221], v[56:59], v[138:141]
	v_mfma_f32_16x16x32_bf16 v[104:107], v[202:205], v[56:59], v[104:107]
	ds_read_b128 v[198:201], v130 offset:288
	ds_read_b128 v[214:217], v130 offset:864
	ds_read_b128 v[202:205], v131 offset:288
	ds_read_b128 v[218:221], v131 offset:864
	s_waitcnt lgkmcnt(6)
	v_mfma_f32_16x16x32_bf16 v[100:103], v[206:209], v[28:31], v[100:103]
	v_mfma_f32_16x16x32_bf16 v[112:115], v[222:225], v[28:31], v[112:115]
	v_mfma_f32_16x16x32_bf16 v[138:141], v[222:225], v[60:63], v[138:141]
	v_mfma_f32_16x16x32_bf16 v[104:107], v[206:209], v[60:63], v[104:107]
	v_mfma_f32_16x16x32_bf16 v[108:111], v[206:209], v[88:91], v[108:111]
	v_mfma_f32_16x16x32_bf16 v[142:145], v[222:225], v[88:91], v[142:145]
	s_waitcnt lgkmcnt(4)
	v_mfma_f32_16x16x32_bf16 v[100:103], v[210:213], v[32:35], v[100:103]
	v_mfma_f32_16x16x32_bf16 v[112:115], v[226:229], v[32:35], v[112:115]
	v_mfma_f32_16x16x32_bf16 v[138:141], v[226:229], v[64:67], v[138:141]
	v_mfma_f32_16x16x32_bf16 v[104:107], v[210:213], v[64:67], v[104:107]
	ds_read_b128 v[206:209], v130 offset:432
	ds_read_b128 v[222:225], v130 offset:1008
	ds_read_b128 v[210:213], v131 offset:432
	ds_read_b128 v[226:229], v131 offset:1008
	s_waitcnt lgkmcnt(6)
	v_mfma_f32_16x16x32_bf16 v[100:103], v[198:201], v[36:39], v[100:103]
	v_mfma_f32_16x16x32_bf16 v[112:115], v[214:217], v[36:39], v[112:115]
	v_mfma_f32_16x16x32_bf16 v[138:141], v[214:217], v[68:71], v[138:141]
	v_mfma_f32_16x16x32_bf16 v[104:107], v[198:201], v[68:71], v[104:107]
	v_mfma_f32_16x16x32_bf16 v[108:111], v[198:201], v[92:95], v[108:111]
	v_mfma_f32_16x16x32_bf16 v[142:145], v[214:217], v[92:95], v[142:145]
	s_waitcnt lgkmcnt(4)
	v_mfma_f32_16x16x32_bf16 v[100:103], v[202:205], v[40:43], v[100:103]
	v_mfma_f32_16x16x32_bf16 v[112:115], v[218:221], v[40:43], v[112:115]
	v_mfma_f32_16x16x32_bf16 v[138:141], v[218:221], v[72:75], v[138:141]
	v_mfma_f32_16x16x32_bf16 v[104:107], v[202:205], v[72:75], v[104:107]
	s_waitcnt lgkmcnt(2)
	v_mfma_f32_16x16x32_bf16 v[100:103], v[206:209], v[44:47], v[100:103]
	v_mfma_f32_16x16x32_bf16 v[112:115], v[222:225], v[44:47], v[112:115]
	v_mfma_f32_16x16x32_bf16 v[138:141], v[222:225], v[76:79], v[138:141]
	v_mfma_f32_16x16x32_bf16 v[104:107], v[206:209], v[76:79], v[104:107]
	v_mfma_f32_16x16x32_bf16 v[108:111], v[206:209], v[96:99], v[108:111]
	v_mfma_f32_16x16x32_bf16 v[142:145], v[222:225], v[96:99], v[142:145]
	s_waitcnt lgkmcnt(0)
	v_mfma_f32_16x16x32_bf16 v[100:103], v[210:213], v[48:51], v[100:103]
	v_mfma_f32_16x16x32_bf16 v[112:115], v[226:229], v[48:51], v[112:115]
	v_mfma_f32_16x16x32_bf16 v[138:141], v[226:229], v[80:83], v[138:141]
	v_mfma_f32_16x16x32_bf16 v[104:107], v[210:213], v[80:83], v[104:107]
	s_waitcnt lgkmcnt(0)
	s_barrier
	s_waitcnt vmcnt(5)
	ds_write_b128 v134, v[146:149]
	ds_write_b128 v134, v[150:153] offset:4608
	ds_write_b128 v135, v[160:163]
	s_add_i32 s64, s4, -1
	s_mul_i32 s71, s64, 0x30000
	s_add_u32 s38, s60, s71
	s_addc_u32 s39, s61, 0
	s_lshl_b32 s64, s64, 12
	v_add_u32_e32 v136, s64, v195
	ds_read_b128 v[116:119], v136
	s_waitcnt vmcnt(3)
	s_waitcnt lgkmcnt(0)
	v_lshlrev_b32_e32 v136, 16, v116
	v_lshlrev_b32_e32 v137, 16, v8
	v_and_b32_e32 v168, 0xffff0000, v116
	v_and_b32_e32 v169, 0xffff0000, v8
	v_mul_f32_e32 v136, v136, v137
	v_mul_f32_e32 v168, v168, v169
	v_cvt_pk_bf16_f32 v116, v136, v168
	v_lshlrev_b32_e32 v136, 16, v117
	v_lshlrev_b32_e32 v137, 16, v9
	v_and_b32_e32 v168, 0xffff0000, v117
	v_and_b32_e32 v169, 0xffff0000, v9
	v_mul_f32_e32 v136, v136, v137
	v_mul_f32_e32 v168, v168, v169
	v_cvt_pk_bf16_f32 v117, v136, v168
	v_lshlrev_b32_e32 v136, 16, v118
	v_lshlrev_b32_e32 v137, 16, v10
	v_and_b32_e32 v168, 0xffff0000, v118
	v_and_b32_e32 v169, 0xffff0000, v10
	v_mul_f32_e32 v136, v136, v137
	v_mul_f32_e32 v168, v168, v169
	v_cvt_pk_bf16_f32 v118, v136, v168
	v_lshlrev_b32_e32 v136, 16, v119
	v_lshlrev_b32_e32 v137, 16, v11
	v_and_b32_e32 v168, 0xffff0000, v119
	v_and_b32_e32 v169, 0xffff0000, v11
	v_mul_f32_e32 v136, v136, v137
	v_mul_f32_e32 v168, v168, v169
	v_cvt_pk_bf16_f32 v119, v136, v168
	global_store_dwordx4 v255, v[116:119], s[38:39]
	s_add_i32 s64, s4, 0
	s_mul_i32 s71, s64, 0x30000
	s_add_u32 s38, s60, s71
	s_addc_u32 s39, s61, 0
	s_lshl_b32 s64, s64, 12
	global_load_dwordx4 v[8:11], v255, s[38:39]
	s_add_i32 s52, s4, 3
	s_min_u32 s52, s52, 31
	s_lshl_b32 s52, s52, 13
	s_add_u32 s26, s50, s52
	s_addc_u32 s27, s51, 0
	global_load_dwordx4 v[146:149], v154, s[26:27]
	global_load_dwordx4 v[150:153], v155, s[26:27]
	global_load_dwordx4 v[160:163], v159, s[26:27]
	v_exp_f32_e32 v198, v100
	v_exp_f32_e32 v199, v101
	v_exp_f32_e32 v200, v102
	v_exp_f32_e32 v201, v103
	v_exp_f32_e32 v202, v112
	v_exp_f32_e32 v203, v113
	v_exp_f32_e32 v204, v114
	v_exp_f32_e32 v205, v115
	v_exp_f32_e32 v214, v104
	v_add_f32_e32 v198, 1.0, v198
	v_exp_f32_e32 v215, v105
	v_add_f32_e32 v199, 1.0, v199
	v_exp_f32_e32 v216, v106
	v_add_f32_e32 v200, 1.0, v200
	v_exp_f32_e32 v217, v107
	v_add_f32_e32 v201, 1.0, v201
	v_exp_f32_e32 v218, v138
	v_add_f32_e32 v202, 1.0, v202
	v_exp_f32_e32 v219, v139
	v_add_f32_e32 v203, 1.0, v203
	v_exp_f32_e32 v220, v140
	v_add_f32_e32 v204, 1.0, v204
	v_exp_f32_e32 v221, v141
	v_add_f32_e32 v205, 1.0, v205
	v_rcp_f32_e32 v198, v198
	v_add_f32_e32 v214, 1.0, v214
	v_rcp_f32_e32 v199, v199
	v_add_f32_e32 v215, 1.0, v215
	v_rcp_f32_e32 v200, v200
	v_add_f32_e32 v216, 1.0, v216
	v_rcp_f32_e32 v201, v201
	v_add_f32_e32 v217, 1.0, v217
	v_rcp_f32_e32 v202, v202
	v_add_f32_e32 v218, 1.0, v218
	v_rcp_f32_e32 v203, v203
	v_add_f32_e32 v219, 1.0, v219
	v_rcp_f32_e32 v204, v204
	v_add_f32_e32 v220, 1.0, v220
	v_rcp_f32_e32 v205, v205
	v_add_f32_e32 v221, 1.0, v221
	v_mul_f32_e32 v198, v179, v198
	v_mul_f32_e32 v199, v179, v199
	v_mul_f32_e32 v200, v179, v200
	v_mul_f32_e32 v201, v179, v201
	v_mul_f32_e32 v202, v179, v202
	v_mul_f32_e32 v203, v179, v203
	v_mul_f32_e32 v204, v179, v204
	v_mul_f32_e32 v205, v179, v205
	v_exp_f32_e32 v120, v198
	v_exp_f32_e32 v121, v199
	v_exp_f32_e32 v122, v200
	v_exp_f32_e32 v123, v201
	v_exp_f32_e32 v124, v202
	v_exp_f32_e32 v125, v203
	v_exp_f32_e32 v126, v204
	v_exp_f32_e32 v127, v205
	v_fma_f32 v206, -v120, v120, 1.0
	v_fma_f32 v207, -v121, v121, 1.0
	v_fma_f32 v208, -v122, v122, 1.0
	v_fma_f32 v209, -v123, v123, 1.0
	v_fma_f32 v210, -v124, v124, 1.0
	v_fma_f32 v211, -v125, v125, 1.0
	v_fma_f32 v212, -v126, v126, 1.0
	v_fma_f32 v213, -v127, v127, 1.0
	v_max_f32_e32 v206, 0xda24260, v206
	v_max_f32_e32 v207, 0xda24260, v207
	v_max_f32_e32 v208, 0xda24260, v208
	v_max_f32_e32 v209, 0xda24260, v209
	v_max_f32_e32 v210, 0xda24260, v210
	v_max_f32_e32 v211, 0xda24260, v211
	v_max_f32_e32 v212, 0xda24260, v212
	v_max_f32_e32 v213, 0xda24260, v213
	v_mul_f32_e32 v198, v214, v206
	v_mul_f32_e32 v199, v215, v207
	v_mul_f32_e32 v200, v216, v208
	v_mul_f32_e32 v201, v217, v209
	v_mul_f32_e32 v202, v218, v210
	v_mul_f32_e32 v203, v219, v211
	v_mul_f32_e32 v204, v220, v212
	v_mul_f32_e32 v205, v221, v213
	v_mul_f32_e32 v214, v214, v198
	v_mul_f32_e32 v215, v215, v199
	v_mul_f32_e32 v216, v216, v200
	v_mul_f32_e32 v217, v217, v201
	v_mul_f32_e32 v218, v218, v202
	v_mul_f32_e32 v219, v219, v203
	v_mul_f32_e32 v220, v220, v204
	v_mul_f32_e32 v221, v221, v205
	v_rsq_f32_e32 v214, v214
	v_mul_f32_e32 v222, v108, v206
	v_rsq_f32_e32 v215, v215
	v_mul_f32_e32 v223, v109, v207
	v_rsq_f32_e32 v216, v216
	v_mul_f32_e32 v224, v110, v208
	v_rsq_f32_e32 v217, v217
	v_mul_f32_e32 v225, v111, v209
	v_rsq_f32_e32 v218, v218
	v_mul_f32_e32 v226, v142, v210
	v_rsq_f32_e32 v219, v219
	v_mul_f32_e32 v227, v143, v211
	v_rsq_f32_e32 v220, v220
	v_mul_f32_e32 v228, v144, v212
	v_rsq_f32_e32 v221, v221
	v_mul_f32_e32 v229, v145, v213
	v_mul_f32_e32 v170, v222, v214
	v_mul_f32_e32 v171, v223, v215
	v_mul_f32_e32 v172, v224, v216
	v_mul_f32_e32 v173, v225, v217
	v_mul_f32_e32 v174, v226, v218
	v_mul_f32_e32 v175, v227, v219
	v_mul_f32_e32 v176, v228, v220
	v_mul_f32_e32 v177, v229, v221
	v_mov_b32_e32 v198, v170
	v_mov_b32_e32 v199, v120
	v_fma_f32 v198, v121, v198, v171
	v_mul_f32_e32 v199, v199, v121
	v_fma_f32 v198, v122, v198, v172
	v_mul_f32_e32 v199, v199, v122
	v_fma_f32 v198, v123, v198, v173
	v_mul_f32_e32 v199, v199, v123
	v_fma_f32 v198, v124, v198, v174
	v_mul_f32_e32 v199, v199, v124
	v_fma_f32 v198, v125, v198, v175
	v_mul_f32_e32 v199, v199, v125
	v_fma_f32 v198, v126, v198, v176
	v_mul_f32_e32 v199, v199, v126
	v_fma_f32 v198, v127, v198, v177
	v_mul_f32_e32 v199, v199, v127
	ds_bpermute_b32 v164, v185, v199 offset:0
	ds_bpermute_b32 v246, v185, v198 offset:0
	ds_bpermute_b32 v165, v185, v199 offset:64
	ds_bpermute_b32 v247, v185, v198 offset:64
	ds_bpermute_b32 v166, v185, v199 offset:128
	ds_bpermute_b32 v248, v185, v198 offset:128
	ds_bpermute_b32 v167, v185, v199 offset:192
	ds_bpermute_b32 v249, v185, v198 offset:192
	s_waitcnt lgkmcnt(0)
	v_mov_b32_e32 v251, v246
	v_mov_b32_e32 v250, v164
	v_fma_f32 v251, v251, v165, v247
	v_mul_f32_e32 v250, v250, v165
	v_fma_f32 v251, v251, v166, v248
	v_mul_f32_e32 v250, v250, v166
	v_fma_f32 v251, v251, v167, v249
	v_mul_f32_e32 v250, v250, v167
	s_mov_b64 exec, s[10:11]
	ds_write_b64 v182, v[250:251] offset:0
	s_mov_b64 exec, -1
	s_waitcnt lgkmcnt(0)
	s_barrier
	ds_read2_b64 v[4:7], v183 offset0:0 offset1:16
	s_add_i32 s52, s4, 0
	s_lshl_b32 s52, s52, 12
	v_add_u32_e32 v197, s52, v184
	s_waitcnt lgkmcnt(0)
	v_fma_f32 v198, v180, v4, v5
	v_cndmask_b32_e64 v199, v180, v198, s[24:25]
	v_fma_f32 v180, v198, v6, v7
	v_fma_f32 v200, v199, v164, v246
	v_cndmask_b32_e64 v199, v199, v200, s[16:17]
	v_fma_f32 v200, v199, v165, v247
	v_cndmask_b32_e64 v199, v199, v200, s[20:21]
	v_fma_f32 v200, v199, v166, v248
	v_cndmask_b32_e64 v199, v199, v200, s[22:23]
	v_fma_f32 v214, v120, v199, v170
	v_fma_f32 v215, v121, v214, v171
	v_fma_f32 v216, v122, v215, v172
	v_fma_f32 v217, v123, v216, v173
	v_fma_f32 v218, v124, v217, v174
	v_fma_f32 v219, v125, v218, v175
	v_fma_f32 v220, v126, v219, v176
	v_fma_f32 v221, v127, v220, v177
	ds_read_u16 v206, v197 offset:0
	ds_read_u16 v207, v197 offset:64
	ds_read_u16 v208, v197 offset:128
	ds_read_u16 v209, v197 offset:192
	ds_read_u16 v210, v197 offset:256
	ds_read_u16 v211, v197 offset:320
	ds_read_u16 v212, v197 offset:384
	ds_read_u16 v213, v197 offset:448
	s_waitcnt lgkmcnt(0)
	v_lshlrev_b32_e32 v206, 16, v206
	v_lshlrev_b32_e32 v207, 16, v207
	v_lshlrev_b32_e32 v208, 16, v208
	v_lshlrev_b32_e32 v209, 16, v209
	v_lshlrev_b32_e32 v210, 16, v210
	v_lshlrev_b32_e32 v211, 16, v211
	v_lshlrev_b32_e32 v212, 16, v212
	v_lshlrev_b32_e32 v213, 16, v213
	v_add_f32_e32 v214, v214, v206
	v_add_f32_e32 v215, v215, v207
	v_add_f32_e32 v216, v216, v208
	v_add_f32_e32 v217, v217, v209
	v_add_f32_e32 v218, v218, v210
	v_add_f32_e32 v219, v219, v211
	v_add_f32_e32 v220, v220, v212
	v_add_f32_e32 v221, v221, v213
	v_cvt_pk_bf16_f32 v206, v214, v215
	v_cvt_pk_bf16_f32 v208, v216, v217
	v_cvt_pk_bf16_f32 v210, v218, v219
	v_cvt_pk_bf16_f32 v212, v220, v221
	ds_write_b16 v197, v206 offset:0
	ds_write_b16_d16_hi v197, v206 offset:64
	ds_write_b16 v197, v208 offset:128
	ds_write_b16_d16_hi v197, v208 offset:192
	ds_write_b16 v197, v210 offset:256
	ds_write_b16_d16_hi v197, v210 offset:320
	ds_write_b16 v197, v212 offset:384
	ds_write_b16_d16_hi v197, v212 offset:448
	ds_read_b128 v[198:201], v130 offset:0
	ds_read_b128 v[214:217], v130 offset:576
	ds_read_b128 v[202:205], v131 offset:0
	ds_read_b128 v[218:221], v131 offset:576
	ds_read_b128 v[206:209], v130 offset:144
	ds_read_b128 v[222:225], v130 offset:720
	ds_read_b128 v[210:213], v131 offset:144
	s_waitcnt lgkmcnt(14)
	ds_read_b128 v[226:229], v131 offset:720
	s_waitcnt lgkmcnt(6)
	v_mfma_f32_16x16x32_bf16 v[100:103], v[198:201], v[20:23], v[12:15]
	v_mfma_f32_16x16x32_bf16 v[112:115], v[214:217], v[20:23], v[12:15]
	v_mfma_f32_16x16x32_bf16 v[138:141], v[214:217], v[52:55], v[16:19]
	v_mfma_f32_16x16x32_bf16 v[104:107], v[198:201], v[52:55], v[16:19]
	v_mfma_f32_16x16x32_bf16 v[108:111], v[198:201], v[84:87], v[242:245]
	v_mfma_f32_16x16x32_bf16 v[142:145], v[214:217], v[84:87], v[242:245]
	s_waitcnt lgkmcnt(4)
	v_mfma_f32_16x16x32_bf16 v[100:103], v[202:205], v[24:27], v[100:103]
	v_mfma_f32_16x16x32_bf16 v[112:115], v[218:221], v[24:27], v[112:115]
	v_mfma_f32_16x16x32_bf16 v[138:141], v[218:221], v[56:59], v[138:141]
	v_mfma_f32_16x16x32_bf16 v[104:107], v[202:205], v[56:59], v[104:107]
	ds_read_b128 v[198:201], v130 offset:288
	ds_read_b128 v[214:217], v130 offset:864
	ds_read_b128 v[202:205], v131 offset:288
	ds_read_b128 v[218:221], v131 offset:864
	s_waitcnt lgkmcnt(6)
	v_mfma_f32_16x16x32_bf16 v[100:103], v[206:209], v[28:31], v[100:103]
	v_mfma_f32_16x16x32_bf16 v[112:115], v[222:225], v[28:31], v[112:115]
	v_mfma_f32_16x16x32_bf16 v[138:141], v[222:225], v[60:63], v[138:141]
	v_mfma_f32_16x16x32_bf16 v[104:107], v[206:209], v[60:63], v[104:107]
	v_mfma_f32_16x16x32_bf16 v[108:111], v[206:209], v[88:91], v[108:111]
	v_mfma_f32_16x16x32_bf16 v[142:145], v[222:225], v[88:91], v[142:145]
	s_waitcnt lgkmcnt(4)
	v_mfma_f32_16x16x32_bf16 v[100:103], v[210:213], v[32:35], v[100:103]
	v_mfma_f32_16x16x32_bf16 v[112:115], v[226:229], v[32:35], v[112:115]
	v_mfma_f32_16x16x32_bf16 v[138:141], v[226:229], v[64:67], v[138:141]
	v_mfma_f32_16x16x32_bf16 v[104:107], v[210:213], v[64:67], v[104:107]
	ds_read_b128 v[206:209], v130 offset:432
	ds_read_b128 v[222:225], v130 offset:1008
	ds_read_b128 v[210:213], v131 offset:432
	ds_read_b128 v[226:229], v131 offset:1008
	s_waitcnt lgkmcnt(6)
	v_mfma_f32_16x16x32_bf16 v[100:103], v[198:201], v[36:39], v[100:103]
	v_mfma_f32_16x16x32_bf16 v[112:115], v[214:217], v[36:39], v[112:115]
	v_mfma_f32_16x16x32_bf16 v[138:141], v[214:217], v[68:71], v[138:141]
	v_mfma_f32_16x16x32_bf16 v[104:107], v[198:201], v[68:71], v[104:107]
	v_mfma_f32_16x16x32_bf16 v[108:111], v[198:201], v[92:95], v[108:111]
	v_mfma_f32_16x16x32_bf16 v[142:145], v[214:217], v[92:95], v[142:145]
	s_waitcnt lgkmcnt(4)
	v_mfma_f32_16x16x32_bf16 v[100:103], v[202:205], v[40:43], v[100:103]
	v_mfma_f32_16x16x32_bf16 v[112:115], v[218:221], v[40:43], v[112:115]
	v_mfma_f32_16x16x32_bf16 v[138:141], v[218:221], v[72:75], v[138:141]
	v_mfma_f32_16x16x32_bf16 v[104:107], v[202:205], v[72:75], v[104:107]
	s_waitcnt lgkmcnt(2)
	v_mfma_f32_16x16x32_bf16 v[100:103], v[206:209], v[44:47], v[100:103]
	v_mfma_f32_16x16x32_bf16 v[112:115], v[222:225], v[44:47], v[112:115]
	v_mfma_f32_16x16x32_bf16 v[138:141], v[222:225], v[76:79], v[138:141]
	v_mfma_f32_16x16x32_bf16 v[104:107], v[206:209], v[76:79], v[104:107]
	v_mfma_f32_16x16x32_bf16 v[108:111], v[206:209], v[96:99], v[108:111]
	v_mfma_f32_16x16x32_bf16 v[142:145], v[222:225], v[96:99], v[142:145]
	s_waitcnt lgkmcnt(0)
	v_mfma_f32_16x16x32_bf16 v[100:103], v[210:213], v[48:51], v[100:103]
	v_mfma_f32_16x16x32_bf16 v[112:115], v[226:229], v[48:51], v[112:115]
	v_mfma_f32_16x16x32_bf16 v[138:141], v[226:229], v[80:83], v[138:141]
	v_mfma_f32_16x16x32_bf16 v[104:107], v[210:213], v[80:83], v[104:107]
	s_waitcnt lgkmcnt(0)
	s_barrier
	s_waitcnt vmcnt(5)
	ds_write_b128 v134, v[230:233]
	ds_write_b128 v134, v[234:237] offset:4608
	ds_write_b128 v135, v[238:241]
	s_add_i32 s64, s4, 0
	s_mul_i32 s71, s64, 0x30000
	s_add_u32 s38, s60, s71
	s_addc_u32 s39, s61, 0
	s_lshl_b32 s64, s64, 12
	v_add_u32_e32 v136, s64, v195
	ds_read_b128 v[116:119], v136
	s_waitcnt vmcnt(3)
	s_waitcnt lgkmcnt(0)
	v_lshlrev_b32_e32 v136, 16, v116
	v_lshlrev_b32_e32 v137, 16, v8
	v_and_b32_e32 v168, 0xffff0000, v116
	v_and_b32_e32 v169, 0xffff0000, v8
	v_mul_f32_e32 v136, v136, v137
	v_mul_f32_e32 v168, v168, v169
	v_cvt_pk_bf16_f32 v116, v136, v168
	v_lshlrev_b32_e32 v136, 16, v117
	v_lshlrev_b32_e32 v137, 16, v9
	v_and_b32_e32 v168, 0xffff0000, v117
	v_and_b32_e32 v169, 0xffff0000, v9
	v_mul_f32_e32 v136, v136, v137
	v_mul_f32_e32 v168, v168, v169
	v_cvt_pk_bf16_f32 v117, v136, v168
	v_lshlrev_b32_e32 v136, 16, v118
	v_lshlrev_b32_e32 v137, 16, v10
	v_and_b32_e32 v168, 0xffff0000, v118
	v_and_b32_e32 v169, 0xffff0000, v10
	v_mul_f32_e32 v136, v136, v137
	v_mul_f32_e32 v168, v168, v169
	v_cvt_pk_bf16_f32 v118, v136, v168
	v_lshlrev_b32_e32 v136, 16, v119
	v_lshlrev_b32_e32 v137, 16, v11
	v_and_b32_e32 v168, 0xffff0000, v119
	v_and_b32_e32 v169, 0xffff0000, v11
	v_mul_f32_e32 v136, v136, v137
	v_mul_f32_e32 v168, v168, v169
	v_cvt_pk_bf16_f32 v119, v136, v168
	global_store_dwordx4 v255, v[116:119], s[38:39]
	s_add_i32 s64, s4, 1
	s_mul_i32 s71, s64, 0x30000
	s_add_u32 s38, s60, s71
	s_addc_u32 s39, s61, 0
	s_lshl_b32 s64, s64, 12
	global_load_dwordx4 v[8:11], v255, s[38:39]
	s_add_i32 s52, s4, 4
	s_min_u32 s52, s52, 31
	s_lshl_b32 s52, s52, 13
	s_add_u32 s26, s50, s52
	s_addc_u32 s27, s51, 0
	global_load_dwordx4 v[230:233], v154, s[26:27]
	global_load_dwordx4 v[234:237], v155, s[26:27]
	global_load_dwordx4 v[238:241], v159, s[26:27]
	v_exp_f32_e32 v198, v100
	v_exp_f32_e32 v199, v101
	v_exp_f32_e32 v200, v102
	v_exp_f32_e32 v201, v103
	v_exp_f32_e32 v202, v112
	v_exp_f32_e32 v203, v113
	v_exp_f32_e32 v204, v114
	v_exp_f32_e32 v205, v115
	v_exp_f32_e32 v214, v104
	v_add_f32_e32 v198, 1.0, v198
	v_exp_f32_e32 v215, v105
	v_add_f32_e32 v199, 1.0, v199
	v_exp_f32_e32 v216, v106
	v_add_f32_e32 v200, 1.0, v200
	v_exp_f32_e32 v217, v107
	v_add_f32_e32 v201, 1.0, v201
	v_exp_f32_e32 v218, v138
	v_add_f32_e32 v202, 1.0, v202
	v_exp_f32_e32 v219, v139
	v_add_f32_e32 v203, 1.0, v203
	v_exp_f32_e32 v220, v140
	v_add_f32_e32 v204, 1.0, v204
	v_exp_f32_e32 v221, v141
	v_add_f32_e32 v205, 1.0, v205
	v_rcp_f32_e32 v198, v198
	v_add_f32_e32 v214, 1.0, v214
	v_rcp_f32_e32 v199, v199
	v_add_f32_e32 v215, 1.0, v215
	v_rcp_f32_e32 v200, v200
	v_add_f32_e32 v216, 1.0, v216
	v_rcp_f32_e32 v201, v201
	v_add_f32_e32 v217, 1.0, v217
	v_rcp_f32_e32 v202, v202
	v_add_f32_e32 v218, 1.0, v218
	v_rcp_f32_e32 v203, v203
	v_add_f32_e32 v219, 1.0, v219
	v_rcp_f32_e32 v204, v204
	v_add_f32_e32 v220, 1.0, v220
	v_rcp_f32_e32 v205, v205
	v_add_f32_e32 v221, 1.0, v221
	v_mul_f32_e32 v198, v179, v198
	v_mul_f32_e32 v199, v179, v199
	v_mul_f32_e32 v200, v179, v200
	v_mul_f32_e32 v201, v179, v201
	v_mul_f32_e32 v202, v179, v202
	v_mul_f32_e32 v203, v179, v203
	v_mul_f32_e32 v204, v179, v204
	v_mul_f32_e32 v205, v179, v205
	v_exp_f32_e32 v120, v198
	v_exp_f32_e32 v121, v199
	v_exp_f32_e32 v122, v200
	v_exp_f32_e32 v123, v201
	v_exp_f32_e32 v124, v202
	v_exp_f32_e32 v125, v203
	v_exp_f32_e32 v126, v204
	v_exp_f32_e32 v127, v205
	v_fma_f32 v206, -v120, v120, 1.0
	v_fma_f32 v207, -v121, v121, 1.0
	v_fma_f32 v208, -v122, v122, 1.0
	v_fma_f32 v209, -v123, v123, 1.0
	v_fma_f32 v210, -v124, v124, 1.0
	v_fma_f32 v211, -v125, v125, 1.0
	v_fma_f32 v212, -v126, v126, 1.0
	v_fma_f32 v213, -v127, v127, 1.0
	v_max_f32_e32 v206, 0xda24260, v206
	v_max_f32_e32 v207, 0xda24260, v207
	v_max_f32_e32 v208, 0xda24260, v208
	v_max_f32_e32 v209, 0xda24260, v209
	v_max_f32_e32 v210, 0xda24260, v210
	v_max_f32_e32 v211, 0xda24260, v211
	v_max_f32_e32 v212, 0xda24260, v212
	v_max_f32_e32 v213, 0xda24260, v213
	v_mul_f32_e32 v198, v214, v206
	v_mul_f32_e32 v199, v215, v207
	v_mul_f32_e32 v200, v216, v208
	v_mul_f32_e32 v201, v217, v209
	v_mul_f32_e32 v202, v218, v210
	v_mul_f32_e32 v203, v219, v211
	v_mul_f32_e32 v204, v220, v212
	v_mul_f32_e32 v205, v221, v213
	v_mul_f32_e32 v214, v214, v198
	v_mul_f32_e32 v215, v215, v199
	v_mul_f32_e32 v216, v216, v200
	v_mul_f32_e32 v217, v217, v201
	v_mul_f32_e32 v218, v218, v202
	v_mul_f32_e32 v219, v219, v203
	v_mul_f32_e32 v220, v220, v204
	v_mul_f32_e32 v221, v221, v205
	v_rsq_f32_e32 v214, v214
	v_mul_f32_e32 v222, v108, v206
	v_rsq_f32_e32 v215, v215
	v_mul_f32_e32 v223, v109, v207
	v_rsq_f32_e32 v216, v216
	v_mul_f32_e32 v224, v110, v208
	v_rsq_f32_e32 v217, v217
	v_mul_f32_e32 v225, v111, v209
	v_rsq_f32_e32 v218, v218
	v_mul_f32_e32 v226, v142, v210
	v_rsq_f32_e32 v219, v219
	v_mul_f32_e32 v227, v143, v211
	v_rsq_f32_e32 v220, v220
	v_mul_f32_e32 v228, v144, v212
	v_rsq_f32_e32 v221, v221
	v_mul_f32_e32 v229, v145, v213
	v_mul_f32_e32 v170, v222, v214
	v_mul_f32_e32 v171, v223, v215
	v_mul_f32_e32 v172, v224, v216
	v_mul_f32_e32 v173, v225, v217
	v_mul_f32_e32 v174, v226, v218
	v_mul_f32_e32 v175, v227, v219
	v_mul_f32_e32 v176, v228, v220
	v_mul_f32_e32 v177, v229, v221
	v_mov_b32_e32 v198, v170
	v_mov_b32_e32 v199, v120
	v_fma_f32 v198, v121, v198, v171
	v_mul_f32_e32 v199, v199, v121
	v_fma_f32 v198, v122, v198, v172
	v_mul_f32_e32 v199, v199, v122
	v_fma_f32 v198, v123, v198, v173
	v_mul_f32_e32 v199, v199, v123
	v_fma_f32 v198, v124, v198, v174
	v_mul_f32_e32 v199, v199, v124
	v_fma_f32 v198, v125, v198, v175
	v_mul_f32_e32 v199, v199, v125
	v_fma_f32 v198, v126, v198, v176
	v_mul_f32_e32 v199, v199, v126
	v_fma_f32 v198, v127, v198, v177
	v_mul_f32_e32 v199, v199, v127
	ds_bpermute_b32 v164, v185, v199 offset:0
	ds_bpermute_b32 v246, v185, v198 offset:0
	ds_bpermute_b32 v165, v185, v199 offset:64
	ds_bpermute_b32 v247, v185, v198 offset:64
	ds_bpermute_b32 v166, v185, v199 offset:128
	ds_bpermute_b32 v248, v185, v198 offset:128
	ds_bpermute_b32 v167, v185, v199 offset:192
	ds_bpermute_b32 v249, v185, v198 offset:192
	s_waitcnt lgkmcnt(0)
	v_mov_b32_e32 v251, v246
	v_mov_b32_e32 v250, v164
	v_fma_f32 v251, v251, v165, v247
	v_mul_f32_e32 v250, v250, v165
	v_fma_f32 v251, v251, v166, v248
	v_mul_f32_e32 v250, v250, v166
	v_fma_f32 v251, v251, v167, v249
	v_mul_f32_e32 v250, v250, v167
	s_mov_b64 exec, s[10:11]
	ds_write_b64 v182, v[250:251] offset:1024
	s_mov_b64 exec, -1
	s_waitcnt lgkmcnt(0)
	s_barrier
	ds_read2_b64 v[4:7], v183 offset0:128 offset1:144
	s_add_i32 s52, s4, 1
	s_lshl_b32 s52, s52, 12
	v_add_u32_e32 v197, s52, v184
	s_waitcnt lgkmcnt(0)
	v_fma_f32 v198, v180, v4, v5
	v_cndmask_b32_e64 v199, v180, v198, s[24:25]
	v_fma_f32 v180, v198, v6, v7
	v_fma_f32 v200, v199, v164, v246
	v_cndmask_b32_e64 v199, v199, v200, s[16:17]
	v_fma_f32 v200, v199, v165, v247
	v_cndmask_b32_e64 v199, v199, v200, s[20:21]
	v_fma_f32 v200, v199, v166, v248
	v_cndmask_b32_e64 v199, v199, v200, s[22:23]
	v_fma_f32 v214, v120, v199, v170
	v_fma_f32 v215, v121, v214, v171
	v_fma_f32 v216, v122, v215, v172
	v_fma_f32 v217, v123, v216, v173
	v_fma_f32 v218, v124, v217, v174
	v_fma_f32 v219, v125, v218, v175
	v_fma_f32 v220, v126, v219, v176
	v_fma_f32 v221, v127, v220, v177
	ds_read_u16 v206, v197 offset:0
	ds_read_u16 v207, v197 offset:64
	ds_read_u16 v208, v197 offset:128
	ds_read_u16 v209, v197 offset:192
	ds_read_u16 v210, v197 offset:256
	ds_read_u16 v211, v197 offset:320
	ds_read_u16 v212, v197 offset:384
	ds_read_u16 v213, v197 offset:448
	s_waitcnt lgkmcnt(0)
	v_lshlrev_b32_e32 v206, 16, v206
	v_lshlrev_b32_e32 v207, 16, v207
	v_lshlrev_b32_e32 v208, 16, v208
	v_lshlrev_b32_e32 v209, 16, v209
	v_lshlrev_b32_e32 v210, 16, v210
	v_lshlrev_b32_e32 v211, 16, v211
	v_lshlrev_b32_e32 v212, 16, v212
	v_lshlrev_b32_e32 v213, 16, v213
	v_add_f32_e32 v214, v214, v206
	v_add_f32_e32 v215, v215, v207
	v_add_f32_e32 v216, v216, v208
	v_add_f32_e32 v217, v217, v209
	v_add_f32_e32 v218, v218, v210
	v_add_f32_e32 v219, v219, v211
	v_add_f32_e32 v220, v220, v212
	v_add_f32_e32 v221, v221, v213
	v_cvt_pk_bf16_f32 v206, v214, v215
	v_cvt_pk_bf16_f32 v208, v216, v217
	v_cvt_pk_bf16_f32 v210, v218, v219
	v_cvt_pk_bf16_f32 v212, v220, v221
	ds_write_b16 v197, v206 offset:0
	ds_write_b16_d16_hi v197, v206 offset:64
	ds_write_b16 v197, v208 offset:128
	ds_write_b16_d16_hi v197, v208 offset:192
	ds_write_b16 v197, v210 offset:256
	ds_write_b16_d16_hi v197, v210 offset:320
	ds_write_b16 v197, v212 offset:384
	ds_write_b16_d16_hi v197, v212 offset:448
	s_add_i32 s4, s4, 2
	s_cmp_lt_u32 s4, 32
	s_cbranch_scc1 .Lrec2_loopB_d0
	s_waitcnt lgkmcnt(0)
	s_barrier
	s_add_i32 s64, s4, -1
	s_mul_i32 s71, s64, 0x30000
	s_add_u32 s38, s60, s71
	s_addc_u32 s39, s61, 0
	s_lshl_b32 s64, s64, 12
	v_add_u32_e32 v136, s64, v195
	ds_read_b128 v[116:119], v136
	s_waitcnt vmcnt(3)
	s_waitcnt lgkmcnt(0)
	v_lshlrev_b32_e32 v136, 16, v116
	v_lshlrev_b32_e32 v137, 16, v8
	v_and_b32_e32 v168, 0xffff0000, v116
	v_and_b32_e32 v169, 0xffff0000, v8
	v_mul_f32_e32 v136, v136, v137
	v_mul_f32_e32 v168, v168, v169
	v_cvt_pk_bf16_f32 v116, v136, v168
	v_lshlrev_b32_e32 v136, 16, v117
	v_lshlrev_b32_e32 v137, 16, v9
	v_and_b32_e32 v168, 0xffff0000, v117
	v_and_b32_e32 v169, 0xffff0000, v9
	v_mul_f32_e32 v136, v136, v137
	v_mul_f32_e32 v168, v168, v169
	v_cvt_pk_bf16_f32 v117, v136, v168
	v_lshlrev_b32_e32 v136, 16, v118
	v_lshlrev_b32_e32 v137, 16, v10
	v_and_b32_e32 v168, 0xffff0000, v118
	v_and_b32_e32 v169, 0xffff0000, v10
	v_mul_f32_e32 v136, v136, v137
	v_mul_f32_e32 v168, v168, v169
	v_cvt_pk_bf16_f32 v118, v136, v168
	v_lshlrev_b32_e32 v136, 16, v119
	v_lshlrev_b32_e32 v137, 16, v11
	v_and_b32_e32 v168, 0xffff0000, v119
	v_and_b32_e32 v169, 0xffff0000, v11
	v_mul_f32_e32 v136, v136, v137
	v_mul_f32_e32 v168, v168, v169
	v_cvt_pk_bf16_f32 v119, v136, v168
	global_store_dwordx4 v255, v[116:119], s[38:39]
	s_barrier
	s_branch .Lrec2_done

.Lrec2_loopA_d1:
	ds_read_b128 v[198:201], v130 offset:0
	ds_read_b128 v[214:217], v130 offset:576
	ds_read_b128 v[202:205], v131 offset:0
	ds_read_b128 v[218:221], v131 offset:576
	ds_read_b128 v[206:209], v130 offset:144
	ds_read_b128 v[222:225], v130 offset:720
	ds_read_b128 v[210:213], v131 offset:144
	s_waitcnt lgkmcnt(14)
	ds_read_b128 v[226:229], v131 offset:720
	s_waitcnt lgkmcnt(6)
	v_mfma_f32_16x16x32_bf16 v[100:103], v[198:201], v[20:23], v[12:15]
	v_mfma_f32_16x16x32_bf16 v[112:115], v[214:217], v[20:23], v[12:15]
	v_mfma_f32_16x16x32_bf16 v[138:141], v[214:217], v[52:55], v[16:19]
	v_mfma_f32_16x16x32_bf16 v[104:107], v[198:201], v[52:55], v[16:19]
	v_mfma_f32_16x16x32_bf16 v[108:111], v[198:201], v[84:87], v[242:245]
	v_mfma_f32_16x16x32_bf16 v[142:145], v[214:217], v[84:87], v[242:245]
	s_waitcnt lgkmcnt(4)
	v_mfma_f32_16x16x32_bf16 v[100:103], v[202:205], v[24:27], v[100:103]
	v_mfma_f32_16x16x32_bf16 v[112:115], v[218:221], v[24:27], v[112:115]
	v_mfma_f32_16x16x32_bf16 v[138:141], v[218:221], v[56:59], v[138:141]
	v_mfma_f32_16x16x32_bf16 v[104:107], v[202:205], v[56:59], v[104:107]
	ds_read_b128 v[198:201], v130 offset:288
	ds_read_b128 v[214:217], v130 offset:864
	ds_read_b128 v[202:205], v131 offset:288
	ds_read_b128 v[218:221], v131 offset:864
	s_waitcnt lgkmcnt(6)
	v_mfma_f32_16x16x32_bf16 v[100:103], v[206:209], v[28:31], v[100:103]
	v_mfma_f32_16x16x32_bf16 v[112:115], v[222:225], v[28:31], v[112:115]
	v_mfma_f32_16x16x32_bf16 v[138:141], v[222:225], v[60:63], v[138:141]
	v_mfma_f32_16x16x32_bf16 v[104:107], v[206:209], v[60:63], v[104:107]
	v_mfma_f32_16x16x32_bf16 v[108:111], v[206:209], v[88:91], v[108:111]
	v_mfma_f32_16x16x32_bf16 v[142:145], v[222:225], v[88:91], v[142:145]
	s_waitcnt lgkmcnt(4)
	v_mfma_f32_16x16x32_bf16 v[100:103], v[210:213], v[32:35], v[100:103]
	v_mfma_f32_16x16x32_bf16 v[112:115], v[226:229], v[32:35], v[112:115]
	v_mfma_f32_16x16x32_bf16 v[138:141], v[226:229], v[64:67], v[138:141]
	v_mfma_f32_16x16x32_bf16 v[104:107], v[210:213], v[64:67], v[104:107]
	ds_read_b128 v[206:209], v130 offset:432
	ds_read_b128 v[222:225], v130 offset:1008
	ds_read_b128 v[210:213], v131 offset:432
	ds_read_b128 v[226:229], v131 offset:1008
	s_waitcnt lgkmcnt(6)
	v_mfma_f32_16x16x32_bf16 v[100:103], v[198:201], v[36:39], v[100:103]
	v_mfma_f32_16x16x32_bf16 v[112:115], v[214:217], v[36:39], v[112:115]
	v_mfma_f32_16x16x32_bf16 v[138:141], v[214:217], v[68:71], v[138:141]
	v_mfma_f32_16x16x32_bf16 v[104:107], v[198:201], v[68:71], v[104:107]
	v_mfma_f32_16x16x32_bf16 v[108:111], v[198:201], v[92:95], v[108:111]
	v_mfma_f32_16x16x32_bf16 v[142:145], v[214:217], v[92:95], v[142:145]
	s_waitcnt lgkmcnt(4)
	v_mfma_f32_16x16x32_bf16 v[100:103], v[202:205], v[40:43], v[100:103]
	v_mfma_f32_16x16x32_bf16 v[112:115], v[218:221], v[40:43], v[112:115]
	v_mfma_f32_16x16x32_bf16 v[138:141], v[218:221], v[72:75], v[138:141]
	v_mfma_f32_16x16x32_bf16 v[104:107], v[202:205], v[72:75], v[104:107]
	s_waitcnt lgkmcnt(2)
	v_mfma_f32_16x16x32_bf16 v[100:103], v[206:209], v[44:47], v[100:103]
	v_mfma_f32_16x16x32_bf16 v[112:115], v[222:225], v[44:47], v[112:115]
	v_mfma_f32_16x16x32_bf16 v[138:141], v[222:225], v[76:79], v[138:141]
	v_mfma_f32_16x16x32_bf16 v[104:107], v[206:209], v[76:79], v[104:107]
	v_mfma_f32_16x16x32_bf16 v[108:111], v[206:209], v[96:99], v[108:111]
	v_mfma_f32_16x16x32_bf16 v[142:145], v[222:225], v[96:99], v[142:145]
	s_waitcnt lgkmcnt(0)
	v_mfma_f32_16x16x32_bf16 v[100:103], v[210:213], v[48:51], v[100:103]
	v_mfma_f32_16x16x32_bf16 v[112:115], v[226:229], v[48:51], v[112:115]
	v_mfma_f32_16x16x32_bf16 v[138:141], v[226:229], v[80:83], v[138:141]
	v_mfma_f32_16x16x32_bf16 v[104:107], v[210:213], v[80:83], v[104:107]
	s_waitcnt lgkmcnt(0)
	s_barrier
	s_waitcnt vmcnt(3)
	ds_write_b128 v134, v[146:149]
	ds_write_b128 v134, v[150:153] offset:4608
	ds_write_b128 v135, v[160:163]
	s_add_i32 s52, s4, 3
	s_min_u32 s52, s52, 31
	s_sub_i32 s52, 31, s52
	s_lshl_b32 s52, s52, 13
	s_add_u32 s26, s50, s52
	s_addc_u32 s27, s51, 0
	global_load_dwordx4 v[146:149], v154, s[26:27]
	global_load_dwordx4 v[150:153], v155, s[26:27]
	global_load_dwordx4 v[160:163], v159, s[26:27]
	v_exp_f32_e32 v198, v100
	v_exp_f32_e32 v199, v101
	v_exp_f32_e32 v200, v102
	v_exp_f32_e32 v201, v103
	v_exp_f32_e32 v202, v112
	v_exp_f32_e32 v203, v113
	v_exp_f32_e32 v204, v114
	v_exp_f32_e32 v205, v115
	v_exp_f32_e32 v214, v104
	v_add_f32_e32 v198, 1.0, v198
	v_exp_f32_e32 v215, v105
	v_add_f32_e32 v199, 1.0, v199
	v_exp_f32_e32 v216, v106
	v_add_f32_e32 v200, 1.0, v200
	v_exp_f32_e32 v217, v107
	v_add_f32_e32 v201, 1.0, v201
	v_exp_f32_e32 v218, v138
	v_add_f32_e32 v202, 1.0, v202
	v_exp_f32_e32 v219, v139
	v_add_f32_e32 v203, 1.0, v203
	v_exp_f32_e32 v220, v140
	v_add_f32_e32 v204, 1.0, v204
	v_exp_f32_e32 v221, v141
	v_add_f32_e32 v205, 1.0, v205
	v_rcp_f32_e32 v198, v198
	v_add_f32_e32 v214, 1.0, v214
	v_rcp_f32_e32 v199, v199
	v_add_f32_e32 v215, 1.0, v215
	v_rcp_f32_e32 v200, v200
	v_add_f32_e32 v216, 1.0, v216
	v_rcp_f32_e32 v201, v201
	v_add_f32_e32 v217, 1.0, v217
	v_rcp_f32_e32 v202, v202
	v_add_f32_e32 v218, 1.0, v218
	v_rcp_f32_e32 v203, v203
	v_add_f32_e32 v219, 1.0, v219
	v_rcp_f32_e32 v204, v204
	v_add_f32_e32 v220, 1.0, v220
	v_rcp_f32_e32 v205, v205
	v_add_f32_e32 v221, 1.0, v221
	v_mul_f32_e32 v198, v179, v198
	v_mul_f32_e32 v199, v179, v199
	v_mul_f32_e32 v200, v179, v200
	v_mul_f32_e32 v201, v179, v201
	v_mul_f32_e32 v202, v179, v202
	v_mul_f32_e32 v203, v179, v203
	v_mul_f32_e32 v204, v179, v204
	v_mul_f32_e32 v205, v179, v205
	v_exp_f32_e32 v120, v198
	v_exp_f32_e32 v121, v199
	v_exp_f32_e32 v122, v200
	v_exp_f32_e32 v123, v201
	v_exp_f32_e32 v124, v202
	v_exp_f32_e32 v125, v203
	v_exp_f32_e32 v126, v204
	v_exp_f32_e32 v127, v205
	v_fma_f32 v206, -v120, v120, 1.0
	v_fma_f32 v207, -v121, v121, 1.0
	v_fma_f32 v208, -v122, v122, 1.0
	v_fma_f32 v209, -v123, v123, 1.0
	v_fma_f32 v210, -v124, v124, 1.0
	v_fma_f32 v211, -v125, v125, 1.0
	v_fma_f32 v212, -v126, v126, 1.0
	v_fma_f32 v213, -v127, v127, 1.0
	v_max_f32_e32 v206, 0xda24260, v206
	v_max_f32_e32 v207, 0xda24260, v207
	v_max_f32_e32 v208, 0xda24260, v208
	v_max_f32_e32 v209, 0xda24260, v209
	v_max_f32_e32 v210, 0xda24260, v210
	v_max_f32_e32 v211, 0xda24260, v211
	v_max_f32_e32 v212, 0xda24260, v212
	v_max_f32_e32 v213, 0xda24260, v213
	v_mul_f32_e32 v198, v214, v206
	v_mul_f32_e32 v199, v215, v207
	v_mul_f32_e32 v200, v216, v208
	v_mul_f32_e32 v201, v217, v209
	v_mul_f32_e32 v202, v218, v210
	v_mul_f32_e32 v203, v219, v211
	v_mul_f32_e32 v204, v220, v212
	v_mul_f32_e32 v205, v221, v213
	v_mul_f32_e32 v214, v214, v198
	v_mul_f32_e32 v215, v215, v199
	v_mul_f32_e32 v216, v216, v200
	v_mul_f32_e32 v217, v217, v201
	v_mul_f32_e32 v218, v218, v202
	v_mul_f32_e32 v219, v219, v203
	v_mul_f32_e32 v220, v220, v204
	v_mul_f32_e32 v221, v221, v205
	v_rsq_f32_e32 v214, v214
	v_mul_f32_e32 v222, v108, v206
	v_rsq_f32_e32 v215, v215
	v_mul_f32_e32 v223, v109, v207
	v_rsq_f32_e32 v216, v216
	v_mul_f32_e32 v224, v110, v208
	v_rsq_f32_e32 v217, v217
	v_mul_f32_e32 v225, v111, v209
	v_rsq_f32_e32 v218, v218
	v_mul_f32_e32 v226, v142, v210
	v_rsq_f32_e32 v219, v219
	v_mul_f32_e32 v227, v143, v211
	v_rsq_f32_e32 v220, v220
	v_mul_f32_e32 v228, v144, v212
	v_rsq_f32_e32 v221, v221
	v_mul_f32_e32 v229, v145, v213
	v_mul_f32_e32 v170, v222, v214
	v_mul_f32_e32 v171, v223, v215
	v_mul_f32_e32 v172, v224, v216
	v_mul_f32_e32 v173, v225, v217
	v_mul_f32_e32 v174, v226, v218
	v_mul_f32_e32 v175, v227, v219
	v_mul_f32_e32 v176, v228, v220
	v_mul_f32_e32 v177, v229, v221
	v_mov_b32_e32 v198, v177
	v_mov_b32_e32 v199, v127
	v_fma_f32 v198, v126, v198, v176
	v_mul_f32_e32 v199, v199, v126
	v_fma_f32 v198, v125, v198, v175
	v_mul_f32_e32 v199, v199, v125
	v_fma_f32 v198, v124, v198, v174
	v_mul_f32_e32 v199, v199, v124
	v_fma_f32 v198, v123, v198, v173
	v_mul_f32_e32 v199, v199, v123
	v_fma_f32 v198, v122, v198, v172
	v_mul_f32_e32 v199, v199, v122
	v_fma_f32 v198, v121, v198, v171
	v_mul_f32_e32 v199, v199, v121
	v_fma_f32 v198, v120, v198, v170
	v_mul_f32_e32 v199, v199, v120
	ds_bpermute_b32 v164, v185, v199 offset:0
	ds_bpermute_b32 v246, v185, v198 offset:0
	ds_bpermute_b32 v165, v185, v199 offset:64
	ds_bpermute_b32 v247, v185, v198 offset:64
	ds_bpermute_b32 v166, v185, v199 offset:128
	ds_bpermute_b32 v248, v185, v198 offset:128
	ds_bpermute_b32 v167, v185, v199 offset:192
	ds_bpermute_b32 v249, v185, v198 offset:192
	s_waitcnt lgkmcnt(0)
	v_mov_b32_e32 v251, v249
	v_mov_b32_e32 v250, v167
	v_fma_f32 v251, v251, v166, v248
	v_mul_f32_e32 v250, v250, v166
	v_fma_f32 v251, v251, v165, v247
	v_mul_f32_e32 v250, v250, v165
	v_fma_f32 v251, v251, v164, v246
	v_mul_f32_e32 v250, v250, v164
	s_mov_b64 exec, s[10:11]
	ds_write_b64 v182, v[250:251] offset:0
	s_mov_b64 exec, -1
	s_waitcnt lgkmcnt(0)
	s_barrier
	ds_read2_b64 v[4:7], v183 offset0:0 offset1:16
	s_add_i32 s52, s4, 0
	s_sub_i32 s52, 31, s52
	s_lshl_b32 s52, s52, 12
	v_add_u32_e32 v197, s52, v184
	s_waitcnt lgkmcnt(0)
	v_fma_f32 v198, v180, v6, v7
	v_cndmask_b32_e64 v199, v180, v198, s[24:25]
	v_fma_f32 v180, v198, v4, v5
	v_fma_f32 v200, v199, v167, v249
	v_cndmask_b32_e64 v199, v199, v200, s[16:17]
	v_fma_f32 v200, v199, v166, v248
	v_cndmask_b32_e64 v199, v199, v200, s[20:21]
	v_fma_f32 v200, v199, v165, v247
	v_cndmask_b32_e64 v199, v199, v200, s[22:23]
	v_fma_f32 v221, v127, v199, v177
	v_fma_f32 v220, v126, v221, v176
	v_fma_f32 v219, v125, v220, v175
	v_fma_f32 v218, v124, v219, v174
	v_fma_f32 v217, v123, v218, v173
	v_fma_f32 v216, v122, v217, v172
	v_fma_f32 v215, v121, v216, v171
	v_fma_f32 v214, v120, v215, v170
	v_cvt_pk_bf16_f32 v206, v214, v215
	v_cvt_pk_bf16_f32 v208, v216, v217
	v_cvt_pk_bf16_f32 v210, v218, v219
	v_cvt_pk_bf16_f32 v212, v220, v221
	ds_write_b16 v197, v206 offset:0
	ds_write_b16_d16_hi v197, v206 offset:64
	ds_write_b16 v197, v208 offset:128
	ds_write_b16_d16_hi v197, v208 offset:192
	ds_write_b16 v197, v210 offset:256
	ds_write_b16_d16_hi v197, v210 offset:320
	ds_write_b16 v197, v212 offset:384
	ds_write_b16_d16_hi v197, v212 offset:448
	ds_read_b128 v[198:201], v130 offset:0
	ds_read_b128 v[214:217], v130 offset:576
	ds_read_b128 v[202:205], v131 offset:0
	ds_read_b128 v[218:221], v131 offset:576
	ds_read_b128 v[206:209], v130 offset:144
	ds_read_b128 v[222:225], v130 offset:720
	ds_read_b128 v[210:213], v131 offset:144
	s_waitcnt lgkmcnt(14)
	ds_read_b128 v[226:229], v131 offset:720
	s_waitcnt lgkmcnt(6)
	v_mfma_f32_16x16x32_bf16 v[100:103], v[198:201], v[20:23], v[12:15]
	v_mfma_f32_16x16x32_bf16 v[112:115], v[214:217], v[20:23], v[12:15]
	v_mfma_f32_16x16x32_bf16 v[138:141], v[214:217], v[52:55], v[16:19]
	v_mfma_f32_16x16x32_bf16 v[104:107], v[198:201], v[52:55], v[16:19]
	v_mfma_f32_16x16x32_bf16 v[108:111], v[198:201], v[84:87], v[242:245]
	v_mfma_f32_16x16x32_bf16 v[142:145], v[214:217], v[84:87], v[242:245]
	s_waitcnt lgkmcnt(4)
	v_mfma_f32_16x16x32_bf16 v[100:103], v[202:205], v[24:27], v[100:103]
	v_mfma_f32_16x16x32_bf16 v[112:115], v[218:221], v[24:27], v[112:115]
	v_mfma_f32_16x16x32_bf16 v[138:141], v[218:221], v[56:59], v[138:141]
	v_mfma_f32_16x16x32_bf16 v[104:107], v[202:205], v[56:59], v[104:107]
	ds_read_b128 v[198:201], v130 offset:288
	ds_read_b128 v[214:217], v130 offset:864
	ds_read_b128 v[202:205], v131 offset:288
	ds_read_b128 v[218:221], v131 offset:864
	s_waitcnt lgkmcnt(6)
	v_mfma_f32_16x16x32_bf16 v[100:103], v[206:209], v[28:31], v[100:103]
	v_mfma_f32_16x16x32_bf16 v[112:115], v[222:225], v[28:31], v[112:115]
	v_mfma_f32_16x16x32_bf16 v[138:141], v[222:225], v[60:63], v[138:141]
	v_mfma_f32_16x16x32_bf16 v[104:107], v[206:209], v[60:63], v[104:107]
	v_mfma_f32_16x16x32_bf16 v[108:111], v[206:209], v[88:91], v[108:111]
	v_mfma_f32_16x16x32_bf16 v[142:145], v[222:225], v[88:91], v[142:145]
	s_waitcnt lgkmcnt(4)
	v_mfma_f32_16x16x32_bf16 v[100:103], v[210:213], v[32:35], v[100:103]
	v_mfma_f32_16x16x32_bf16 v[112:115], v[226:229], v[32:35], v[112:115]
	v_mfma_f32_16x16x32_bf16 v[138:141], v[226:229], v[64:67], v[138:141]
	v_mfma_f32_16x16x32_bf16 v[104:107], v[210:213], v[64:67], v[104:107]
	ds_read_b128 v[206:209], v130 offset:432
	ds_read_b128 v[222:225], v130 offset:1008
	ds_read_b128 v[210:213], v131 offset:432
	ds_read_b128 v[226:229], v131 offset:1008
	s_waitcnt lgkmcnt(6)
	v_mfma_f32_16x16x32_bf16 v[100:103], v[198:201], v[36:39], v[100:103]
	v_mfma_f32_16x16x32_bf16 v[112:115], v[214:217], v[36:39], v[112:115]
	v_mfma_f32_16x16x32_bf16 v[138:141], v[214:217], v[68:71], v[138:141]
	v_mfma_f32_16x16x32_bf16 v[104:107], v[198:201], v[68:71], v[104:107]
	v_mfma_f32_16x16x32_bf16 v[108:111], v[198:201], v[92:95], v[108:111]
	v_mfma_f32_16x16x32_bf16 v[142:145], v[214:217], v[92:95], v[142:145]
	s_waitcnt lgkmcnt(4)
	v_mfma_f32_16x16x32_bf16 v[100:103], v[202:205], v[40:43], v[100:103]
	v_mfma_f32_16x16x32_bf16 v[112:115], v[218:221], v[40:43], v[112:115]
	v_mfma_f32_16x16x32_bf16 v[138:141], v[218:221], v[72:75], v[138:141]
	v_mfma_f32_16x16x32_bf16 v[104:107], v[202:205], v[72:75], v[104:107]
	s_waitcnt lgkmcnt(2)
	v_mfma_f32_16x16x32_bf16 v[100:103], v[206:209], v[44:47], v[100:103]
	v_mfma_f32_16x16x32_bf16 v[112:115], v[222:225], v[44:47], v[112:115]
	v_mfma_f32_16x16x32_bf16 v[138:141], v[222:225], v[76:79], v[138:141]
	v_mfma_f32_16x16x32_bf16 v[104:107], v[206:209], v[76:79], v[104:107]
	v_mfma_f32_16x16x32_bf16 v[108:111], v[206:209], v[96:99], v[108:111]
	v_mfma_f32_16x16x32_bf16 v[142:145], v[222:225], v[96:99], v[142:145]
	s_waitcnt lgkmcnt(0)
	v_mfma_f32_16x16x32_bf16 v[100:103], v[210:213], v[48:51], v[100:103]
	v_mfma_f32_16x16x32_bf16 v[112:115], v[226:229], v[48:51], v[112:115]
	v_mfma_f32_16x16x32_bf16 v[138:141], v[226:229], v[80:83], v[138:141]
	v_mfma_f32_16x16x32_bf16 v[104:107], v[210:213], v[80:83], v[104:107]
	s_waitcnt lgkmcnt(0)
	s_barrier
	s_waitcnt vmcnt(3)
	ds_write_b128 v134, v[230:233]
	ds_write_b128 v134, v[234:237] offset:4608
	ds_write_b128 v135, v[238:241]
	s_add_i32 s52, s4, 4
	s_min_u32 s52, s52, 31
	s_sub_i32 s52, 31, s52
	s_lshl_b32 s52, s52, 13
	s_add_u32 s26, s50, s52
	s_addc_u32 s27, s51, 0
	global_load_dwordx4 v[230:233], v154, s[26:27]
	global_load_dwordx4 v[234:237], v155, s[26:27]
	global_load_dwordx4 v[238:241], v159, s[26:27]
	v_exp_f32_e32 v198, v100
	v_exp_f32_e32 v199, v101
	v_exp_f32_e32 v200, v102
	v_exp_f32_e32 v201, v103
	v_exp_f32_e32 v202, v112
	v_exp_f32_e32 v203, v113
	v_exp_f32_e32 v204, v114
	v_exp_f32_e32 v205, v115
	v_exp_f32_e32 v214, v104
	v_add_f32_e32 v198, 1.0, v198
	v_exp_f32_e32 v215, v105
	v_add_f32_e32 v199, 1.0, v199
	v_exp_f32_e32 v216, v106
	v_add_f32_e32 v200, 1.0, v200
	v_exp_f32_e32 v217, v107
	v_add_f32_e32 v201, 1.0, v201
	v_exp_f32_e32 v218, v138
	v_add_f32_e32 v202, 1.0, v202
	v_exp_f32_e32 v219, v139
	v_add_f32_e32 v203, 1.0, v203
	v_exp_f32_e32 v220, v140
	v_add_f32_e32 v204, 1.0, v204
	v_exp_f32_e32 v221, v141
	v_add_f32_e32 v205, 1.0, v205
	v_rcp_f32_e32 v198, v198
	v_add_f32_e32 v214, 1.0, v214
	v_rcp_f32_e32 v199, v199
	v_add_f32_e32 v215, 1.0, v215
	v_rcp_f32_e32 v200, v200
	v_add_f32_e32 v216, 1.0, v216
	v_rcp_f32_e32 v201, v201
	v_add_f32_e32 v217, 1.0, v217
	v_rcp_f32_e32 v202, v202
	v_add_f32_e32 v218, 1.0, v218
	v_rcp_f32_e32 v203, v203
	v_add_f32_e32 v219, 1.0, v219
	v_rcp_f32_e32 v204, v204
	v_add_f32_e32 v220, 1.0, v220
	v_rcp_f32_e32 v205, v205
	v_add_f32_e32 v221, 1.0, v221
	v_mul_f32_e32 v198, v179, v198
	v_mul_f32_e32 v199, v179, v199
	v_mul_f32_e32 v200, v179, v200
	v_mul_f32_e32 v201, v179, v201
	v_mul_f32_e32 v202, v179, v202
	v_mul_f32_e32 v203, v179, v203
	v_mul_f32_e32 v204, v179, v204
	v_mul_f32_e32 v205, v179, v205
	v_exp_f32_e32 v120, v198
	v_exp_f32_e32 v121, v199
	v_exp_f32_e32 v122, v200
	v_exp_f32_e32 v123, v201
	v_exp_f32_e32 v124, v202
	v_exp_f32_e32 v125, v203
	v_exp_f32_e32 v126, v204
	v_exp_f32_e32 v127, v205
	v_fma_f32 v206, -v120, v120, 1.0
	v_fma_f32 v207, -v121, v121, 1.0
	v_fma_f32 v208, -v122, v122, 1.0
	v_fma_f32 v209, -v123, v123, 1.0
	v_fma_f32 v210, -v124, v124, 1.0
	v_fma_f32 v211, -v125, v125, 1.0
	v_fma_f32 v212, -v126, v126, 1.0
	v_fma_f32 v213, -v127, v127, 1.0
	v_max_f32_e32 v206, 0xda24260, v206
	v_max_f32_e32 v207, 0xda24260, v207
	v_max_f32_e32 v208, 0xda24260, v208
	v_max_f32_e32 v209, 0xda24260, v209
	v_max_f32_e32 v210, 0xda24260, v210
	v_max_f32_e32 v211, 0xda24260, v211
	v_max_f32_e32 v212, 0xda24260, v212
	v_max_f32_e32 v213, 0xda24260, v213
	v_mul_f32_e32 v198, v214, v206
	v_mul_f32_e32 v199, v215, v207
	v_mul_f32_e32 v200, v216, v208
	v_mul_f32_e32 v201, v217, v209
	v_mul_f32_e32 v202, v218, v210
	v_mul_f32_e32 v203, v219, v211
	v_mul_f32_e32 v204, v220, v212
	v_mul_f32_e32 v205, v221, v213
	v_mul_f32_e32 v214, v214, v198
	v_mul_f32_e32 v215, v215, v199
	v_mul_f32_e32 v216, v216, v200
	v_mul_f32_e32 v217, v217, v201
	v_mul_f32_e32 v218, v218, v202
	v_mul_f32_e32 v219, v219, v203
	v_mul_f32_e32 v220, v220, v204
	v_mul_f32_e32 v221, v221, v205
	v_rsq_f32_e32 v214, v214
	v_mul_f32_e32 v222, v108, v206
	v_rsq_f32_e32 v215, v215
	v_mul_f32_e32 v223, v109, v207
	v_rsq_f32_e32 v216, v216
	v_mul_f32_e32 v224, v110, v208
	v_rsq_f32_e32 v217, v217
	v_mul_f32_e32 v225, v111, v209
	v_rsq_f32_e32 v218, v218
	v_mul_f32_e32 v226, v142, v210
	v_rsq_f32_e32 v219, v219
	v_mul_f32_e32 v227, v143, v211
	v_rsq_f32_e32 v220, v220
	v_mul_f32_e32 v228, v144, v212
	v_rsq_f32_e32 v221, v221
	v_mul_f32_e32 v229, v145, v213
	v_mul_f32_e32 v170, v222, v214
	v_mul_f32_e32 v171, v223, v215
	v_mul_f32_e32 v172, v224, v216
	v_mul_f32_e32 v173, v225, v217
	v_mul_f32_e32 v174, v226, v218
	v_mul_f32_e32 v175, v227, v219
	v_mul_f32_e32 v176, v228, v220
	v_mul_f32_e32 v177, v229, v221
	v_mov_b32_e32 v198, v177
	v_mov_b32_e32 v199, v127
	v_fma_f32 v198, v126, v198, v176
	v_mul_f32_e32 v199, v199, v126
	v_fma_f32 v198, v125, v198, v175
	v_mul_f32_e32 v199, v199, v125
	v_fma_f32 v198, v124, v198, v174
	v_mul_f32_e32 v199, v199, v124
	v_fma_f32 v198, v123, v198, v173
	v_mul_f32_e32 v199, v199, v123
	v_fma_f32 v198, v122, v198, v172
	v_mul_f32_e32 v199, v199, v122
	v_fma_f32 v198, v121, v198, v171
	v_mul_f32_e32 v199, v199, v121
	v_fma_f32 v198, v120, v198, v170
	v_mul_f32_e32 v199, v199, v120
	ds_bpermute_b32 v164, v185, v199 offset:0
	ds_bpermute_b32 v246, v185, v198 offset:0
	ds_bpermute_b32 v165, v185, v199 offset:64
	ds_bpermute_b32 v247, v185, v198 offset:64
	ds_bpermute_b32 v166, v185, v199 offset:128
	ds_bpermute_b32 v248, v185, v198 offset:128
	ds_bpermute_b32 v167, v185, v199 offset:192
	ds_bpermute_b32 v249, v185, v198 offset:192
	s_waitcnt lgkmcnt(0)
	v_mov_b32_e32 v251, v249
	v_mov_b32_e32 v250, v167
	v_fma_f32 v251, v251, v166, v248
	v_mul_f32_e32 v250, v250, v166
	v_fma_f32 v251, v251, v165, v247
	v_mul_f32_e32 v250, v250, v165
	v_fma_f32 v251, v251, v164, v246
	v_mul_f32_e32 v250, v250, v164
	s_mov_b64 exec, s[10:11]
	ds_write_b64 v182, v[250:251] offset:1024
	s_mov_b64 exec, -1
	s_waitcnt lgkmcnt(0)
	s_barrier
	ds_read2_b64 v[4:7], v183 offset0:128 offset1:144
	s_add_i32 s52, s4, 1
	s_sub_i32 s52, 31, s52
	s_lshl_b32 s52, s52, 12
	v_add_u32_e32 v197, s52, v184
	s_waitcnt lgkmcnt(0)
	v_fma_f32 v198, v180, v6, v7
	v_cndmask_b32_e64 v199, v180, v198, s[24:25]
	v_fma_f32 v180, v198, v4, v5
	v_fma_f32 v200, v199, v167, v249
	v_cndmask_b32_e64 v199, v199, v200, s[16:17]
	v_fma_f32 v200, v199, v166, v248
	v_cndmask_b32_e64 v199, v199, v200, s[20:21]
	v_fma_f32 v200, v199, v165, v247
	v_cndmask_b32_e64 v199, v199, v200, s[22:23]
	v_fma_f32 v221, v127, v199, v177
	v_fma_f32 v220, v126, v221, v176
	v_fma_f32 v219, v125, v220, v175
	v_fma_f32 v218, v124, v219, v174
	v_fma_f32 v217, v123, v218, v173
	v_fma_f32 v216, v122, v217, v172
	v_fma_f32 v215, v121, v216, v171
	v_fma_f32 v214, v120, v215, v170
	v_cvt_pk_bf16_f32 v206, v214, v215
	v_cvt_pk_bf16_f32 v208, v216, v217
	v_cvt_pk_bf16_f32 v210, v218, v219
	v_cvt_pk_bf16_f32 v212, v220, v221
	ds_write_b16 v197, v206 offset:0
	ds_write_b16_d16_hi v197, v206 offset:64
	ds_write_b16 v197, v208 offset:128
	ds_write_b16_d16_hi v197, v208 offset:192
	ds_write_b16 v197, v210 offset:256
	ds_write_b16_d16_hi v197, v210 offset:320
	ds_write_b16 v197, v212 offset:384
	ds_write_b16_d16_hi v197, v212 offset:448
	s_add_i32 s4, s4, 2
	s_cmp_lt_u32 s4, 16
	s_cbranch_scc1 .Lrec2_loopA_d1
	ds_read_b128 v[198:201], v130 offset:0
	ds_read_b128 v[214:217], v130 offset:576
	ds_read_b128 v[202:205], v131 offset:0
	ds_read_b128 v[218:221], v131 offset:576
	ds_read_b128 v[206:209], v130 offset:144
	ds_read_b128 v[222:225], v130 offset:720
	ds_read_b128 v[210:213], v131 offset:144
	s_waitcnt lgkmcnt(14)
	ds_read_b128 v[226:229], v131 offset:720
	s_waitcnt lgkmcnt(6)
	v_mfma_f32_16x16x32_bf16 v[100:103], v[198:201], v[20:23], v[12:15]
	v_mfma_f32_16x16x32_bf16 v[112:115], v[214:217], v[20:23], v[12:15]
	v_mfma_f32_16x16x32_bf16 v[138:141], v[214:217], v[52:55], v[16:19]
	v_mfma_f32_16x16x32_bf16 v[104:107], v[198:201], v[52:55], v[16:19]
	v_mfma_f32_16x16x32_bf16 v[108:111], v[198:201], v[84:87], v[242:245]
	v_mfma_f32_16x16x32_bf16 v[142:145], v[214:217], v[84:87], v[242:245]
	s_waitcnt lgkmcnt(4)
	v_mfma_f32_16x16x32_bf16 v[100:103], v[202:205], v[24:27], v[100:103]
	v_mfma_f32_16x16x32_bf16 v[112:115], v[218:221], v[24:27], v[112:115]
	v_mfma_f32_16x16x32_bf16 v[138:141], v[218:221], v[56:59], v[138:141]
	v_mfma_f32_16x16x32_bf16 v[104:107], v[202:205], v[56:59], v[104:107]
	ds_read_b128 v[198:201], v130 offset:288
	ds_read_b128 v[214:217], v130 offset:864
	ds_read_b128 v[202:205], v131 offset:288
	ds_read_b128 v[218:221], v131 offset:864
	s_waitcnt lgkmcnt(6)
	v_mfma_f32_16x16x32_bf16 v[100:103], v[206:209], v[28:31], v[100:103]
	v_mfma_f32_16x16x32_bf16 v[112:115], v[222:225], v[28:31], v[112:115]
	v_mfma_f32_16x16x32_bf16 v[138:141], v[222:225], v[60:63], v[138:141]
	v_mfma_f32_16x16x32_bf16 v[104:107], v[206:209], v[60:63], v[104:107]
	v_mfma_f32_16x16x32_bf16 v[108:111], v[206:209], v[88:91], v[108:111]
	v_mfma_f32_16x16x32_bf16 v[142:145], v[222:225], v[88:91], v[142:145]
	s_waitcnt lgkmcnt(4)
	v_mfma_f32_16x16x32_bf16 v[100:103], v[210:213], v[32:35], v[100:103]
	v_mfma_f32_16x16x32_bf16 v[112:115], v[226:229], v[32:35], v[112:115]
	v_mfma_f32_16x16x32_bf16 v[138:141], v[226:229], v[64:67], v[138:141]
	v_mfma_f32_16x16x32_bf16 v[104:107], v[210:213], v[64:67], v[104:107]
	ds_read_b128 v[206:209], v130 offset:432
	ds_read_b128 v[222:225], v130 offset:1008
	ds_read_b128 v[210:213], v131 offset:432
	ds_read_b128 v[226:229], v131 offset:1008
	s_waitcnt lgkmcnt(6)
	v_mfma_f32_16x16x32_bf16 v[100:103], v[198:201], v[36:39], v[100:103]
	v_mfma_f32_16x16x32_bf16 v[112:115], v[214:217], v[36:39], v[112:115]
	v_mfma_f32_16x16x32_bf16 v[138:141], v[214:217], v[68:71], v[138:141]
	v_mfma_f32_16x16x32_bf16 v[104:107], v[198:201], v[68:71], v[104:107]
	v_mfma_f32_16x16x32_bf16 v[108:111], v[198:201], v[92:95], v[108:111]
	v_mfma_f32_16x16x32_bf16 v[142:145], v[214:217], v[92:95], v[142:145]
	s_waitcnt lgkmcnt(4)
	v_mfma_f32_16x16x32_bf16 v[100:103], v[202:205], v[40:43], v[100:103]
	v_mfma_f32_16x16x32_bf16 v[112:115], v[218:221], v[40:43], v[112:115]
	v_mfma_f32_16x16x32_bf16 v[138:141], v[218:221], v[72:75], v[138:141]
	v_mfma_f32_16x16x32_bf16 v[104:107], v[202:205], v[72:75], v[104:107]
	s_waitcnt lgkmcnt(2)
	v_mfma_f32_16x16x32_bf16 v[100:103], v[206:209], v[44:47], v[100:103]
	v_mfma_f32_16x16x32_bf16 v[112:115], v[222:225], v[44:47], v[112:115]
	v_mfma_f32_16x16x32_bf16 v[138:141], v[222:225], v[76:79], v[138:141]
	v_mfma_f32_16x16x32_bf16 v[104:107], v[206:209], v[76:79], v[104:107]
	v_mfma_f32_16x16x32_bf16 v[108:111], v[206:209], v[96:99], v[108:111]
	v_mfma_f32_16x16x32_bf16 v[142:145], v[222:225], v[96:99], v[142:145]
	s_waitcnt lgkmcnt(0)
	v_mfma_f32_16x16x32_bf16 v[100:103], v[210:213], v[48:51], v[100:103]
	v_mfma_f32_16x16x32_bf16 v[112:115], v[226:229], v[48:51], v[112:115]
	v_mfma_f32_16x16x32_bf16 v[138:141], v[226:229], v[80:83], v[138:141]
	v_mfma_f32_16x16x32_bf16 v[104:107], v[210:213], v[80:83], v[104:107]
	s_waitcnt lgkmcnt(0)
	s_barrier
	s_waitcnt vmcnt(3)
	ds_write_b128 v134, v[146:149]
	ds_write_b128 v134, v[150:153] offset:4608
	ds_write_b128 v135, v[160:163]
	s_add_i32 s64, s4, 0
	s_sub_i32 s64, 31, s64
	s_mul_i32 s71, s64, 0x30000
	s_add_u32 s38, s60, s71
	s_addc_u32 s39, s61, 0
	s_lshl_b32 s64, s64, 12
	global_load_dwordx4 v[8:11], v255, s[38:39]
	s_add_i32 s52, s4, 3
	s_min_u32 s52, s52, 31
	s_sub_i32 s52, 31, s52
	s_lshl_b32 s52, s52, 13
	s_add_u32 s26, s50, s52
	s_addc_u32 s27, s51, 0
	global_load_dwordx4 v[146:149], v154, s[26:27]
	global_load_dwordx4 v[150:153], v155, s[26:27]
	global_load_dwordx4 v[160:163], v159, s[26:27]
	v_exp_f32_e32 v198, v100
	v_exp_f32_e32 v199, v101
	v_exp_f32_e32 v200, v102
	v_exp_f32_e32 v201, v103
	v_exp_f32_e32 v202, v112
	v_exp_f32_e32 v203, v113
	v_exp_f32_e32 v204, v114
	v_exp_f32_e32 v205, v115
	v_exp_f32_e32 v214, v104
	v_add_f32_e32 v198, 1.0, v198
	v_exp_f32_e32 v215, v105
	v_add_f32_e32 v199, 1.0, v199
	v_exp_f32_e32 v216, v106
	v_add_f32_e32 v200, 1.0, v200
	v_exp_f32_e32 v217, v107
	v_add_f32_e32 v201, 1.0, v201
	v_exp_f32_e32 v218, v138
	v_add_f32_e32 v202, 1.0, v202
	v_exp_f32_e32 v219, v139
	v_add_f32_e32 v203, 1.0, v203
	v_exp_f32_e32 v220, v140
	v_add_f32_e32 v204, 1.0, v204
	v_exp_f32_e32 v221, v141
	v_add_f32_e32 v205, 1.0, v205
	v_rcp_f32_e32 v198, v198
	v_add_f32_e32 v214, 1.0, v214
	v_rcp_f32_e32 v199, v199
	v_add_f32_e32 v215, 1.0, v215
	v_rcp_f32_e32 v200, v200
	v_add_f32_e32 v216, 1.0, v216
	v_rcp_f32_e32 v201, v201
	v_add_f32_e32 v217, 1.0, v217
	v_rcp_f32_e32 v202, v202
	v_add_f32_e32 v218, 1.0, v218
	v_rcp_f32_e32 v203, v203
	v_add_f32_e32 v219, 1.0, v219
	v_rcp_f32_e32 v204, v204
	v_add_f32_e32 v220, 1.0, v220
	v_rcp_f32_e32 v205, v205
	v_add_f32_e32 v221, 1.0, v221
	v_mul_f32_e32 v198, v179, v198
	v_mul_f32_e32 v199, v179, v199
	v_mul_f32_e32 v200, v179, v200
	v_mul_f32_e32 v201, v179, v201
	v_mul_f32_e32 v202, v179, v202
	v_mul_f32_e32 v203, v179, v203
	v_mul_f32_e32 v204, v179, v204
	v_mul_f32_e32 v205, v179, v205
	v_exp_f32_e32 v120, v198
	v_exp_f32_e32 v121, v199
	v_exp_f32_e32 v122, v200
	v_exp_f32_e32 v123, v201
	v_exp_f32_e32 v124, v202
	v_exp_f32_e32 v125, v203
	v_exp_f32_e32 v126, v204
	v_exp_f32_e32 v127, v205
	v_fma_f32 v206, -v120, v120, 1.0
	v_fma_f32 v207, -v121, v121, 1.0
	v_fma_f32 v208, -v122, v122, 1.0
	v_fma_f32 v209, -v123, v123, 1.0
	v_fma_f32 v210, -v124, v124, 1.0
	v_fma_f32 v211, -v125, v125, 1.0
	v_fma_f32 v212, -v126, v126, 1.0
	v_fma_f32 v213, -v127, v127, 1.0
	v_max_f32_e32 v206, 0xda24260, v206
	v_max_f32_e32 v207, 0xda24260, v207
	v_max_f32_e32 v208, 0xda24260, v208
	v_max_f32_e32 v209, 0xda24260, v209
	v_max_f32_e32 v210, 0xda24260, v210
	v_max_f32_e32 v211, 0xda24260, v211
	v_max_f32_e32 v212, 0xda24260, v212
	v_max_f32_e32 v213, 0xda24260, v213
	v_mul_f32_e32 v198, v214, v206
	v_mul_f32_e32 v199, v215, v207
	v_mul_f32_e32 v200, v216, v208
	v_mul_f32_e32 v201, v217, v209
	v_mul_f32_e32 v202, v218, v210
	v_mul_f32_e32 v203, v219, v211
	v_mul_f32_e32 v204, v220, v212
	v_mul_f32_e32 v205, v221, v213
	v_mul_f32_e32 v214, v214, v198
	v_mul_f32_e32 v215, v215, v199
	v_mul_f32_e32 v216, v216, v200
	v_mul_f32_e32 v217, v217, v201
	v_mul_f32_e32 v218, v218, v202
	v_mul_f32_e32 v219, v219, v203
	v_mul_f32_e32 v220, v220, v204
	v_mul_f32_e32 v221, v221, v205
	v_rsq_f32_e32 v214, v214
	v_mul_f32_e32 v222, v108, v206
	v_rsq_f32_e32 v215, v215
	v_mul_f32_e32 v223, v109, v207
	v_rsq_f32_e32 v216, v216
	v_mul_f32_e32 v224, v110, v208
	v_rsq_f32_e32 v217, v217
	v_mul_f32_e32 v225, v111, v209
	v_rsq_f32_e32 v218, v218
	v_mul_f32_e32 v226, v142, v210
	v_rsq_f32_e32 v219, v219
	v_mul_f32_e32 v227, v143, v211
	v_rsq_f32_e32 v220, v220
	v_mul_f32_e32 v228, v144, v212
	v_rsq_f32_e32 v221, v221
	v_mul_f32_e32 v229, v145, v213
	v_mul_f32_e32 v170, v222, v214
	v_mul_f32_e32 v171, v223, v215
	v_mul_f32_e32 v172, v224, v216
	v_mul_f32_e32 v173, v225, v217
	v_mul_f32_e32 v174, v226, v218
	v_mul_f32_e32 v175, v227, v219
	v_mul_f32_e32 v176, v228, v220
	v_mul_f32_e32 v177, v229, v221
	v_mov_b32_e32 v198, v177
	v_mov_b32_e32 v199, v127
	v_fma_f32 v198, v126, v198, v176
	v_mul_f32_e32 v199, v199, v126
	v_fma_f32 v198, v125, v198, v175
	v_mul_f32_e32 v199, v199, v125
	v_fma_f32 v198, v124, v198, v174
	v_mul_f32_e32 v199, v199, v124
	v_fma_f32 v198, v123, v198, v173
	v_mul_f32_e32 v199, v199, v123
	v_fma_f32 v198, v122, v198, v172
	v_mul_f32_e32 v199, v199, v122
	v_fma_f32 v198, v121, v198, v171
	v_mul_f32_e32 v199, v199, v121
	v_fma_f32 v198, v120, v198, v170
	v_mul_f32_e32 v199, v199, v120
	ds_bpermute_b32 v164, v185, v199 offset:0
	ds_bpermute_b32 v246, v185, v198 offset:0
	ds_bpermute_b32 v165, v185, v199 offset:64
	ds_bpermute_b32 v247, v185, v198 offset:64
	ds_bpermute_b32 v166, v185, v199 offset:128
	ds_bpermute_b32 v248, v185, v198 offset:128
	ds_bpermute_b32 v167, v185, v199 offset:192
	ds_bpermute_b32 v249, v185, v198 offset:192
	s_waitcnt lgkmcnt(0)
	v_mov_b32_e32 v251, v249
	v_mov_b32_e32 v250, v167
	v_fma_f32 v251, v251, v166, v248
	v_mul_f32_e32 v250, v250, v166
	v_fma_f32 v251, v251, v165, v247
	v_mul_f32_e32 v250, v250, v165
	v_fma_f32 v251, v251, v164, v246
	v_mul_f32_e32 v250, v250, v164
	s_mov_b64 exec, s[10:11]
	ds_write_b64 v182, v[250:251] offset:0
	s_mov_b64 exec, -1
	s_waitcnt lgkmcnt(0)
	s_barrier
	ds_read2_b64 v[4:7], v183 offset0:0 offset1:16
	s_add_i32 s52, s4, 0
	s_sub_i32 s52, 31, s52
	s_lshl_b32 s52, s52, 12
	v_add_u32_e32 v197, s52, v184
	s_waitcnt lgkmcnt(0)
	v_fma_f32 v198, v180, v6, v7
	v_cndmask_b32_e64 v199, v180, v198, s[24:25]
	v_fma_f32 v180, v198, v4, v5
	v_fma_f32 v200, v199, v167, v249
	v_cndmask_b32_e64 v199, v199, v200, s[16:17]
	v_fma_f32 v200, v199, v166, v248
	v_cndmask_b32_e64 v199, v199, v200, s[20:21]
	v_fma_f32 v200, v199, v165, v247
	v_cndmask_b32_e64 v199, v199, v200, s[22:23]
	v_fma_f32 v221, v127, v199, v177
	v_fma_f32 v220, v126, v221, v176
	v_fma_f32 v219, v125, v220, v175
	v_fma_f32 v218, v124, v219, v174
	v_fma_f32 v217, v123, v218, v173
	v_fma_f32 v216, v122, v217, v172
	v_fma_f32 v215, v121, v216, v171
	v_fma_f32 v214, v120, v215, v170
	ds_read_u16 v206, v197 offset:0
	ds_read_u16 v207, v197 offset:64
	ds_read_u16 v208, v197 offset:128
	ds_read_u16 v209, v197 offset:192
	ds_read_u16 v210, v197 offset:256
	ds_read_u16 v211, v197 offset:320
	ds_read_u16 v212, v197 offset:384
	ds_read_u16 v213, v197 offset:448
	s_waitcnt lgkmcnt(0)
	v_lshlrev_b32_e32 v206, 16, v206
	v_lshlrev_b32_e32 v207, 16, v207
	v_lshlrev_b32_e32 v208, 16, v208
	v_lshlrev_b32_e32 v209, 16, v209
	v_lshlrev_b32_e32 v210, 16, v210
	v_lshlrev_b32_e32 v211, 16, v211
	v_lshlrev_b32_e32 v212, 16, v212
	v_lshlrev_b32_e32 v213, 16, v213
	v_add_f32_e32 v214, v214, v206
	v_add_f32_e32 v215, v215, v207
	v_add_f32_e32 v216, v216, v208
	v_add_f32_e32 v217, v217, v209
	v_add_f32_e32 v218, v218, v210
	v_add_f32_e32 v219, v219, v211
	v_add_f32_e32 v220, v220, v212
	v_add_f32_e32 v221, v221, v213
	v_cvt_pk_bf16_f32 v206, v214, v215
	v_cvt_pk_bf16_f32 v208, v216, v217
	v_cvt_pk_bf16_f32 v210, v218, v219
	v_cvt_pk_bf16_f32 v212, v220, v221
	ds_write_b16 v197, v206 offset:0
	ds_write_b16_d16_hi v197, v206 offset:64
	ds_write_b16 v197, v208 offset:128
	ds_write_b16_d16_hi v197, v208 offset:192
	ds_write_b16 v197, v210 offset:256
	ds_write_b16_d16_hi v197, v210 offset:320
	ds_write_b16 v197, v212 offset:384
	ds_write_b16_d16_hi v197, v212 offset:448
	ds_read_b128 v[198:201], v130 offset:0
	ds_read_b128 v[214:217], v130 offset:576
	ds_read_b128 v[202:205], v131 offset:0
	ds_read_b128 v[218:221], v131 offset:576
	ds_read_b128 v[206:209], v130 offset:144
	ds_read_b128 v[222:225], v130 offset:720
	ds_read_b128 v[210:213], v131 offset:144
	s_waitcnt lgkmcnt(14)
	ds_read_b128 v[226:229], v131 offset:720
	s_waitcnt lgkmcnt(6)
	v_mfma_f32_16x16x32_bf16 v[100:103], v[198:201], v[20:23], v[12:15]
	v_mfma_f32_16x16x32_bf16 v[112:115], v[214:217], v[20:23], v[12:15]
	v_mfma_f32_16x16x32_bf16 v[138:141], v[214:217], v[52:55], v[16:19]
	v_mfma_f32_16x16x32_bf16 v[104:107], v[198:201], v[52:55], v[16:19]
	v_mfma_f32_16x16x32_bf16 v[108:111], v[198:201], v[84:87], v[242:245]
	v_mfma_f32_16x16x32_bf16 v[142:145], v[214:217], v[84:87], v[242:245]
	s_waitcnt lgkmcnt(4)
	v_mfma_f32_16x16x32_bf16 v[100:103], v[202:205], v[24:27], v[100:103]
	v_mfma_f32_16x16x32_bf16 v[112:115], v[218:221], v[24:27], v[112:115]
	v_mfma_f32_16x16x32_bf16 v[138:141], v[218:221], v[56:59], v[138:141]
	v_mfma_f32_16x16x32_bf16 v[104:107], v[202:205], v[56:59], v[104:107]
	ds_read_b128 v[198:201], v130 offset:288
	ds_read_b128 v[214:217], v130 offset:864
	ds_read_b128 v[202:205], v131 offset:288
	ds_read_b128 v[218:221], v131 offset:864
	s_waitcnt lgkmcnt(6)
	v_mfma_f32_16x16x32_bf16 v[100:103], v[206:209], v[28:31], v[100:103]
	v_mfma_f32_16x16x32_bf16 v[112:115], v[222:225], v[28:31], v[112:115]
	v_mfma_f32_16x16x32_bf16 v[138:141], v[222:225], v[60:63], v[138:141]
	v_mfma_f32_16x16x32_bf16 v[104:107], v[206:209], v[60:63], v[104:107]
	v_mfma_f32_16x16x32_bf16 v[108:111], v[206:209], v[88:91], v[108:111]
	v_mfma_f32_16x16x32_bf16 v[142:145], v[222:225], v[88:91], v[142:145]
	s_waitcnt lgkmcnt(4)
	v_mfma_f32_16x16x32_bf16 v[100:103], v[210:213], v[32:35], v[100:103]
	v_mfma_f32_16x16x32_bf16 v[112:115], v[226:229], v[32:35], v[112:115]
	v_mfma_f32_16x16x32_bf16 v[138:141], v[226:229], v[64:67], v[138:141]
	v_mfma_f32_16x16x32_bf16 v[104:107], v[210:213], v[64:67], v[104:107]
	ds_read_b128 v[206:209], v130 offset:432
	ds_read_b128 v[222:225], v130 offset:1008
	ds_read_b128 v[210:213], v131 offset:432
	ds_read_b128 v[226:229], v131 offset:1008
	s_waitcnt lgkmcnt(6)
	v_mfma_f32_16x16x32_bf16 v[100:103], v[198:201], v[36:39], v[100:103]
	v_mfma_f32_16x16x32_bf16 v[112:115], v[214:217], v[36:39], v[112:115]
	v_mfma_f32_16x16x32_bf16 v[138:141], v[214:217], v[68:71], v[138:141]
	v_mfma_f32_16x16x32_bf16 v[104:107], v[198:201], v[68:71], v[104:107]
	v_mfma_f32_16x16x32_bf16 v[108:111], v[198:201], v[92:95], v[108:111]
	v_mfma_f32_16x16x32_bf16 v[142:145], v[214:217], v[92:95], v[142:145]
	s_waitcnt lgkmcnt(4)
	v_mfma_f32_16x16x32_bf16 v[100:103], v[202:205], v[40:43], v[100:103]
	v_mfma_f32_16x16x32_bf16 v[112:115], v[218:221], v[40:43], v[112:115]
	v_mfma_f32_16x16x32_bf16 v[138:141], v[218:221], v[72:75], v[138:141]
	v_mfma_f32_16x16x32_bf16 v[104:107], v[202:205], v[72:75], v[104:107]
	s_waitcnt lgkmcnt(2)
	v_mfma_f32_16x16x32_bf16 v[100:103], v[206:209], v[44:47], v[100:103]
	v_mfma_f32_16x16x32_bf16 v[112:115], v[222:225], v[44:47], v[112:115]
	v_mfma_f32_16x16x32_bf16 v[138:141], v[222:225], v[76:79], v[138:141]
	v_mfma_f32_16x16x32_bf16 v[104:107], v[206:209], v[76:79], v[104:107]
	v_mfma_f32_16x16x32_bf16 v[108:111], v[206:209], v[96:99], v[108:111]
	v_mfma_f32_16x16x32_bf16 v[142:145], v[222:225], v[96:99], v[142:145]
	s_waitcnt lgkmcnt(0)
	v_mfma_f32_16x16x32_bf16 v[100:103], v[210:213], v[48:51], v[100:103]
	v_mfma_f32_16x16x32_bf16 v[112:115], v[226:229], v[48:51], v[112:115]
	v_mfma_f32_16x16x32_bf16 v[138:141], v[226:229], v[80:83], v[138:141]
	v_mfma_f32_16x16x32_bf16 v[104:107], v[210:213], v[80:83], v[104:107]
	s_waitcnt lgkmcnt(0)
	s_barrier
	s_waitcnt vmcnt(4)
	ds_write_b128 v134, v[230:233]
	ds_write_b128 v134, v[234:237] offset:4608
	ds_write_b128 v135, v[238:241]
	s_add_i32 s64, s4, 0
	s_sub_i32 s64, 31, s64
	s_mul_i32 s71, s64, 0x30000
	s_add_u32 s38, s60, s71
	s_addc_u32 s39, s61, 0
	s_lshl_b32 s64, s64, 12
	v_add_u32_e32 v136, s64, v195
	ds_read_b128 v[116:119], v136
	s_waitcnt vmcnt(3)
	s_waitcnt lgkmcnt(0)
	v_lshlrev_b32_e32 v136, 16, v116
	v_lshlrev_b32_e32 v137, 16, v8
	v_and_b32_e32 v168, 0xffff0000, v116
	v_and_b32_e32 v169, 0xffff0000, v8
	v_mul_f32_e32 v136, v136, v137
	v_mul_f32_e32 v168, v168, v169
	v_cvt_pk_bf16_f32 v116, v136, v168
	v_lshlrev_b32_e32 v136, 16, v117
	v_lshlrev_b32_e32 v137, 16, v9
	v_and_b32_e32 v168, 0xffff0000, v117
	v_and_b32_e32 v169, 0xffff0000, v9
	v_mul_f32_e32 v136, v136, v137
	v_mul_f32_e32 v168, v168, v169
	v_cvt_pk_bf16_f32 v117, v136, v168
	v_lshlrev_b32_e32 v136, 16, v118
	v_lshlrev_b32_e32 v137, 16, v10
	v_and_b32_e32 v168, 0xffff0000, v118
	v_and_b32_e32 v169, 0xffff0000, v10
	v_mul_f32_e32 v136, v136, v137
	v_mul_f32_e32 v168, v168, v169
	v_cvt_pk_bf16_f32 v118, v136, v168
	v_lshlrev_b32_e32 v136, 16, v119
	v_lshlrev_b32_e32 v137, 16, v11
	v_and_b32_e32 v168, 0xffff0000, v119
	v_and_b32_e32 v169, 0xffff0000, v11
	v_mul_f32_e32 v136, v136, v137
	v_mul_f32_e32 v168, v168, v169
	v_cvt_pk_bf16_f32 v119, v136, v168
	global_store_dwordx4 v255, v[116:119], s[38:39]
	s_add_i32 s64, s4, 1
	s_sub_i32 s64, 31, s64
	s_mul_i32 s71, s64, 0x30000
	s_add_u32 s38, s60, s71
	s_addc_u32 s39, s61, 0
	s_lshl_b32 s64, s64, 12
	global_load_dwordx4 v[8:11], v255, s[38:39]
	s_add_i32 s52, s4, 4
	s_min_u32 s52, s52, 31
	s_sub_i32 s52, 31, s52
	s_lshl_b32 s52, s52, 13
	s_add_u32 s26, s50, s52
	s_addc_u32 s27, s51, 0
	global_load_dwordx4 v[230:233], v154, s[26:27]
	global_load_dwordx4 v[234:237], v155, s[26:27]
	global_load_dwordx4 v[238:241], v159, s[26:27]
	v_exp_f32_e32 v198, v100
	v_exp_f32_e32 v199, v101
	v_exp_f32_e32 v200, v102
	v_exp_f32_e32 v201, v103
	v_exp_f32_e32 v202, v112
	v_exp_f32_e32 v203, v113
	v_exp_f32_e32 v204, v114
	v_exp_f32_e32 v205, v115
	v_exp_f32_e32 v214, v104
	v_add_f32_e32 v198, 1.0, v198
	v_exp_f32_e32 v215, v105
	v_add_f32_e32 v199, 1.0, v199
	v_exp_f32_e32 v216, v106
	v_add_f32_e32 v200, 1.0, v200
	v_exp_f32_e32 v217, v107
	v_add_f32_e32 v201, 1.0, v201
	v_exp_f32_e32 v218, v138
	v_add_f32_e32 v202, 1.0, v202
	v_exp_f32_e32 v219, v139
	v_add_f32_e32 v203, 1.0, v203
	v_exp_f32_e32 v220, v140
	v_add_f32_e32 v204, 1.0, v204
	v_exp_f32_e32 v221, v141
	v_add_f32_e32 v205, 1.0, v205
	v_rcp_f32_e32 v198, v198
	v_add_f32_e32 v214, 1.0, v214
	v_rcp_f32_e32 v199, v199
	v_add_f32_e32 v215, 1.0, v215
	v_rcp_f32_e32 v200, v200
	v_add_f32_e32 v216, 1.0, v216
	v_rcp_f32_e32 v201, v201
	v_add_f32_e32 v217, 1.0, v217
	v_rcp_f32_e32 v202, v202
	v_add_f32_e32 v218, 1.0, v218
	v_rcp_f32_e32 v203, v203
	v_add_f32_e32 v219, 1.0, v219
	v_rcp_f32_e32 v204, v204
	v_add_f32_e32 v220, 1.0, v220
	v_rcp_f32_e32 v205, v205
	v_add_f32_e32 v221, 1.0, v221
	v_mul_f32_e32 v198, v179, v198
	v_mul_f32_e32 v199, v179, v199
	v_mul_f32_e32 v200, v179, v200
	v_mul_f32_e32 v201, v179, v201
	v_mul_f32_e32 v202, v179, v202
	v_mul_f32_e32 v203, v179, v203
	v_mul_f32_e32 v204, v179, v204
	v_mul_f32_e32 v205, v179, v205
	v_exp_f32_e32 v120, v198
	v_exp_f32_e32 v121, v199
	v_exp_f32_e32 v122, v200
	v_exp_f32_e32 v123, v201
	v_exp_f32_e32 v124, v202
	v_exp_f32_e32 v125, v203
	v_exp_f32_e32 v126, v204
	v_exp_f32_e32 v127, v205
	v_fma_f32 v206, -v120, v120, 1.0
	v_fma_f32 v207, -v121, v121, 1.0
	v_fma_f32 v208, -v122, v122, 1.0
	v_fma_f32 v209, -v123, v123, 1.0
	v_fma_f32 v210, -v124, v124, 1.0
	v_fma_f32 v211, -v125, v125, 1.0
	v_fma_f32 v212, -v126, v126, 1.0
	v_fma_f32 v213, -v127, v127, 1.0
	v_max_f32_e32 v206, 0xda24260, v206
	v_max_f32_e32 v207, 0xda24260, v207
	v_max_f32_e32 v208, 0xda24260, v208
	v_max_f32_e32 v209, 0xda24260, v209
	v_max_f32_e32 v210, 0xda24260, v210
	v_max_f32_e32 v211, 0xda24260, v211
	v_max_f32_e32 v212, 0xda24260, v212
	v_max_f32_e32 v213, 0xda24260, v213
	v_mul_f32_e32 v198, v214, v206
	v_mul_f32_e32 v199, v215, v207
	v_mul_f32_e32 v200, v216, v208
	v_mul_f32_e32 v201, v217, v209
	v_mul_f32_e32 v202, v218, v210
	v_mul_f32_e32 v203, v219, v211
	v_mul_f32_e32 v204, v220, v212
	v_mul_f32_e32 v205, v221, v213
	v_mul_f32_e32 v214, v214, v198
	v_mul_f32_e32 v215, v215, v199
	v_mul_f32_e32 v216, v216, v200
	v_mul_f32_e32 v217, v217, v201
	v_mul_f32_e32 v218, v218, v202
	v_mul_f32_e32 v219, v219, v203
	v_mul_f32_e32 v220, v220, v204
	v_mul_f32_e32 v221, v221, v205
	v_rsq_f32_e32 v214, v214
	v_mul_f32_e32 v222, v108, v206
	v_rsq_f32_e32 v215, v215
	v_mul_f32_e32 v223, v109, v207
	v_rsq_f32_e32 v216, v216
	v_mul_f32_e32 v224, v110, v208
	v_rsq_f32_e32 v217, v217
	v_mul_f32_e32 v225, v111, v209
	v_rsq_f32_e32 v218, v218
	v_mul_f32_e32 v226, v142, v210
	v_rsq_f32_e32 v219, v219
	v_mul_f32_e32 v227, v143, v211
	v_rsq_f32_e32 v220, v220
	v_mul_f32_e32 v228, v144, v212
	v_rsq_f32_e32 v221, v221
	v_mul_f32_e32 v229, v145, v213
	v_mul_f32_e32 v170, v222, v214
	v_mul_f32_e32 v171, v223, v215
	v_mul_f32_e32 v172, v224, v216
	v_mul_f32_e32 v173, v225, v217
	v_mul_f32_e32 v174, v226, v218
	v_mul_f32_e32 v175, v227, v219
	v_mul_f32_e32 v176, v228, v220
	v_mul_f32_e32 v177, v229, v221
	v_mov_b32_e32 v198, v177
	v_mov_b32_e32 v199, v127
	v_fma_f32 v198, v126, v198, v176
	v_mul_f32_e32 v199, v199, v126
	v_fma_f32 v198, v125, v198, v175
	v_mul_f32_e32 v199, v199, v125
	v_fma_f32 v198, v124, v198, v174
	v_mul_f32_e32 v199, v199, v124
	v_fma_f32 v198, v123, v198, v173
	v_mul_f32_e32 v199, v199, v123
	v_fma_f32 v198, v122, v198, v172
	v_mul_f32_e32 v199, v199, v122
	v_fma_f32 v198, v121, v198, v171
	v_mul_f32_e32 v199, v199, v121
	v_fma_f32 v198, v120, v198, v170
	v_mul_f32_e32 v199, v199, v120
	ds_bpermute_b32 v164, v185, v199 offset:0
	ds_bpermute_b32 v246, v185, v198 offset:0
	ds_bpermute_b32 v165, v185, v199 offset:64
	ds_bpermute_b32 v247, v185, v198 offset:64
	ds_bpermute_b32 v166, v185, v199 offset:128
	ds_bpermute_b32 v248, v185, v198 offset:128
	ds_bpermute_b32 v167, v185, v199 offset:192
	ds_bpermute_b32 v249, v185, v198 offset:192
	s_waitcnt lgkmcnt(0)
	v_mov_b32_e32 v251, v249
	v_mov_b32_e32 v250, v167
	v_fma_f32 v251, v251, v166, v248
	v_mul_f32_e32 v250, v250, v166
	v_fma_f32 v251, v251, v165, v247
	v_mul_f32_e32 v250, v250, v165
	v_fma_f32 v251, v251, v164, v246
	v_mul_f32_e32 v250, v250, v164
	s_mov_b64 exec, s[10:11]
	ds_write_b64 v182, v[250:251] offset:1024
	s_mov_b64 exec, -1
	s_waitcnt lgkmcnt(0)
	s_barrier
	ds_read2_b64 v[4:7], v183 offset0:128 offset1:144
	s_add_i32 s52, s4, 1
	s_sub_i32 s52, 31, s52
	s_lshl_b32 s52, s52, 12
	v_add_u32_e32 v197, s52, v184
	s_waitcnt lgkmcnt(0)
	v_fma_f32 v198, v180, v6, v7
	v_cndmask_b32_e64 v199, v180, v198, s[24:25]
	v_fma_f32 v180, v198, v4, v5
	v_fma_f32 v200, v199, v167, v249
	v_cndmask_b32_e64 v199, v199, v200, s[16:17]
	v_fma_f32 v200, v199, v166, v248
	v_cndmask_b32_e64 v199, v199, v200, s[20:21]
	v_fma_f32 v200, v199, v165, v247
	v_cndmask_b32_e64 v199, v199, v200, s[22:23]
	v_fma_f32 v221, v127, v199, v177
	v_fma_f32 v220, v126, v221, v176
	v_fma_f32 v219, v125, v220, v175
	v_fma_f32 v218, v124, v219, v174
	v_fma_f32 v217, v123, v218, v173
	v_fma_f32 v216, v122, v217, v172
	v_fma_f32 v215, v121, v216, v171
	v_fma_f32 v214, v120, v215, v170
	ds_read_u16 v206, v197 offset:0
	ds_read_u16 v207, v197 offset:64
	ds_read_u16 v208, v197 offset:128
	ds_read_u16 v209, v197 offset:192
	ds_read_u16 v210, v197 offset:256
	ds_read_u16 v211, v197 offset:320
	ds_read_u16 v212, v197 offset:384
	ds_read_u16 v213, v197 offset:448
	s_waitcnt lgkmcnt(0)
	v_lshlrev_b32_e32 v206, 16, v206
	v_lshlrev_b32_e32 v207, 16, v207
	v_lshlrev_b32_e32 v208, 16, v208
	v_lshlrev_b32_e32 v209, 16, v209
	v_lshlrev_b32_e32 v210, 16, v210
	v_lshlrev_b32_e32 v211, 16, v211
	v_lshlrev_b32_e32 v212, 16, v212
	v_lshlrev_b32_e32 v213, 16, v213
	v_add_f32_e32 v214, v214, v206
	v_add_f32_e32 v215, v215, v207
	v_add_f32_e32 v216, v216, v208
	v_add_f32_e32 v217, v217, v209
	v_add_f32_e32 v218, v218, v210
	v_add_f32_e32 v219, v219, v211
	v_add_f32_e32 v220, v220, v212
	v_add_f32_e32 v221, v221, v213
	v_cvt_pk_bf16_f32 v206, v214, v215
	v_cvt_pk_bf16_f32 v208, v216, v217
	v_cvt_pk_bf16_f32 v210, v218, v219
	v_cvt_pk_bf16_f32 v212, v220, v221
	ds_write_b16 v197, v206 offset:0
	ds_write_b16_d16_hi v197, v206 offset:64
	ds_write_b16 v197, v208 offset:128
	ds_write_b16_d16_hi v197, v208 offset:192
	ds_write_b16 v197, v210 offset:256
	ds_write_b16_d16_hi v197, v210 offset:320
	ds_write_b16 v197, v212 offset:384
	ds_write_b16_d16_hi v197, v212 offset:448
	s_add_i32 s4, s4, 2
.Lrec2_loopB_d1:
	ds_read_b128 v[198:201], v130 offset:0
	ds_read_b128 v[214:217], v130 offset:576
	ds_read_b128 v[202:205], v131 offset:0
	ds_read_b128 v[218:221], v131 offset:576
	ds_read_b128 v[206:209], v130 offset:144
	ds_read_b128 v[222:225], v130 offset:720
	ds_read_b128 v[210:213], v131 offset:144
	s_waitcnt lgkmcnt(14)
	ds_read_b128 v[226:229], v131 offset:720
	s_waitcnt lgkmcnt(6)
	v_mfma_f32_16x16x32_bf16 v[100:103], v[198:201], v[20:23], v[12:15]
	v_mfma_f32_16x16x32_bf16 v[112:115], v[214:217], v[20:23], v[12:15]
	v_mfma_f32_16x16x32_bf16 v[138:141], v[214:217], v[52:55], v[16:19]
	v_mfma_f32_16x16x32_bf16 v[104:107], v[198:201], v[52:55], v[16:19]
	v_mfma_f32_16x16x32_bf16 v[108:111], v[198:201], v[84:87], v[242:245]
	v_mfma_f32_16x16x32_bf16 v[142:145], v[214:217], v[84:87], v[242:245]
	s_waitcnt lgkmcnt(4)
	v_mfma_f32_16x16x32_bf16 v[100:103], v[202:205], v[24:27], v[100:103]
	v_mfma_f32_16x16x32_bf16 v[112:115], v[218:221], v[24:27], v[112:115]
	v_mfma_f32_16x16x32_bf16 v[138:141], v[218:221], v[56:59], v[138:141]
	v_mfma_f32_16x16x32_bf16 v[104:107], v[202:205], v[56:59], v[104:107]
	ds_read_b128 v[198:201], v130 offset:288
	ds_read_b128 v[214:217], v130 offset:864
	ds_read_b128 v[202:205], v131 offset:288
	ds_read_b128 v[218:221], v131 offset:864
	s_waitcnt lgkmcnt(6)
	v_mfma_f32_16x16x32_bf16 v[100:103], v[206:209], v[28:31], v[100:103]
	v_mfma_f32_16x16x32_bf16 v[112:115], v[222:225], v[28:31], v[112:115]
	v_mfma_f32_16x16x32_bf16 v[138:141], v[222:225], v[60:63], v[138:141]
	v_mfma_f32_16x16x32_bf16 v[104:107], v[206:209], v[60:63], v[104:107]
	v_mfma_f32_16x16x32_bf16 v[108:111], v[206:209], v[88:91], v[108:111]
	v_mfma_f32_16x16x32_bf16 v[142:145], v[222:225], v[88:91], v[142:145]
	s_waitcnt lgkmcnt(4)
	v_mfma_f32_16x16x32_bf16 v[100:103], v[210:213], v[32:35], v[100:103]
	v_mfma_f32_16x16x32_bf16 v[112:115], v[226:229], v[32:35], v[112:115]
	v_mfma_f32_16x16x32_bf16 v[138:141], v[226:229], v[64:67], v[138:141]
	v_mfma_f32_16x16x32_bf16 v[104:107], v[210:213], v[64:67], v[104:107]
	ds_read_b128 v[206:209], v130 offset:432
	ds_read_b128 v[222:225], v130 offset:1008
	ds_read_b128 v[210:213], v131 offset:432
	ds_read_b128 v[226:229], v131 offset:1008
	s_waitcnt lgkmcnt(6)
	v_mfma_f32_16x16x32_bf16 v[100:103], v[198:201], v[36:39], v[100:103]
	v_mfma_f32_16x16x32_bf16 v[112:115], v[214:217], v[36:39], v[112:115]
	v_mfma_f32_16x16x32_bf16 v[138:141], v[214:217], v[68:71], v[138:141]
	v_mfma_f32_16x16x32_bf16 v[104:107], v[198:201], v[68:71], v[104:107]
	v_mfma_f32_16x16x32_bf16 v[108:111], v[198:201], v[92:95], v[108:111]
	v_mfma_f32_16x16x32_bf16 v[142:145], v[214:217], v[92:95], v[142:145]
	s_waitcnt lgkmcnt(4)
	v_mfma_f32_16x16x32_bf16 v[100:103], v[202:205], v[40:43], v[100:103]
	v_mfma_f32_16x16x32_bf16 v[112:115], v[218:221], v[40:43], v[112:115]
	v_mfma_f32_16x16x32_bf16 v[138:141], v[218:221], v[72:75], v[138:141]
	v_mfma_f32_16x16x32_bf16 v[104:107], v[202:205], v[72:75], v[104:107]
	s_waitcnt lgkmcnt(2)
	v_mfma_f32_16x16x32_bf16 v[100:103], v[206:209], v[44:47], v[100:103]
	v_mfma_f32_16x16x32_bf16 v[112:115], v[222:225], v[44:47], v[112:115]
	v_mfma_f32_16x16x32_bf16 v[138:141], v[222:225], v[76:79], v[138:141]
	v_mfma_f32_16x16x32_bf16 v[104:107], v[206:209], v[76:79], v[104:107]
	v_mfma_f32_16x16x32_bf16 v[108:111], v[206:209], v[96:99], v[108:111]
	v_mfma_f32_16x16x32_bf16 v[142:145], v[222:225], v[96:99], v[142:145]
	s_waitcnt lgkmcnt(0)
	v_mfma_f32_16x16x32_bf16 v[100:103], v[210:213], v[48:51], v[100:103]
	v_mfma_f32_16x16x32_bf16 v[112:115], v[226:229], v[48:51], v[112:115]
	v_mfma_f32_16x16x32_bf16 v[138:141], v[226:229], v[80:83], v[138:141]
	v_mfma_f32_16x16x32_bf16 v[104:107], v[210:213], v[80:83], v[104:107]
	s_waitcnt lgkmcnt(0)
	s_barrier
	s_waitcnt vmcnt(5)
	ds_write_b128 v134, v[146:149]
	ds_write_b128 v134, v[150:153] offset:4608
	ds_write_b128 v135, v[160:163]
	s_add_i32 s64, s4, -1
	s_sub_i32 s64, 31, s64
	s_mul_i32 s71, s64, 0x30000
	s_add_u32 s38, s60, s71
	s_addc_u32 s39, s61, 0
	s_lshl_b32 s64, s64, 12
	v_add_u32_e32 v136, s64, v195
	ds_read_b128 v[116:119], v136
	s_waitcnt vmcnt(3)
	s_waitcnt lgkmcnt(0)
	v_lshlrev_b32_e32 v136, 16, v116
	v_lshlrev_b32_e32 v137, 16, v8
	v_and_b32_e32 v168, 0xffff0000, v116
	v_and_b32_e32 v169, 0xffff0000, v8
	v_mul_f32_e32 v136, v136, v137
	v_mul_f32_e32 v168, v168, v169
	v_cvt_pk_bf16_f32 v116, v136, v168
	v_lshlrev_b32_e32 v136, 16, v117
	v_lshlrev_b32_e32 v137, 16, v9
	v_and_b32_e32 v168, 0xffff0000, v117
	v_and_b32_e32 v169, 0xffff0000, v9
	v_mul_f32_e32 v136, v136, v137
	v_mul_f32_e32 v168, v168, v169
	v_cvt_pk_bf16_f32 v117, v136, v168
	v_lshlrev_b32_e32 v136, 16, v118
	v_lshlrev_b32_e32 v137, 16, v10
	v_and_b32_e32 v168, 0xffff0000, v118
	v_and_b32_e32 v169, 0xffff0000, v10
	v_mul_f32_e32 v136, v136, v137
	v_mul_f32_e32 v168, v168, v169
	v_cvt_pk_bf16_f32 v118, v136, v168
	v_lshlrev_b32_e32 v136, 16, v119
	v_lshlrev_b32_e32 v137, 16, v11
	v_and_b32_e32 v168, 0xffff0000, v119
	v_and_b32_e32 v169, 0xffff0000, v11
	v_mul_f32_e32 v136, v136, v137
	v_mul_f32_e32 v168, v168, v169
	v_cvt_pk_bf16_f32 v119, v136, v168
	global_store_dwordx4 v255, v[116:119], s[38:39]
	s_add_i32 s64, s4, 0
	s_sub_i32 s64, 31, s64
	s_mul_i32 s71, s64, 0x30000
	s_add_u32 s38, s60, s71
	s_addc_u32 s39, s61, 0
	s_lshl_b32 s64, s64, 12
	global_load_dwordx4 v[8:11], v255, s[38:39]
	s_add_i32 s52, s4, 3
	s_min_u32 s52, s52, 31
	s_sub_i32 s52, 31, s52
	s_lshl_b32 s52, s52, 13
	s_add_u32 s26, s50, s52
	s_addc_u32 s27, s51, 0
	global_load_dwordx4 v[146:149], v154, s[26:27]
	global_load_dwordx4 v[150:153], v155, s[26:27]
	global_load_dwordx4 v[160:163], v159, s[26:27]
	v_exp_f32_e32 v198, v100
	v_exp_f32_e32 v199, v101
	v_exp_f32_e32 v200, v102
	v_exp_f32_e32 v201, v103
	v_exp_f32_e32 v202, v112
	v_exp_f32_e32 v203, v113
	v_exp_f32_e32 v204, v114
	v_exp_f32_e32 v205, v115
	v_exp_f32_e32 v214, v104
	v_add_f32_e32 v198, 1.0, v198
	v_exp_f32_e32 v215, v105
	v_add_f32_e32 v199, 1.0, v199
	v_exp_f32_e32 v216, v106
	v_add_f32_e32 v200, 1.0, v200
	v_exp_f32_e32 v217, v107
	v_add_f32_e32 v201, 1.0, v201
	v_exp_f32_e32 v218, v138
	v_add_f32_e32 v202, 1.0, v202
	v_exp_f32_e32 v219, v139
	v_add_f32_e32 v203, 1.0, v203
	v_exp_f32_e32 v220, v140
	v_add_f32_e32 v204, 1.0, v204
	v_exp_f32_e32 v221, v141
	v_add_f32_e32 v205, 1.0, v205
	v_rcp_f32_e32 v198, v198
	v_add_f32_e32 v214, 1.0, v214
	v_rcp_f32_e32 v199, v199
	v_add_f32_e32 v215, 1.0, v215
	v_rcp_f32_e32 v200, v200
	v_add_f32_e32 v216, 1.0, v216
	v_rcp_f32_e32 v201, v201
	v_add_f32_e32 v217, 1.0, v217
	v_rcp_f32_e32 v202, v202
	v_add_f32_e32 v218, 1.0, v218
	v_rcp_f32_e32 v203, v203
	v_add_f32_e32 v219, 1.0, v219
	v_rcp_f32_e32 v204, v204
	v_add_f32_e32 v220, 1.0, v220
	v_rcp_f32_e32 v205, v205
	v_add_f32_e32 v221, 1.0, v221
	v_mul_f32_e32 v198, v179, v198
	v_mul_f32_e32 v199, v179, v199
	v_mul_f32_e32 v200, v179, v200
	v_mul_f32_e32 v201, v179, v201
	v_mul_f32_e32 v202, v179, v202
	v_mul_f32_e32 v203, v179, v203
	v_mul_f32_e32 v204, v179, v204
	v_mul_f32_e32 v205, v179, v205
	v_exp_f32_e32 v120, v198
	v_exp_f32_e32 v121, v199
	v_exp_f32_e32 v122, v200
	v_exp_f32_e32 v123, v201
	v_exp_f32_e32 v124, v202
	v_exp_f32_e32 v125, v203
	v_exp_f32_e32 v126, v204
	v_exp_f32_e32 v127, v205
	v_fma_f32 v206, -v120, v120, 1.0
	v_fma_f32 v207, -v121, v121, 1.0
	v_fma_f32 v208, -v122, v122, 1.0
	v_fma_f32 v209, -v123, v123, 1.0
	v_fma_f32 v210, -v124, v124, 1.0
	v_fma_f32 v211, -v125, v125, 1.0
	v_fma_f32 v212, -v126, v126, 1.0
	v_fma_f32 v213, -v127, v127, 1.0
	v_max_f32_e32 v206, 0xda24260, v206
	v_max_f32_e32 v207, 0xda24260, v207
	v_max_f32_e32 v208, 0xda24260, v208
	v_max_f32_e32 v209, 0xda24260, v209
	v_max_f32_e32 v210, 0xda24260, v210
	v_max_f32_e32 v211, 0xda24260, v211
	v_max_f32_e32 v212, 0xda24260, v212
	v_max_f32_e32 v213, 0xda24260, v213
	v_mul_f32_e32 v198, v214, v206
	v_mul_f32_e32 v199, v215, v207
	v_mul_f32_e32 v200, v216, v208
	v_mul_f32_e32 v201, v217, v209
	v_mul_f32_e32 v202, v218, v210
	v_mul_f32_e32 v203, v219, v211
	v_mul_f32_e32 v204, v220, v212
	v_mul_f32_e32 v205, v221, v213
	v_mul_f32_e32 v214, v214, v198
	v_mul_f32_e32 v215, v215, v199
	v_mul_f32_e32 v216, v216, v200
	v_mul_f32_e32 v217, v217, v201
	v_mul_f32_e32 v218, v218, v202
	v_mul_f32_e32 v219, v219, v203
	v_mul_f32_e32 v220, v220, v204
	v_mul_f32_e32 v221, v221, v205
	v_rsq_f32_e32 v214, v214
	v_mul_f32_e32 v222, v108, v206
	v_rsq_f32_e32 v215, v215
	v_mul_f32_e32 v223, v109, v207
	v_rsq_f32_e32 v216, v216
	v_mul_f32_e32 v224, v110, v208
	v_rsq_f32_e32 v217, v217
	v_mul_f32_e32 v225, v111, v209
	v_rsq_f32_e32 v218, v218
	v_mul_f32_e32 v226, v142, v210
	v_rsq_f32_e32 v219, v219
	v_mul_f32_e32 v227, v143, v211
	v_rsq_f32_e32 v220, v220
	v_mul_f32_e32 v228, v144, v212
	v_rsq_f32_e32 v221, v221
	v_mul_f32_e32 v229, v145, v213
	v_mul_f32_e32 v170, v222, v214
	v_mul_f32_e32 v171, v223, v215
	v_mul_f32_e32 v172, v224, v216
	v_mul_f32_e32 v173, v225, v217
	v_mul_f32_e32 v174, v226, v218
	v_mul_f32_e32 v175, v227, v219
	v_mul_f32_e32 v176, v228, v220
	v_mul_f32_e32 v177, v229, v221
	v_mov_b32_e32 v198, v177
	v_mov_b32_e32 v199, v127
	v_fma_f32 v198, v126, v198, v176
	v_mul_f32_e32 v199, v199, v126
	v_fma_f32 v198, v125, v198, v175
	v_mul_f32_e32 v199, v199, v125
	v_fma_f32 v198, v124, v198, v174
	v_mul_f32_e32 v199, v199, v124
	v_fma_f32 v198, v123, v198, v173
	v_mul_f32_e32 v199, v199, v123
	v_fma_f32 v198, v122, v198, v172
	v_mul_f32_e32 v199, v199, v122
	v_fma_f32 v198, v121, v198, v171
	v_mul_f32_e32 v199, v199, v121
	v_fma_f32 v198, v120, v198, v170
	v_mul_f32_e32 v199, v199, v120
	ds_bpermute_b32 v164, v185, v199 offset:0
	ds_bpermute_b32 v246, v185, v198 offset:0
	ds_bpermute_b32 v165, v185, v199 offset:64
	ds_bpermute_b32 v247, v185, v198 offset:64
	ds_bpermute_b32 v166, v185, v199 offset:128
	ds_bpermute_b32 v248, v185, v198 offset:128
	ds_bpermute_b32 v167, v185, v199 offset:192
	ds_bpermute_b32 v249, v185, v198 offset:192
	s_waitcnt lgkmcnt(0)
	v_mov_b32_e32 v251, v249
	v_mov_b32_e32 v250, v167
	v_fma_f32 v251, v251, v166, v248
	v_mul_f32_e32 v250, v250, v166
	v_fma_f32 v251, v251, v165, v247
	v_mul_f32_e32 v250, v250, v165
	v_fma_f32 v251, v251, v164, v246
	v_mul_f32_e32 v250, v250, v164
	s_mov_b64 exec, s[10:11]
	ds_write_b64 v182, v[250:251] offset:0
	s_mov_b64 exec, -1
	s_waitcnt lgkmcnt(0)
	s_barrier
	ds_read2_b64 v[4:7], v183 offset0:0 offset1:16
	s_add_i32 s52, s4, 0
	s_sub_i32 s52, 31, s52
	s_lshl_b32 s52, s52, 12
	v_add_u32_e32 v197, s52, v184
	s_waitcnt lgkmcnt(0)
	v_fma_f32 v198, v180, v6, v7
	v_cndmask_b32_e64 v199, v180, v198, s[24:25]
	v_fma_f32 v180, v198, v4, v5
	v_fma_f32 v200, v199, v167, v249
	v_cndmask_b32_e64 v199, v199, v200, s[16:17]
	v_fma_f32 v200, v199, v166, v248
	v_cndmask_b32_e64 v199, v199, v200, s[20:21]
	v_fma_f32 v200, v199, v165, v247
	v_cndmask_b32_e64 v199, v199, v200, s[22:23]
	v_fma_f32 v221, v127, v199, v177
	v_fma_f32 v220, v126, v221, v176
	v_fma_f32 v219, v125, v220, v175
	v_fma_f32 v218, v124, v219, v174
	v_fma_f32 v217, v123, v218, v173
	v_fma_f32 v216, v122, v217, v172
	v_fma_f32 v215, v121, v216, v171
	v_fma_f32 v214, v120, v215, v170
	ds_read_u16 v206, v197 offset:0
	ds_read_u16 v207, v197 offset:64
	ds_read_u16 v208, v197 offset:128
	ds_read_u16 v209, v197 offset:192
	ds_read_u16 v210, v197 offset:256
	ds_read_u16 v211, v197 offset:320
	ds_read_u16 v212, v197 offset:384
	ds_read_u16 v213, v197 offset:448
	s_waitcnt lgkmcnt(0)
	v_lshlrev_b32_e32 v206, 16, v206
	v_lshlrev_b32_e32 v207, 16, v207
	v_lshlrev_b32_e32 v208, 16, v208
	v_lshlrev_b32_e32 v209, 16, v209
	v_lshlrev_b32_e32 v210, 16, v210
	v_lshlrev_b32_e32 v211, 16, v211
	v_lshlrev_b32_e32 v212, 16, v212
	v_lshlrev_b32_e32 v213, 16, v213
	v_add_f32_e32 v214, v214, v206
	v_add_f32_e32 v215, v215, v207
	v_add_f32_e32 v216, v216, v208
	v_add_f32_e32 v217, v217, v209
	v_add_f32_e32 v218, v218, v210
	v_add_f32_e32 v219, v219, v211
	v_add_f32_e32 v220, v220, v212
	v_add_f32_e32 v221, v221, v213
	v_cvt_pk_bf16_f32 v206, v214, v215
	v_cvt_pk_bf16_f32 v208, v216, v217
	v_cvt_pk_bf16_f32 v210, v218, v219
	v_cvt_pk_bf16_f32 v212, v220, v221
	ds_write_b16 v197, v206 offset:0
	ds_write_b16_d16_hi v197, v206 offset:64
	ds_write_b16 v197, v208 offset:128
	ds_write_b16_d16_hi v197, v208 offset:192
	ds_write_b16 v197, v210 offset:256
	ds_write_b16_d16_hi v197, v210 offset:320
	ds_write_b16 v197, v212 offset:384
	ds_write_b16_d16_hi v197, v212 offset:448
	ds_read_b128 v[198:201], v130 offset:0
	ds_read_b128 v[214:217], v130 offset:576
	ds_read_b128 v[202:205], v131 offset:0
	ds_read_b128 v[218:221], v131 offset:576
	ds_read_b128 v[206:209], v130 offset:144
	ds_read_b128 v[222:225], v130 offset:720
	ds_read_b128 v[210:213], v131 offset:144
	s_waitcnt lgkmcnt(14)
	ds_read_b128 v[226:229], v131 offset:720
	s_waitcnt lgkmcnt(6)
	v_mfma_f32_16x16x32_bf16 v[100:103], v[198:201], v[20:23], v[12:15]
	v_mfma_f32_16x16x32_bf16 v[112:115], v[214:217], v[20:23], v[12:15]
	v_mfma_f32_16x16x32_bf16 v[138:141], v[214:217], v[52:55], v[16:19]
	v_mfma_f32_16x16x32_bf16 v[104:107], v[198:201], v[52:55], v[16:19]
	v_mfma_f32_16x16x32_bf16 v[108:111], v[198:201], v[84:87], v[242:245]
	v_mfma_f32_16x16x32_bf16 v[142:145], v[214:217], v[84:87], v[242:245]
	s_waitcnt lgkmcnt(4)
	v_mfma_f32_16x16x32_bf16 v[100:103], v[202:205], v[24:27], v[100:103]
	v_mfma_f32_16x16x32_bf16 v[112:115], v[218:221], v[24:27], v[112:115]
	v_mfma_f32_16x16x32_bf16 v[138:141], v[218:221], v[56:59], v[138:141]
	v_mfma_f32_16x16x32_bf16 v[104:107], v[202:205], v[56:59], v[104:107]
	ds_read_b128 v[198:201], v130 offset:288
	ds_read_b128 v[214:217], v130 offset:864
	ds_read_b128 v[202:205], v131 offset:288
	ds_read_b128 v[218:221], v131 offset:864
	s_waitcnt lgkmcnt(6)
	v_mfma_f32_16x16x32_bf16 v[100:103], v[206:209], v[28:31], v[100:103]
	v_mfma_f32_16x16x32_bf16 v[112:115], v[222:225], v[28:31], v[112:115]
	v_mfma_f32_16x16x32_bf16 v[138:141], v[222:225], v[60:63], v[138:141]
	v_mfma_f32_16x16x32_bf16 v[104:107], v[206:209], v[60:63], v[104:107]
	v_mfma_f32_16x16x32_bf16 v[108:111], v[206:209], v[88:91], v[108:111]
	v_mfma_f32_16x16x32_bf16 v[142:145], v[222:225], v[88:91], v[142:145]
	s_waitcnt lgkmcnt(4)
	v_mfma_f32_16x16x32_bf16 v[100:103], v[210:213], v[32:35], v[100:103]
	v_mfma_f32_16x16x32_bf16 v[112:115], v[226:229], v[32:35], v[112:115]
	v_mfma_f32_16x16x32_bf16 v[138:141], v[226:229], v[64:67], v[138:141]
	v_mfma_f32_16x16x32_bf16 v[104:107], v[210:213], v[64:67], v[104:107]
	ds_read_b128 v[206:209], v130 offset:432
	ds_read_b128 v[222:225], v130 offset:1008
	ds_read_b128 v[210:213], v131 offset:432
	ds_read_b128 v[226:229], v131 offset:1008
	s_waitcnt lgkmcnt(6)
	v_mfma_f32_16x16x32_bf16 v[100:103], v[198:201], v[36:39], v[100:103]
	v_mfma_f32_16x16x32_bf16 v[112:115], v[214:217], v[36:39], v[112:115]
	v_mfma_f32_16x16x32_bf16 v[138:141], v[214:217], v[68:71], v[138:141]
	v_mfma_f32_16x16x32_bf16 v[104:107], v[198:201], v[68:71], v[104:107]
	v_mfma_f32_16x16x32_bf16 v[108:111], v[198:201], v[92:95], v[108:111]
	v_mfma_f32_16x16x32_bf16 v[142:145], v[214:217], v[92:95], v[142:145]
	s_waitcnt lgkmcnt(4)
	v_mfma_f32_16x16x32_bf16 v[100:103], v[202:205], v[40:43], v[100:103]
	v_mfma_f32_16x16x32_bf16 v[112:115], v[218:221], v[40:43], v[112:115]
	v_mfma_f32_16x16x32_bf16 v[138:141], v[218:221], v[72:75], v[138:141]
	v_mfma_f32_16x16x32_bf16 v[104:107], v[202:205], v[72:75], v[104:107]
	s_waitcnt lgkmcnt(2)
	v_mfma_f32_16x16x32_bf16 v[100:103], v[206:209], v[44:47], v[100:103]
	v_mfma_f32_16x16x32_bf16 v[112:115], v[222:225], v[44:47], v[112:115]
	v_mfma_f32_16x16x32_bf16 v[138:141], v[222:225], v[76:79], v[138:141]
	v_mfma_f32_16x16x32_bf16 v[104:107], v[206:209], v[76:79], v[104:107]
	v_mfma_f32_16x16x32_bf16 v[108:111], v[206:209], v[96:99], v[108:111]
	v_mfma_f32_16x16x32_bf16 v[142:145], v[222:225], v[96:99], v[142:145]
	s_waitcnt lgkmcnt(0)
	v_mfma_f32_16x16x32_bf16 v[100:103], v[210:213], v[48:51], v[100:103]
	v_mfma_f32_16x16x32_bf16 v[112:115], v[226:229], v[48:51], v[112:115]
	v_mfma_f32_16x16x32_bf16 v[138:141], v[226:229], v[80:83], v[138:141]
	v_mfma_f32_16x16x32_bf16 v[104:107], v[210:213], v[80:83], v[104:107]
	s_waitcnt lgkmcnt(0)
	s_barrier
	s_waitcnt vmcnt(5)
	ds_write_b128 v134, v[230:233]
	ds_write_b128 v134, v[234:237] offset:4608
	ds_write_b128 v135, v[238:241]
	s_add_i32 s64, s4, 0
	s_sub_i32 s64, 31, s64
	s_mul_i32 s71, s64, 0x30000
	s_add_u32 s38, s60, s71
	s_addc_u32 s39, s61, 0
	s_lshl_b32 s64, s64, 12
	v_add_u32_e32 v136, s64, v195
	ds_read_b128 v[116:119], v136
	s_waitcnt vmcnt(3)
	s_waitcnt lgkmcnt(0)
	v_lshlrev_b32_e32 v136, 16, v116
	v_lshlrev_b32_e32 v137, 16, v8
	v_and_b32_e32 v168, 0xffff0000, v116
	v_and_b32_e32 v169, 0xffff0000, v8
	v_mul_f32_e32 v136, v136, v137
	v_mul_f32_e32 v168, v168, v169
	v_cvt_pk_bf16_f32 v116, v136, v168
	v_lshlrev_b32_e32 v136, 16, v117
	v_lshlrev_b32_e32 v137, 16, v9
	v_and_b32_e32 v168, 0xffff0000, v117
	v_and_b32_e32 v169, 0xffff0000, v9
	v_mul_f32_e32 v136, v136, v137
	v_mul_f32_e32 v168, v168, v169
	v_cvt_pk_bf16_f32 v117, v136, v168
	v_lshlrev_b32_e32 v136, 16, v118
	v_lshlrev_b32_e32 v137, 16, v10
	v_and_b32_e32 v168, 0xffff0000, v118
	v_and_b32_e32 v169, 0xffff0000, v10
	v_mul_f32_e32 v136, v136, v137
	v_mul_f32_e32 v168, v168, v169
	v_cvt_pk_bf16_f32 v118, v136, v168
	v_lshlrev_b32_e32 v136, 16, v119
	v_lshlrev_b32_e32 v137, 16, v11
	v_and_b32_e32 v168, 0xffff0000, v119
	v_and_b32_e32 v169, 0xffff0000, v11
	v_mul_f32_e32 v136, v136, v137
	v_mul_f32_e32 v168, v168, v169
	v_cvt_pk_bf16_f32 v119, v136, v168
	global_store_dwordx4 v255, v[116:119], s[38:39]
	s_add_i32 s64, s4, 1
	s_sub_i32 s64, 31, s64
	s_mul_i32 s71, s64, 0x30000
	s_add_u32 s38, s60, s71
	s_addc_u32 s39, s61, 0
	s_lshl_b32 s64, s64, 12
	global_load_dwordx4 v[8:11], v255, s[38:39]
	s_add_i32 s52, s4, 4
	s_min_u32 s52, s52, 31
	s_sub_i32 s52, 31, s52
	s_lshl_b32 s52, s52, 13
	s_add_u32 s26, s50, s52
	s_addc_u32 s27, s51, 0
	global_load_dwordx4 v[230:233], v154, s[26:27]
	global_load_dwordx4 v[234:237], v155, s[26:27]
	global_load_dwordx4 v[238:241], v159, s[26:27]
	v_exp_f32_e32 v198, v100
	v_exp_f32_e32 v199, v101
	v_exp_f32_e32 v200, v102
	v_exp_f32_e32 v201, v103
	v_exp_f32_e32 v202, v112
	v_exp_f32_e32 v203, v113
	v_exp_f32_e32 v204, v114
	v_exp_f32_e32 v205, v115
	v_exp_f32_e32 v214, v104
	v_add_f32_e32 v198, 1.0, v198
	v_exp_f32_e32 v215, v105
	v_add_f32_e32 v199, 1.0, v199
	v_exp_f32_e32 v216, v106
	v_add_f32_e32 v200, 1.0, v200
	v_exp_f32_e32 v217, v107
	v_add_f32_e32 v201, 1.0, v201
	v_exp_f32_e32 v218, v138
	v_add_f32_e32 v202, 1.0, v202
	v_exp_f32_e32 v219, v139
	v_add_f32_e32 v203, 1.0, v203
	v_exp_f32_e32 v220, v140
	v_add_f32_e32 v204, 1.0, v204
	v_exp_f32_e32 v221, v141
	v_add_f32_e32 v205, 1.0, v205
	v_rcp_f32_e32 v198, v198
	v_add_f32_e32 v214, 1.0, v214
	v_rcp_f32_e32 v199, v199
	v_add_f32_e32 v215, 1.0, v215
	v_rcp_f32_e32 v200, v200
	v_add_f32_e32 v216, 1.0, v216
	v_rcp_f32_e32 v201, v201
	v_add_f32_e32 v217, 1.0, v217
	v_rcp_f32_e32 v202, v202
	v_add_f32_e32 v218, 1.0, v218
	v_rcp_f32_e32 v203, v203
	v_add_f32_e32 v219, 1.0, v219
	v_rcp_f32_e32 v204, v204
	v_add_f32_e32 v220, 1.0, v220
	v_rcp_f32_e32 v205, v205
	v_add_f32_e32 v221, 1.0, v221
	v_mul_f32_e32 v198, v179, v198
	v_mul_f32_e32 v199, v179, v199
	v_mul_f32_e32 v200, v179, v200
	v_mul_f32_e32 v201, v179, v201
	v_mul_f32_e32 v202, v179, v202
	v_mul_f32_e32 v203, v179, v203
	v_mul_f32_e32 v204, v179, v204
	v_mul_f32_e32 v205, v179, v205
	v_exp_f32_e32 v120, v198
	v_exp_f32_e32 v121, v199
	v_exp_f32_e32 v122, v200
	v_exp_f32_e32 v123, v201
	v_exp_f32_e32 v124, v202
	v_exp_f32_e32 v125, v203
	v_exp_f32_e32 v126, v204
	v_exp_f32_e32 v127, v205
	v_fma_f32 v206, -v120, v120, 1.0
	v_fma_f32 v207, -v121, v121, 1.0
	v_fma_f32 v208, -v122, v122, 1.0
	v_fma_f32 v209, -v123, v123, 1.0
	v_fma_f32 v210, -v124, v124, 1.0
	v_fma_f32 v211, -v125, v125, 1.0
	v_fma_f32 v212, -v126, v126, 1.0
	v_fma_f32 v213, -v127, v127, 1.0
	v_max_f32_e32 v206, 0xda24260, v206
	v_max_f32_e32 v207, 0xda24260, v207
	v_max_f32_e32 v208, 0xda24260, v208
	v_max_f32_e32 v209, 0xda24260, v209
	v_max_f32_e32 v210, 0xda24260, v210
	v_max_f32_e32 v211, 0xda24260, v211
	v_max_f32_e32 v212, 0xda24260, v212
	v_max_f32_e32 v213, 0xda24260, v213
	v_mul_f32_e32 v198, v214, v206
	v_mul_f32_e32 v199, v215, v207
	v_mul_f32_e32 v200, v216, v208
	v_mul_f32_e32 v201, v217, v209
	v_mul_f32_e32 v202, v218, v210
	v_mul_f32_e32 v203, v219, v211
	v_mul_f32_e32 v204, v220, v212
	v_mul_f32_e32 v205, v221, v213
	v_mul_f32_e32 v214, v214, v198
	v_mul_f32_e32 v215, v215, v199
	v_mul_f32_e32 v216, v216, v200
	v_mul_f32_e32 v217, v217, v201
	v_mul_f32_e32 v218, v218, v202
	v_mul_f32_e32 v219, v219, v203
	v_mul_f32_e32 v220, v220, v204
	v_mul_f32_e32 v221, v221, v205
	v_rsq_f32_e32 v214, v214
	v_mul_f32_e32 v222, v108, v206
	v_rsq_f32_e32 v215, v215
	v_mul_f32_e32 v223, v109, v207
	v_rsq_f32_e32 v216, v216
	v_mul_f32_e32 v224, v110, v208
	v_rsq_f32_e32 v217, v217
	v_mul_f32_e32 v225, v111, v209
	v_rsq_f32_e32 v218, v218
	v_mul_f32_e32 v226, v142, v210
	v_rsq_f32_e32 v219, v219
	v_mul_f32_e32 v227, v143, v211
	v_rsq_f32_e32 v220, v220
	v_mul_f32_e32 v228, v144, v212
	v_rsq_f32_e32 v221, v221
	v_mul_f32_e32 v229, v145, v213
	v_mul_f32_e32 v170, v222, v214
	v_mul_f32_e32 v171, v223, v215
	v_mul_f32_e32 v172, v224, v216
	v_mul_f32_e32 v173, v225, v217
	v_mul_f32_e32 v174, v226, v218
	v_mul_f32_e32 v175, v227, v219
	v_mul_f32_e32 v176, v228, v220
	v_mul_f32_e32 v177, v229, v221
	v_mov_b32_e32 v198, v177
	v_mov_b32_e32 v199, v127
	v_fma_f32 v198, v126, v198, v176
	v_mul_f32_e32 v199, v199, v126
	v_fma_f32 v198, v125, v198, v175
	v_mul_f32_e32 v199, v199, v125
	v_fma_f32 v198, v124, v198, v174
	v_mul_f32_e32 v199, v199, v124
	v_fma_f32 v198, v123, v198, v173
	v_mul_f32_e32 v199, v199, v123
	v_fma_f32 v198, v122, v198, v172
	v_mul_f32_e32 v199, v199, v122
	v_fma_f32 v198, v121, v198, v171
	v_mul_f32_e32 v199, v199, v121
	v_fma_f32 v198, v120, v198, v170
	v_mul_f32_e32 v199, v199, v120
	ds_bpermute_b32 v164, v185, v199 offset:0
	ds_bpermute_b32 v246, v185, v198 offset:0
	ds_bpermute_b32 v165, v185, v199 offset:64
	ds_bpermute_b32 v247, v185, v198 offset:64
	ds_bpermute_b32 v166, v185, v199 offset:128
	ds_bpermute_b32 v248, v185, v198 offset:128
	ds_bpermute_b32 v167, v185, v199 offset:192
	ds_bpermute_b32 v249, v185, v198 offset:192
	s_waitcnt lgkmcnt(0)
	v_mov_b32_e32 v251, v249
	v_mov_b32_e32 v250, v167
	v_fma_f32 v251, v251, v166, v248
	v_mul_f32_e32 v250, v250, v166
	v_fma_f32 v251, v251, v165, v247
	v_mul_f32_e32 v250, v250, v165
	v_fma_f32 v251, v251, v164, v246
	v_mul_f32_e32 v250, v250, v164
	s_mov_b64 exec, s[10:11]
	ds_write_b64 v182, v[250:251] offset:1024
	s_mov_b64 exec, -1
	s_waitcnt lgkmcnt(0)
	s_barrier
	ds_read2_b64 v[4:7], v183 offset0:128 offset1:144
	s_add_i32 s52, s4, 1
	s_sub_i32 s52, 31, s52
	s_lshl_b32 s52, s52, 12
	v_add_u32_e32 v197, s52, v184
	s_waitcnt lgkmcnt(0)
	v_fma_f32 v198, v180, v6, v7
	v_cndmask_b32_e64 v199, v180, v198, s[24:25]
	v_fma_f32 v180, v198, v4, v5
	v_fma_f32 v200, v199, v167, v249
	v_cndmask_b32_e64 v199, v199, v200, s[16:17]
	v_fma_f32 v200, v199, v166, v248
	v_cndmask_b32_e64 v199, v199, v200, s[20:21]
	v_fma_f32 v200, v199, v165, v247
	v_cndmask_b32_e64 v199, v199, v200, s[22:23]
	v_fma_f32 v221, v127, v199, v177
	v_fma_f32 v220, v126, v221, v176
	v_fma_f32 v219, v125, v220, v175
	v_fma_f32 v218, v124, v219, v174
	v_fma_f32 v217, v123, v218, v173
	v_fma_f32 v216, v122, v217, v172
	v_fma_f32 v215, v121, v216, v171
	v_fma_f32 v214, v120, v215, v170
	ds_read_u16 v206, v197 offset:0
	ds_read_u16 v207, v197 offset:64
	ds_read_u16 v208, v197 offset:128
	ds_read_u16 v209, v197 offset:192
	ds_read_u16 v210, v197 offset:256
	ds_read_u16 v211, v197 offset:320
	ds_read_u16 v212, v197 offset:384
	ds_read_u16 v213, v197 offset:448
	s_waitcnt lgkmcnt(0)
	v_lshlrev_b32_e32 v206, 16, v206
	v_lshlrev_b32_e32 v207, 16, v207
	v_lshlrev_b32_e32 v208, 16, v208
	v_lshlrev_b32_e32 v209, 16, v209
	v_lshlrev_b32_e32 v210, 16, v210
	v_lshlrev_b32_e32 v211, 16, v211
	v_lshlrev_b32_e32 v212, 16, v212
	v_lshlrev_b32_e32 v213, 16, v213
	v_add_f32_e32 v214, v214, v206
	v_add_f32_e32 v215, v215, v207
	v_add_f32_e32 v216, v216, v208
	v_add_f32_e32 v217, v217, v209
	v_add_f32_e32 v218, v218, v210
	v_add_f32_e32 v219, v219, v211
	v_add_f32_e32 v220, v220, v212
	v_add_f32_e32 v221, v221, v213
	v_cvt_pk_bf16_f32 v206, v214, v215
	v_cvt_pk_bf16_f32 v208, v216, v217
	v_cvt_pk_bf16_f32 v210, v218, v219
	v_cvt_pk_bf16_f32 v212, v220, v221
	ds_write_b16 v197, v206 offset:0
	ds_write_b16_d16_hi v197, v206 offset:64
	ds_write_b16 v197, v208 offset:128
	ds_write_b16_d16_hi v197, v208 offset:192
	ds_write_b16 v197, v210 offset:256
	ds_write_b16_d16_hi v197, v210 offset:320
	ds_write_b16 v197, v212 offset:384
	ds_write_b16_d16_hi v197, v212 offset:448
	s_add_i32 s4, s4, 2
	s_cmp_lt_u32 s4, 32
	s_cbranch_scc1 .Lrec2_loopB_d1
	s_waitcnt lgkmcnt(0)
	s_barrier
	s_add_i32 s64, s4, -1
	s_sub_i32 s64, 31, s64
	s_mul_i32 s71, s64, 0x30000
	s_add_u32 s38, s60, s71
	s_addc_u32 s39, s61, 0
	s_lshl_b32 s64, s64, 12
	v_add_u32_e32 v136, s64, v195
	ds_read_b128 v[116:119], v136
	s_waitcnt vmcnt(3)
	s_waitcnt lgkmcnt(0)
	v_lshlrev_b32_e32 v136, 16, v116
	v_lshlrev_b32_e32 v137, 16, v8
	v_and_b32_e32 v168, 0xffff0000, v116
	v_and_b32_e32 v169, 0xffff0000, v8
	v_mul_f32_e32 v136, v136, v137
	v_mul_f32_e32 v168, v168, v169
	v_cvt_pk_bf16_f32 v116, v136, v168
	v_lshlrev_b32_e32 v136, 16, v117
	v_lshlrev_b32_e32 v137, 16, v9
	v_and_b32_e32 v168, 0xffff0000, v117
	v_and_b32_e32 v169, 0xffff0000, v9
	v_mul_f32_e32 v136, v136, v137
	v_mul_f32_e32 v168, v168, v169
	v_cvt_pk_bf16_f32 v117, v136, v168
	v_lshlrev_b32_e32 v136, 16, v118
	v_lshlrev_b32_e32 v137, 16, v10
	v_and_b32_e32 v168, 0xffff0000, v118
	v_and_b32_e32 v169, 0xffff0000, v10
	v_mul_f32_e32 v136, v136, v137
	v_mul_f32_e32 v168, v168, v169
	v_cvt_pk_bf16_f32 v118, v136, v168
	v_lshlrev_b32_e32 v136, 16, v119
	v_lshlrev_b32_e32 v137, 16, v11
	v_and_b32_e32 v168, 0xffff0000, v119
	v_and_b32_e32 v169, 0xffff0000, v11
	v_mul_f32_e32 v136, v136, v137
	v_mul_f32_e32 v168, v168, v169
	v_cvt_pk_bf16_f32 v119, v136, v168
	global_store_dwordx4 v255, v[116:119], s[38:39]
